# K-loops: the post-MFMA s_setprio 0 moved behind the barrier so the MFMA wave arrives one issue slot earlier
# speedup vs baseline: 1.0030x; 1.0030x over previous
; #define PG8_STAGE(bufoff, gbase, voff) do { _Pragma("unroll") for (int _i = 0; _i < 2; ++_i) \
;         __builtin_amdgcn_global_load_lds((const unsigned*)((const char*)(gbase) + (voff)[_i]), (PG8_LAS unsigned*)(lds + (bufoff) + ldsw + _i * 8192), 16, 0, 0); } while (0)
; #define PG8_LDA(dst, b, h) do { _Pragma("unroll") for (int m = 0; m < 4; ++m) _Pragma("unroll") for (int k = 0; k < 2; ++k) dst[m][k] = *(const PG8_LAS bf16x8*)(lds + PG8_SA(b, h) + aoff + m * 2048 + k * 1024); } while (0)
; #define PG8_LDB(dst, b, h) do { _Pragma("unroll") for (int n = 0; n < 2; ++n) _Pragma("unroll") for (int k = 0; k < 2; ++k) dst[n][k] = *(const PG8_LAS bf16x8*)(lds + PG8_SB(b, h) + boff + n * 2048 + k * 1024); } while (0)
; #define PG8_MMA(ai, bj, At, Bt) do { __builtin_amdgcn_s_setprio(1); _Pragma("unroll") for (int m = 0; m < 4; ++m) _Pragma("unroll") for (int n = 0; n < 2; ++n) _Pragma("unroll") for (int k = 0; k < 2; ++k) \
;         acc[ai][bj][m][n] = __builtin_amdgcn_mfma_f32_16x16x32_bf16(Bt[n][k], At[m][k], acc[ai][bj][m][n], 0, 0, 0); __builtin_amdgcn_s_setprio(0); } while (0)
; #define PG8_WAIT_V(n) asm volatile("s_waitcnt vmcnt(" #n ")" ::: "memory")
; #define PG8_WAIT_L(n) asm volatile("s_waitcnt lgkmcnt(" #n ")" ::: "memory")
; template <class Epi, class Sched, bool ALIGN_EPI = false, bool SP2 = false>
; __device__ __forceinline__ void gemm_phase(PG8_LAS unsigned char* lds, const Gemm g, const Sched& S, const Epi& E) {
;     ...
;             const bool last = (t == nt - 2);
;             const char* a1 = cA + (size_t)(t + 1) * kstep;
;             const char* a2 = last ? nA : cA + (size_t)(t + 2) * kstep; const char* b2 = last ? nB : cB + (size_t)(t + 2) * kstep;
;             const char* a3 = a2 + kstep; const char* b3 = b2 + kstep;
;             if (last && has_next) S.a_ready(nxt);
;             if constexpr (SP2) {
;             PG8_LDB(B0, 0, 0); PG8_LDB(B1, 0, 1); PG8_SCHED; PG8_LDA(At, 0, 0); PG8_STAGE(PG8_SA(1, 1), a1 + hstep, voffA);
;             PG8_WAIT_V(8); PG8_WAIT_L(0); PG8_BAR; PG8_MMA(0, 0, At, B0); PG8_MMA(0, 1, At, B1); PG8_BAR; PG8_SCHED;
;             PG8_LDA(At, 0, 1); PG8_STAGE(PG8_SB(0, 0), b2, voffB); PG8_STAGE(PG8_SB(0, 1), b2 + hstep, voffB); PG8_STAGE(PG8_SA(0, 0), a2, voffA);
;             PG8_WAIT_V(8); PG8_WAIT_L(0); PG8_BAR; PG8_MMA(1, 0, At, B0); PG8_MMA(1, 1, At, B1); PG8_BAR; PG8_SCHED;
.LBB0_67:
	ds_read_b128 v[128:131], v159
	ds_read_b128 v[152:155], v159 offset:1024
	ds_read_b128 v[162:165], v159 offset:2048
	ds_read_b128 v[166:169], v159 offset:3072
	ds_read_b128 v[170:173], v160
	ds_read_b128 v[174:177], v160 offset:1024
	ds_read_b128 v[178:181], v160 offset:2048
	ds_read_b128 v[182:185], v160 offset:3072
	s_add_i32 m0, s1, 0xc000
	ds_read_b128 v[186:189], v161
	ds_read_b128 v[190:193], v161 offset:1024
	ds_read_b128 v[194:197], v161 offset:2048
	ds_read_b128 v[200:203], v161 offset:3072
	ds_read_b128 v[204:207], v161 offset:4096
	ds_read_b128 v[208:211], v161 offset:5120
	ds_read_b128 v[212:215], v161 offset:6144
	ds_read_b128 v[216:219], v161 offset:7168
	global_load_lds_dwordx4 v144, s[74:75]
	s_add_i32 m0, s1, 0xe000
	s_nop 0
	global_load_lds_dwordx4 v146, s[74:75]
	s_add_u32 s76, s74, 0xfff80080
	s_addc_u32 s77, s75, -1
	s_cmp_eq_u32 s88, 28
	s_cselect_b32 s79, s5, s77
	s_cselect_b32 s78, s14, s76
	s_cselect_b32 s77, s24, s69
	s_cselect_b32 s76, s25, s67
	s_add_i32 s89, s85, s0
	s_mov_b32 m0, s89
	s_waitcnt vmcnt(8)
	s_waitcnt lgkmcnt(0)
	s_setprio 1
	s_barrier
	v_mfma_f32_16x16x32_bf16 v[124:127], v[128:131], v[186:189], v[124:127]
	v_mfma_f32_16x16x32_bf16 v[120:123], v[162:165], v[186:189], v[120:123]
	v_mfma_f32_16x16x32_bf16 v[108:111], v[128:131], v[194:197], v[108:111]
	v_mfma_f32_16x16x32_bf16 v[104:107], v[162:165], v[194:197], v[104:107]
	v_mfma_f32_16x16x32_bf16 v[92:95], v[128:131], v[204:207], v[92:95]
	v_mfma_f32_16x16x32_bf16 v[88:91], v[162:165], v[204:207], v[88:91]
	v_mfma_f32_16x16x32_bf16 v[76:79], v[128:131], v[212:215], v[76:79]
	v_mfma_f32_16x16x32_bf16 v[72:75], v[162:165], v[212:215], v[72:75]
	v_mfma_f32_16x16x32_bf16 v[124:127], v[152:155], v[190:193], v[124:127]
	v_mfma_f32_16x16x32_bf16 v[120:123], v[166:169], v[190:193], v[120:123]
	v_mfma_f32_16x16x32_bf16 v[108:111], v[152:155], v[200:203], v[108:111]
	v_mfma_f32_16x16x32_bf16 v[104:107], v[166:169], v[200:203], v[104:107]
	v_mfma_f32_16x16x32_bf16 v[92:95], v[152:155], v[208:211], v[92:95]
	v_mfma_f32_16x16x32_bf16 v[88:91], v[166:169], v[208:211], v[88:91]
	v_mfma_f32_16x16x32_bf16 v[76:79], v[152:155], v[216:219], v[76:79]
	v_mfma_f32_16x16x32_bf16 v[72:75], v[166:169], v[216:219], v[72:75]
	v_mfma_f32_16x16x32_bf16 v[116:119], v[170:173], v[186:189], v[116:119]
	v_mfma_f32_16x16x32_bf16 v[112:115], v[178:181], v[186:189], v[112:115]
	v_mfma_f32_16x16x32_bf16 v[100:103], v[170:173], v[194:197], v[100:103]
	v_mfma_f32_16x16x32_bf16 v[96:99], v[178:181], v[194:197], v[96:99]
	v_mfma_f32_16x16x32_bf16 v[84:87], v[170:173], v[204:207], v[84:87]
	v_mfma_f32_16x16x32_bf16 v[80:83], v[178:181], v[204:207], v[80:83]
	v_mfma_f32_16x16x32_bf16 v[68:71], v[170:173], v[212:215], v[68:71]
	v_mfma_f32_16x16x32_bf16 v[64:67], v[178:181], v[212:215], v[64:67]
	v_mfma_f32_16x16x32_bf16 v[116:119], v[174:177], v[190:193], v[116:119]
	v_mfma_f32_16x16x32_bf16 v[112:115], v[182:185], v[190:193], v[112:115]
	v_mfma_f32_16x16x32_bf16 v[100:103], v[174:177], v[200:203], v[100:103]
	v_mfma_f32_16x16x32_bf16 v[96:99], v[182:185], v[200:203], v[96:99]
	v_mfma_f32_16x16x32_bf16 v[84:87], v[174:177], v[208:211], v[84:87]
	v_mfma_f32_16x16x32_bf16 v[80:83], v[182:185], v[208:211], v[80:83]
	v_mfma_f32_16x16x32_bf16 v[68:71], v[174:177], v[216:219], v[68:71]
	v_mfma_f32_16x16x32_bf16 v[64:67], v[182:185], v[216:219], v[64:67]
	s_barrier
	s_setprio 0
	ds_read_b128 v[186:189], v161 offset:16384
	ds_read_b128 v[190:193], v161 offset:17408
	ds_read_b128 v[194:197], v161 offset:18432
	ds_read_b128 v[200:203], v161 offset:19456
	ds_read_b128 v[204:207], v161 offset:20480
	ds_read_b128 v[208:211], v161 offset:21504
	ds_read_b128 v[212:215], v161 offset:22528
	ds_read_b128 v[216:219], v161 offset:23552
	global_load_lds_dwordx4 v134, s[76:77]
	s_add_i32 m0, s89, 0x2000
	s_add_u32 s96, s76, 0x80000
	s_addc_u32 s97, s77, 0
	s_add_i32 s89, s86, s0
	global_load_lds_dwordx4 v138, s[76:77]
	s_mov_b32 m0, s89
	s_nop 0
	global_load_lds_dwordx4 v134, s[96:97]
	s_add_i32 m0, s89, 0x2000
	s_nop 0
	global_load_lds_dwordx4 v138, s[96:97]
	s_mov_b32 m0, s1
	s_nop 0
	global_load_lds_dwordx4 v132, s[78:79]
	s_mov_b32 m0, s11
	s_nop 0
	global_load_lds_dwordx4 v136, s[78:79]
	s_waitcnt vmcnt(8)
	s_waitcnt lgkmcnt(0)
	s_setprio 1
	s_barrier
	v_mfma_f32_16x16x32_bf16 v[60:63], v[128:131], v[186:189], v[60:63]
	v_mfma_f32_16x16x32_bf16 v[56:59], v[162:165], v[186:189], v[56:59]
	v_mfma_f32_16x16x32_bf16 v[44:47], v[128:131], v[194:197], v[44:47]
	v_mfma_f32_16x16x32_bf16 v[40:43], v[162:165], v[194:197], v[40:43]
	v_mfma_f32_16x16x32_bf16 v[28:31], v[128:131], v[204:207], v[28:31]
	v_mfma_f32_16x16x32_bf16 v[24:27], v[162:165], v[204:207], v[24:27]
	v_mfma_f32_16x16x32_bf16 v[12:15], v[128:131], v[212:215], v[12:15]
	v_mfma_f32_16x16x32_bf16 v[8:11], v[162:165], v[212:215], v[8:11]
	v_mfma_f32_16x16x32_bf16 v[60:63], v[152:155], v[190:193], v[60:63]
	v_mfma_f32_16x16x32_bf16 v[56:59], v[166:169], v[190:193], v[56:59]
	v_mfma_f32_16x16x32_bf16 v[44:47], v[152:155], v[200:203], v[44:47]
	v_mfma_f32_16x16x32_bf16 v[40:43], v[166:169], v[200:203], v[40:43]
	v_mfma_f32_16x16x32_bf16 v[28:31], v[152:155], v[208:211], v[28:31]
	v_mfma_f32_16x16x32_bf16 v[24:27], v[166:169], v[208:211], v[24:27]
	v_mfma_f32_16x16x32_bf16 v[12:15], v[152:155], v[216:219], v[12:15]
	v_mfma_f32_16x16x32_bf16 v[8:11], v[166:169], v[216:219], v[8:11]
	v_mfma_f32_16x16x32_bf16 v[52:55], v[170:173], v[186:189], v[52:55]
	v_mfma_f32_16x16x32_bf16 v[48:51], v[178:181], v[186:189], v[48:51]
	v_mfma_f32_16x16x32_bf16 v[36:39], v[170:173], v[194:197], v[36:39]
	v_mfma_f32_16x16x32_bf16 v[32:35], v[178:181], v[194:197], v[32:35]
	v_mfma_f32_16x16x32_bf16 v[20:23], v[170:173], v[204:207], v[20:23]
	v_mfma_f32_16x16x32_bf16 v[16:19], v[178:181], v[204:207], v[16:19]
	v_mfma_f32_16x16x32_bf16 v[4:7], v[170:173], v[212:215], v[4:7]
	v_mfma_f32_16x16x32_bf16 v[0:3], v[178:181], v[212:215], v[0:3]
	v_mfma_f32_16x16x32_bf16 v[52:55], v[174:177], v[190:193], v[52:55]
	v_mfma_f32_16x16x32_bf16 v[48:51], v[182:185], v[190:193], v[48:51]
	v_mfma_f32_16x16x32_bf16 v[36:39], v[174:177], v[200:203], v[36:39]
	v_mfma_f32_16x16x32_bf16 v[32:35], v[182:185], v[200:203], v[32:35]
	v_mfma_f32_16x16x32_bf16 v[20:23], v[174:177], v[208:211], v[20:23]
	v_mfma_f32_16x16x32_bf16 v[16:19], v[182:185], v[208:211], v[16:19]
	v_mfma_f32_16x16x32_bf16 v[4:7], v[174:177], v[216:219], v[4:7]
	v_mfma_f32_16x16x32_bf16 v[0:3], v[182:185], v[216:219], v[0:3]
	s_barrier
; #define PG8_STAGE(bufoff, gbase, voff) do { _Pragma("unroll") for (int _i = 0; _i < 2; ++_i) \
;         __builtin_amdgcn_global_load_lds((const unsigned*)((const char*)(gbase) + (voff)[_i]), (PG8_LAS unsigned*)(lds + (bufoff) + ldsw + _i * 8192), 16, 0, 0); } while (0)
; #define PG8_LDA(dst, b, h) do { _Pragma("unroll") for (int m = 0; m < 4; ++m) _Pragma("unroll") for (int k = 0; k < 2; ++k) dst[m][k] = *(const PG8_LAS bf16x8*)(lds + PG8_SA(b, h) + aoff + m * 2048 + k * 1024); } while (0)
; #define PG8_LDB(dst, b, h) do { _Pragma("unroll") for (int n = 0; n < 2; ++n) _Pragma("unroll") for (int k = 0; k < 2; ++k) dst[n][k] = *(const PG8_LAS bf16x8*)(lds + PG8_SB(b, h) + boff + n * 2048 + k * 1024); } while (0)
; #define PG8_MMA(ai, bj, At, Bt) do { __builtin_amdgcn_s_setprio(1); _Pragma("unroll") for (int m = 0; m < 4; ++m) _Pragma("unroll") for (int n = 0; n < 2; ++n) _Pragma("unroll") for (int k = 0; k < 2; ++k) \
;         acc[ai][bj][m][n] = __builtin_amdgcn_mfma_f32_16x16x32_bf16(Bt[n][k], At[m][k], acc[ai][bj][m][n], 0, 0, 0); __builtin_amdgcn_s_setprio(0); } while (0)
; #define PG8_WAIT_V(n) asm volatile("s_waitcnt vmcnt(" #n ")" ::: "memory")
; #define PG8_WAIT_L(n) asm volatile("s_waitcnt lgkmcnt(" #n ")" ::: "memory")
; #define PG8_BAR __builtin_amdgcn_s_barrier()
; #define PG8_SCHED __builtin_amdgcn_sched_barrier(0)
; template <class Epi, class Sched, bool ALIGN_EPI = false, bool SP2 = false>
; __device__ __forceinline__ void gemm_phase(PG8_LAS unsigned char* lds, const Gemm g, const Sched& S, const Epi& E) {
;     ...
;             PG8_LDB(B0, 1, 0); PG8_LDB(B1, 1, 1); PG8_SCHED; PG8_LDA(At, 1, 0); PG8_STAGE(PG8_SA(0, 1), a2 + hstep, voffA);
;             PG8_WAIT_V(8); PG8_WAIT_L(0); PG8_BAR; PG8_MMA(0, 0, At, B0); PG8_MMA(0, 1, At, B1); PG8_BAR; PG8_SCHED;
;             PG8_LDA(At, 1, 1); PG8_STAGE(PG8_SB(1, 0), b3, voffB); PG8_STAGE(PG8_SB(1, 1), b3 + hstep, voffB); PG8_STAGE(PG8_SA(1, 0), a3, voffA);
;             PG8_WAIT_V(8); PG8_WAIT_L(0); PG8_BAR; PG8_MMA(1, 0, At, B0); PG8_MMA(1, 1, At, B1); PG8_BAR; PG8_SCHED;
	s_setprio 0
	ds_read_b128 v[128:131], v198
	ds_read_b128 v[152:155], v198 offset:1024
	ds_read_b128 v[162:165], v198 offset:2048
	ds_read_b128 v[166:169], v198 offset:3072
	ds_read_b128 v[170:173], v199
	ds_read_b128 v[174:177], v199 offset:1024
	ds_read_b128 v[178:181], v199 offset:2048
	ds_read_b128 v[182:185], v199 offset:3072
	ds_read_b128 v[186:189], v161 offset:32768
	ds_read_b128 v[190:193], v161 offset:33792
	ds_read_b128 v[194:197], v161 offset:34816
	ds_read_b128 v[200:203], v161 offset:35840
	ds_read_b128 v[204:207], v161 offset:36864
	ds_read_b128 v[208:211], v161 offset:37888
	ds_read_b128 v[212:215], v161 offset:38912
	ds_read_b128 v[216:219], v161 offset:39936
	s_add_u32 s98, s78, 0x80000
	s_addc_u32 s99, s79, 0
	s_mov_b32 m0, s33
	s_add_u32 s100, s78, 0x80
	s_addc_u32 s101, s79, 0
	global_load_lds_dwordx4 v132, s[98:99]
	s_mov_b32 m0, s35
	s_nop 0
	global_load_lds_dwordx4 v136, s[98:99]
	s_add_i32 s89, 0, 0x18000
	s_add_i32 s94, 0, 0x1c000
	s_add_u32 s98, s76, 0x80
	s_addc_u32 s99, s77, 0
	s_add_i32 s78, s89, s0
	s_mov_b32 m0, s78
	s_waitcnt vmcnt(8)
	s_waitcnt lgkmcnt(0)
	s_setprio 1
	s_barrier
	v_mfma_f32_16x16x32_bf16 v[124:127], v[128:131], v[186:189], v[124:127]
	v_mfma_f32_16x16x32_bf16 v[120:123], v[162:165], v[186:189], v[120:123]
	v_mfma_f32_16x16x32_bf16 v[108:111], v[128:131], v[194:197], v[108:111]
	v_mfma_f32_16x16x32_bf16 v[104:107], v[162:165], v[194:197], v[104:107]
	v_mfma_f32_16x16x32_bf16 v[92:95], v[128:131], v[204:207], v[92:95]
	v_mfma_f32_16x16x32_bf16 v[88:91], v[162:165], v[204:207], v[88:91]
	v_mfma_f32_16x16x32_bf16 v[76:79], v[128:131], v[212:215], v[76:79]
	v_mfma_f32_16x16x32_bf16 v[72:75], v[162:165], v[212:215], v[72:75]
	v_mfma_f32_16x16x32_bf16 v[124:127], v[152:155], v[190:193], v[124:127]
	v_mfma_f32_16x16x32_bf16 v[120:123], v[166:169], v[190:193], v[120:123]
	v_mfma_f32_16x16x32_bf16 v[108:111], v[152:155], v[200:203], v[108:111]
	v_mfma_f32_16x16x32_bf16 v[104:107], v[166:169], v[200:203], v[104:107]
	v_mfma_f32_16x16x32_bf16 v[92:95], v[152:155], v[208:211], v[92:95]
	v_mfma_f32_16x16x32_bf16 v[88:91], v[166:169], v[208:211], v[88:91]
	v_mfma_f32_16x16x32_bf16 v[76:79], v[152:155], v[216:219], v[76:79]
	v_mfma_f32_16x16x32_bf16 v[72:75], v[166:169], v[216:219], v[72:75]
	v_mfma_f32_16x16x32_bf16 v[116:119], v[170:173], v[186:189], v[116:119]
	v_mfma_f32_16x16x32_bf16 v[112:115], v[178:181], v[186:189], v[112:115]
	v_mfma_f32_16x16x32_bf16 v[100:103], v[170:173], v[194:197], v[100:103]
	v_mfma_f32_16x16x32_bf16 v[96:99], v[178:181], v[194:197], v[96:99]
	v_mfma_f32_16x16x32_bf16 v[84:87], v[170:173], v[204:207], v[84:87]
	v_mfma_f32_16x16x32_bf16 v[80:83], v[178:181], v[204:207], v[80:83]
	v_mfma_f32_16x16x32_bf16 v[68:71], v[170:173], v[212:215], v[68:71]
	v_mfma_f32_16x16x32_bf16 v[64:67], v[178:181], v[212:215], v[64:67]
	v_mfma_f32_16x16x32_bf16 v[116:119], v[174:177], v[190:193], v[116:119]
	v_mfma_f32_16x16x32_bf16 v[112:115], v[182:185], v[190:193], v[112:115]
	v_mfma_f32_16x16x32_bf16 v[100:103], v[174:177], v[200:203], v[100:103]
	v_mfma_f32_16x16x32_bf16 v[96:99], v[182:185], v[200:203], v[96:99]
	v_mfma_f32_16x16x32_bf16 v[84:87], v[174:177], v[208:211], v[84:87]
	v_mfma_f32_16x16x32_bf16 v[80:83], v[182:185], v[208:211], v[80:83]
	v_mfma_f32_16x16x32_bf16 v[68:71], v[174:177], v[216:219], v[68:71]
	v_mfma_f32_16x16x32_bf16 v[64:67], v[182:185], v[216:219], v[64:67]
	s_barrier
	s_setprio 0
	ds_read_b128 v[186:189], v161 offset:49152
	ds_read_b128 v[190:193], v161 offset:50176
	ds_read_b128 v[194:197], v161 offset:51200
	ds_read_b128 v[200:203], v161 offset:52224
	ds_read_b128 v[204:207], v161 offset:53248
	ds_read_b128 v[208:211], v161 offset:54272
	ds_read_b128 v[212:215], v161 offset:55296
	ds_read_b128 v[216:219], v161 offset:56320
	global_load_lds_dwordx4 v134, s[98:99]
	s_add_i32 m0, s78, 0x2000
	s_add_u32 s76, s76, 0x80080
	s_addc_u32 s77, s77, 0
	s_add_i32 s78, s94, s0
	global_load_lds_dwordx4 v138, s[98:99]
	s_mov_b32 m0, s78
	s_nop 0
	global_load_lds_dwordx4 v134, s[76:77]
	s_add_i32 m0, s78, 0x2000
	s_nop 0
	global_load_lds_dwordx4 v138, s[76:77]
	s_mov_b32 m0, s80
	s_nop 0
	global_load_lds_dwordx4 v132, s[100:101]
	s_mov_b32 m0, s81
	s_nop 0
	global_load_lds_dwordx4 v136, s[100:101]
	s_add_i32 s88, s88, 2
	s_add_u32 s74, s74, 0x100
	s_addc_u32 s75, s75, 0
	s_add_u32 s67, s67, 0x100
	s_addc_u32 s69, s69, 0
	s_cmp_gt_u32 s88, 29
	s_waitcnt vmcnt(8)
	s_waitcnt lgkmcnt(0)
	s_setprio 1
	s_barrier
	v_mfma_f32_16x16x32_bf16 v[60:63], v[128:131], v[186:189], v[60:63]
	v_mfma_f32_16x16x32_bf16 v[56:59], v[162:165], v[186:189], v[56:59]
	v_mfma_f32_16x16x32_bf16 v[44:47], v[128:131], v[194:197], v[44:47]
	v_mfma_f32_16x16x32_bf16 v[40:43], v[162:165], v[194:197], v[40:43]
	v_mfma_f32_16x16x32_bf16 v[28:31], v[128:131], v[204:207], v[28:31]
	v_mfma_f32_16x16x32_bf16 v[24:27], v[162:165], v[204:207], v[24:27]
	v_mfma_f32_16x16x32_bf16 v[12:15], v[128:131], v[212:215], v[12:15]
	v_mfma_f32_16x16x32_bf16 v[8:11], v[162:165], v[212:215], v[8:11]
	v_mfma_f32_16x16x32_bf16 v[60:63], v[152:155], v[190:193], v[60:63]
	v_mfma_f32_16x16x32_bf16 v[56:59], v[166:169], v[190:193], v[56:59]
	v_mfma_f32_16x16x32_bf16 v[44:47], v[152:155], v[200:203], v[44:47]
	v_mfma_f32_16x16x32_bf16 v[40:43], v[166:169], v[200:203], v[40:43]
	v_mfma_f32_16x16x32_bf16 v[28:31], v[152:155], v[208:211], v[28:31]
	v_mfma_f32_16x16x32_bf16 v[24:27], v[166:169], v[208:211], v[24:27]
	v_mfma_f32_16x16x32_bf16 v[12:15], v[152:155], v[216:219], v[12:15]
	v_mfma_f32_16x16x32_bf16 v[8:11], v[166:169], v[216:219], v[8:11]
	v_mfma_f32_16x16x32_bf16 v[52:55], v[170:173], v[186:189], v[52:55]
	v_mfma_f32_16x16x32_bf16 v[48:51], v[178:181], v[186:189], v[48:51]
	v_mfma_f32_16x16x32_bf16 v[36:39], v[170:173], v[194:197], v[36:39]
	v_mfma_f32_16x16x32_bf16 v[32:35], v[178:181], v[194:197], v[32:35]
	v_mfma_f32_16x16x32_bf16 v[20:23], v[170:173], v[204:207], v[20:23]
	v_mfma_f32_16x16x32_bf16 v[16:19], v[178:181], v[204:207], v[16:19]
	v_mfma_f32_16x16x32_bf16 v[4:7], v[170:173], v[212:215], v[4:7]
	v_mfma_f32_16x16x32_bf16 v[0:3], v[178:181], v[212:215], v[0:3]
	v_mfma_f32_16x16x32_bf16 v[52:55], v[174:177], v[190:193], v[52:55]
	v_mfma_f32_16x16x32_bf16 v[48:51], v[182:185], v[190:193], v[48:51]
	v_mfma_f32_16x16x32_bf16 v[36:39], v[174:177], v[200:203], v[36:39]
	v_mfma_f32_16x16x32_bf16 v[32:35], v[182:185], v[200:203], v[32:35]
	v_mfma_f32_16x16x32_bf16 v[20:23], v[174:177], v[208:211], v[20:23]
	v_mfma_f32_16x16x32_bf16 v[16:19], v[182:185], v[208:211], v[16:19]
	v_mfma_f32_16x16x32_bf16 v[4:7], v[174:177], v[216:219], v[4:7]
	v_mfma_f32_16x16x32_bf16 v[0:3], v[182:185], v[216:219], v[0:3]
	s_barrier
	s_setprio 0
	s_cbranch_scc0 .LBB0_67
	s_and_b64 vcc, exec, s[60:61]
	s_cbranch_vccz .LBB0_70
	s_barrier

; #define PG8_STAGE(bufoff, gbase, voff) do { _Pragma("unroll") for (int _i = 0; _i < 2; ++_i) \
;         __builtin_amdgcn_global_load_lds((const unsigned*)((const char*)(gbase) + (voff)[_i]), (PG8_LAS unsigned*)(lds + (bufoff) + ldsw + _i * 8192), 16, 0, 0); } while (0)
; #define PG8_LDA(dst, b, h) do { _Pragma("unroll") for (int m = 0; m < 4; ++m) _Pragma("unroll") for (int k = 0; k < 2; ++k) dst[m][k] = *(const PG8_LAS bf16x8*)(lds + PG8_SA(b, h) + aoff + m * 2048 + k * 1024); } while (0)
; #define PG8_LDB(dst, b, h) do { _Pragma("unroll") for (int n = 0; n < 2; ++n) _Pragma("unroll") for (int k = 0; k < 2; ++k) dst[n][k] = *(const PG8_LAS bf16x8*)(lds + PG8_SB(b, h) + boff + n * 2048 + k * 1024); } while (0)
; #define PG8_MMA(ai, bj, At, Bt) do { __builtin_amdgcn_s_setprio(1); _Pragma("unroll") for (int m = 0; m < 4; ++m) _Pragma("unroll") for (int n = 0; n < 2; ++n) _Pragma("unroll") for (int k = 0; k < 2; ++k) \
;         acc[ai][bj][m][n] = __builtin_amdgcn_mfma_f32_16x16x32_bf16(Bt[n][k], At[m][k], acc[ai][bj][m][n], 0, 0, 0); __builtin_amdgcn_s_setprio(0); } while (0)
; #define PG8_WAIT_V(n) asm volatile("s_waitcnt vmcnt(" #n ")" ::: "memory")
; #define PG8_WAIT_L(n) asm volatile("s_waitcnt lgkmcnt(" #n ")" ::: "memory")
; template <class Epi, class Sched, bool ALIGN_EPI = false, bool SP2 = false>
; __device__ __forceinline__ void gemm_phase(PG8_LAS unsigned char* lds, const Gemm g, const Sched& S, const Epi& E) {
;     ...
;             const bool last = (t == nt - 2);
;             const char* a1 = cA + (size_t)(t + 1) * kstep;
;             const char* a2 = last ? nA : cA + (size_t)(t + 2) * kstep; const char* b2 = last ? nB : cB + (size_t)(t + 2) * kstep;
;             const char* a3 = a2 + kstep; const char* b3 = b2 + kstep;
;             if (last && has_next) S.a_ready(nxt);
;             if constexpr (SP2) {
;             PG8_LDB(B0, 0, 0); PG8_LDB(B1, 0, 1); PG8_SCHED; PG8_LDA(At, 0, 0); PG8_STAGE(PG8_SA(1, 1), a1 + hstep, voffA);
;             PG8_WAIT_V(8); PG8_WAIT_L(0); PG8_BAR; PG8_MMA(0, 0, At, B0); PG8_MMA(0, 1, At, B1); PG8_BAR; PG8_SCHED;
;             PG8_LDA(At, 0, 1); PG8_STAGE(PG8_SB(0, 0), b2, voffB); PG8_STAGE(PG8_SB(0, 1), b2 + hstep, voffB); PG8_STAGE(PG8_SA(0, 0), a2, voffA);
;             PG8_WAIT_V(8); PG8_WAIT_L(0); PG8_BAR; PG8_MMA(1, 0, At, B0); PG8_MMA(1, 1, At, B1); PG8_BAR; PG8_SCHED;
.LBB0_245:
	ds_read_b128 v[144:147], v153
	ds_read_b128 v[156:159], v153 offset:1024
	ds_read_b128 v[160:163], v153 offset:2048
	ds_read_b128 v[164:167], v153 offset:3072
	ds_read_b128 v[168:171], v154
	ds_read_b128 v[172:175], v154 offset:1024
	ds_read_b128 v[176:179], v154 offset:2048
	ds_read_b128 v[180:183], v154 offset:3072
	s_add_i32 m0, s33, 0xc000
	ds_read_b128 v[184:187], v155
	ds_read_b128 v[188:191], v155 offset:1024
	ds_read_b128 v[192:195], v155 offset:2048
	ds_read_b128 v[200:203], v155 offset:3072
	ds_read_b128 v[204:207], v155 offset:4096
	ds_read_b128 v[208:211], v155 offset:5120
	ds_read_b128 v[212:215], v155 offset:6144
	ds_read_b128 v[216:219], v155 offset:7168
	global_load_lds_dwordx4 v136, s[70:71]
	s_add_i32 m0, s33, 0xe000
	s_nop 0
	global_load_lds_dwordx4 v138, s[70:71]
	s_add_u32 s72, s70, 0xfff80080
	s_addc_u32 s73, s71, -1
	s_cmp_eq_u32 s87, 28
	s_cselect_b32 s75, s25, s73
	s_cselect_b32 s74, s63, s72
	s_cselect_b32 s73, s61, s86
	s_cselect_b32 s72, s84, s85
	s_add_i32 s88, s82, s1
	s_mov_b32 m0, s88
	s_waitcnt vmcnt(8)
	s_waitcnt lgkmcnt(0)
	s_setprio 1
	s_barrier
	v_mfma_f32_16x16x32_bf16 v[124:127], v[144:147], v[184:187], v[124:127]
	v_mfma_f32_16x16x32_bf16 v[120:123], v[160:163], v[184:187], v[120:123]
	v_mfma_f32_16x16x32_bf16 v[108:111], v[144:147], v[192:195], v[108:111]
	v_mfma_f32_16x16x32_bf16 v[104:107], v[160:163], v[192:195], v[104:107]
	v_mfma_f32_16x16x32_bf16 v[92:95], v[144:147], v[204:207], v[92:95]
	v_mfma_f32_16x16x32_bf16 v[88:91], v[160:163], v[204:207], v[88:91]
	v_mfma_f32_16x16x32_bf16 v[76:79], v[144:147], v[212:215], v[76:79]
	v_mfma_f32_16x16x32_bf16 v[72:75], v[160:163], v[212:215], v[72:75]
	v_mfma_f32_16x16x32_bf16 v[124:127], v[156:159], v[188:191], v[124:127]
	v_mfma_f32_16x16x32_bf16 v[120:123], v[164:167], v[188:191], v[120:123]
	v_mfma_f32_16x16x32_bf16 v[108:111], v[156:159], v[200:203], v[108:111]
	v_mfma_f32_16x16x32_bf16 v[104:107], v[164:167], v[200:203], v[104:107]
	v_mfma_f32_16x16x32_bf16 v[92:95], v[156:159], v[208:211], v[92:95]
	v_mfma_f32_16x16x32_bf16 v[88:91], v[164:167], v[208:211], v[88:91]
	v_mfma_f32_16x16x32_bf16 v[76:79], v[156:159], v[216:219], v[76:79]
	v_mfma_f32_16x16x32_bf16 v[72:75], v[164:167], v[216:219], v[72:75]
	v_mfma_f32_16x16x32_bf16 v[116:119], v[168:171], v[184:187], v[116:119]
	v_mfma_f32_16x16x32_bf16 v[112:115], v[176:179], v[184:187], v[112:115]
	v_mfma_f32_16x16x32_bf16 v[100:103], v[168:171], v[192:195], v[100:103]
	v_mfma_f32_16x16x32_bf16 v[96:99], v[176:179], v[192:195], v[96:99]
	v_mfma_f32_16x16x32_bf16 v[84:87], v[168:171], v[204:207], v[84:87]
	v_mfma_f32_16x16x32_bf16 v[80:83], v[176:179], v[204:207], v[80:83]
	v_mfma_f32_16x16x32_bf16 v[68:71], v[168:171], v[212:215], v[68:71]
	v_mfma_f32_16x16x32_bf16 v[64:67], v[176:179], v[212:215], v[64:67]
	v_mfma_f32_16x16x32_bf16 v[116:119], v[172:175], v[188:191], v[116:119]
	v_mfma_f32_16x16x32_bf16 v[112:115], v[180:183], v[188:191], v[112:115]
	v_mfma_f32_16x16x32_bf16 v[100:103], v[172:175], v[200:203], v[100:103]
	v_mfma_f32_16x16x32_bf16 v[96:99], v[180:183], v[200:203], v[96:99]
	v_mfma_f32_16x16x32_bf16 v[84:87], v[172:175], v[208:211], v[84:87]
	v_mfma_f32_16x16x32_bf16 v[80:83], v[180:183], v[208:211], v[80:83]
	v_mfma_f32_16x16x32_bf16 v[68:71], v[172:175], v[216:219], v[68:71]
	v_mfma_f32_16x16x32_bf16 v[64:67], v[180:183], v[216:219], v[64:67]
	s_barrier
	s_setprio 0
	ds_read_b128 v[184:187], v155 offset:16384
	ds_read_b128 v[188:191], v155 offset:17408
	ds_read_b128 v[192:195], v155 offset:18432
	ds_read_b128 v[200:203], v155 offset:19456
	ds_read_b128 v[204:207], v155 offset:20480
	ds_read_b128 v[208:211], v155 offset:21504
	ds_read_b128 v[212:215], v155 offset:22528
	ds_read_b128 v[216:219], v155 offset:23552
	global_load_lds_dwordx4 v130, s[72:73]
	s_add_i32 m0, s88, 0x2000
	s_add_u32 s88, s72, 0x80000
	s_addc_u32 s89, s73, 0
	s_add_i32 s94, s83, s1
	global_load_lds_dwordx4 v134, s[72:73]
	s_mov_b32 m0, s94
	s_nop 0
	global_load_lds_dwordx4 v130, s[88:89]
	s_add_i32 m0, s94, 0x2000
	s_nop 0
	global_load_lds_dwordx4 v134, s[88:89]
	s_mov_b32 m0, s33
	s_nop 0
	global_load_lds_dwordx4 v128, s[74:75]
	s_mov_b32 m0, s35
	s_nop 0
	global_load_lds_dwordx4 v132, s[74:75]
	s_waitcnt vmcnt(8)
	s_waitcnt lgkmcnt(0)
	s_setprio 1
	s_barrier
	v_mfma_f32_16x16x32_bf16 v[60:63], v[144:147], v[184:187], v[60:63]
	v_mfma_f32_16x16x32_bf16 v[56:59], v[160:163], v[184:187], v[56:59]
	v_mfma_f32_16x16x32_bf16 v[44:47], v[144:147], v[192:195], v[44:47]
	v_mfma_f32_16x16x32_bf16 v[40:43], v[160:163], v[192:195], v[40:43]
	v_mfma_f32_16x16x32_bf16 v[28:31], v[144:147], v[204:207], v[28:31]
	v_mfma_f32_16x16x32_bf16 v[24:27], v[160:163], v[204:207], v[24:27]
	v_mfma_f32_16x16x32_bf16 v[12:15], v[144:147], v[212:215], v[12:15]
	v_mfma_f32_16x16x32_bf16 v[8:11], v[160:163], v[212:215], v[8:11]
	v_mfma_f32_16x16x32_bf16 v[60:63], v[156:159], v[188:191], v[60:63]
	v_mfma_f32_16x16x32_bf16 v[56:59], v[164:167], v[188:191], v[56:59]
	v_mfma_f32_16x16x32_bf16 v[44:47], v[156:159], v[200:203], v[44:47]
	v_mfma_f32_16x16x32_bf16 v[40:43], v[164:167], v[200:203], v[40:43]
	v_mfma_f32_16x16x32_bf16 v[28:31], v[156:159], v[208:211], v[28:31]
	v_mfma_f32_16x16x32_bf16 v[24:27], v[164:167], v[208:211], v[24:27]
	v_mfma_f32_16x16x32_bf16 v[12:15], v[156:159], v[216:219], v[12:15]
	v_mfma_f32_16x16x32_bf16 v[8:11], v[164:167], v[216:219], v[8:11]
	v_mfma_f32_16x16x32_bf16 v[52:55], v[168:171], v[184:187], v[52:55]
	v_mfma_f32_16x16x32_bf16 v[48:51], v[176:179], v[184:187], v[48:51]
	v_mfma_f32_16x16x32_bf16 v[36:39], v[168:171], v[192:195], v[36:39]
	v_mfma_f32_16x16x32_bf16 v[32:35], v[176:179], v[192:195], v[32:35]
	v_mfma_f32_16x16x32_bf16 v[20:23], v[168:171], v[204:207], v[20:23]
	v_mfma_f32_16x16x32_bf16 v[16:19], v[176:179], v[204:207], v[16:19]
	v_mfma_f32_16x16x32_bf16 v[4:7], v[168:171], v[212:215], v[4:7]
	v_mfma_f32_16x16x32_bf16 v[0:3], v[176:179], v[212:215], v[0:3]
	v_mfma_f32_16x16x32_bf16 v[52:55], v[172:175], v[188:191], v[52:55]
	v_mfma_f32_16x16x32_bf16 v[48:51], v[180:183], v[188:191], v[48:51]
	v_mfma_f32_16x16x32_bf16 v[36:39], v[172:175], v[200:203], v[36:39]
	v_mfma_f32_16x16x32_bf16 v[32:35], v[180:183], v[200:203], v[32:35]
	v_mfma_f32_16x16x32_bf16 v[20:23], v[172:175], v[208:211], v[20:23]
	v_mfma_f32_16x16x32_bf16 v[16:19], v[180:183], v[208:211], v[16:19]
	v_mfma_f32_16x16x32_bf16 v[4:7], v[172:175], v[216:219], v[4:7]
	v_mfma_f32_16x16x32_bf16 v[0:3], v[180:183], v[216:219], v[0:3]
	s_barrier
; #define PG8_STAGE(bufoff, gbase, voff) do { _Pragma("unroll") for (int _i = 0; _i < 2; ++_i) \
;         __builtin_amdgcn_global_load_lds((const unsigned*)((const char*)(gbase) + (voff)[_i]), (PG8_LAS unsigned*)(lds + (bufoff) + ldsw + _i * 8192), 16, 0, 0); } while (0)
; #define PG8_LDA(dst, b, h) do { _Pragma("unroll") for (int m = 0; m < 4; ++m) _Pragma("unroll") for (int k = 0; k < 2; ++k) dst[m][k] = *(const PG8_LAS bf16x8*)(lds + PG8_SA(b, h) + aoff + m * 2048 + k * 1024); } while (0)
; #define PG8_LDB(dst, b, h) do { _Pragma("unroll") for (int n = 0; n < 2; ++n) _Pragma("unroll") for (int k = 0; k < 2; ++k) dst[n][k] = *(const PG8_LAS bf16x8*)(lds + PG8_SB(b, h) + boff + n * 2048 + k * 1024); } while (0)
; #define PG8_MMA(ai, bj, At, Bt) do { __builtin_amdgcn_s_setprio(1); _Pragma("unroll") for (int m = 0; m < 4; ++m) _Pragma("unroll") for (int n = 0; n < 2; ++n) _Pragma("unroll") for (int k = 0; k < 2; ++k) \
;         acc[ai][bj][m][n] = __builtin_amdgcn_mfma_f32_16x16x32_bf16(Bt[n][k], At[m][k], acc[ai][bj][m][n], 0, 0, 0); __builtin_amdgcn_s_setprio(0); } while (0)
; #define PG8_WAIT_V(n) asm volatile("s_waitcnt vmcnt(" #n ")" ::: "memory")
; #define PG8_WAIT_L(n) asm volatile("s_waitcnt lgkmcnt(" #n ")" ::: "memory")
; #define PG8_BAR __builtin_amdgcn_s_barrier()
; #define PG8_SCHED __builtin_amdgcn_sched_barrier(0)
; template <class Epi, class Sched, bool ALIGN_EPI = false, bool SP2 = false>
; __device__ __forceinline__ void gemm_phase(PG8_LAS unsigned char* lds, const Gemm g, const Sched& S, const Epi& E) {
;     ...
;             PG8_LDB(B0, 1, 0); PG8_LDB(B1, 1, 1); PG8_SCHED; PG8_LDA(At, 1, 0); PG8_STAGE(PG8_SA(0, 1), a2 + hstep, voffA);
;             PG8_WAIT_V(8); PG8_WAIT_L(0); PG8_BAR; PG8_MMA(0, 0, At, B0); PG8_MMA(0, 1, At, B1); PG8_BAR; PG8_SCHED;
;             PG8_LDA(At, 1, 1); PG8_STAGE(PG8_SB(1, 0), b3, voffB); PG8_STAGE(PG8_SB(1, 1), b3 + hstep, voffB); PG8_STAGE(PG8_SA(1, 0), a3, voffA);
;             PG8_WAIT_V(8); PG8_WAIT_L(0); PG8_BAR; PG8_MMA(1, 0, At, B0); PG8_MMA(1, 1, At, B1); PG8_BAR; PG8_SCHED;
;     ...
;         if constexpr (ALIGN_EPI) { if (wr == 0) PG8_BAR; }
	s_setprio 0
	ds_read_b128 v[144:147], v196
	ds_read_b128 v[156:159], v196 offset:1024
	ds_read_b128 v[160:163], v196 offset:2048
	ds_read_b128 v[164:167], v196 offset:3072
	ds_read_b128 v[168:171], v197
	ds_read_b128 v[172:175], v197 offset:1024
	ds_read_b128 v[176:179], v197 offset:2048
	ds_read_b128 v[180:183], v197 offset:3072
	ds_read_b128 v[184:187], v155 offset:32768
	ds_read_b128 v[188:191], v155 offset:33792
	ds_read_b128 v[192:195], v155 offset:34816
	ds_read_b128 v[200:203], v155 offset:35840
	ds_read_b128 v[204:207], v155 offset:36864
	ds_read_b128 v[208:211], v155 offset:37888
	ds_read_b128 v[212:215], v155 offset:38912
	ds_read_b128 v[216:219], v155 offset:39936
	s_add_u32 s98, s74, 0x80000
	s_addc_u32 s99, s75, 0
	s_mov_b32 m0, s69
	s_add_u32 s100, s74, 0x80
	s_addc_u32 s101, s75, 0
	global_load_lds_dwordx4 v128, s[98:99]
	s_mov_b32 m0, s76
	s_nop 0
	global_load_lds_dwordx4 v132, s[98:99]
	s_add_i32 s88, 0, 0x18000
	s_add_i32 s89, 0, 0x1c000
	s_add_u32 s98, s72, 0x80
	s_addc_u32 s99, s73, 0
	s_add_i32 s74, s88, s1
	s_mov_b32 m0, s74
	s_waitcnt vmcnt(8)
	s_waitcnt lgkmcnt(0)
	s_setprio 1
	s_barrier
	v_mfma_f32_16x16x32_bf16 v[124:127], v[144:147], v[184:187], v[124:127]
	v_mfma_f32_16x16x32_bf16 v[120:123], v[160:163], v[184:187], v[120:123]
	v_mfma_f32_16x16x32_bf16 v[108:111], v[144:147], v[192:195], v[108:111]
	v_mfma_f32_16x16x32_bf16 v[104:107], v[160:163], v[192:195], v[104:107]
	v_mfma_f32_16x16x32_bf16 v[92:95], v[144:147], v[204:207], v[92:95]
	v_mfma_f32_16x16x32_bf16 v[88:91], v[160:163], v[204:207], v[88:91]
	v_mfma_f32_16x16x32_bf16 v[76:79], v[144:147], v[212:215], v[76:79]
	v_mfma_f32_16x16x32_bf16 v[72:75], v[160:163], v[212:215], v[72:75]
	v_mfma_f32_16x16x32_bf16 v[124:127], v[156:159], v[188:191], v[124:127]
	v_mfma_f32_16x16x32_bf16 v[120:123], v[164:167], v[188:191], v[120:123]
	v_mfma_f32_16x16x32_bf16 v[108:111], v[156:159], v[200:203], v[108:111]
	v_mfma_f32_16x16x32_bf16 v[104:107], v[164:167], v[200:203], v[104:107]
	v_mfma_f32_16x16x32_bf16 v[92:95], v[156:159], v[208:211], v[92:95]
	v_mfma_f32_16x16x32_bf16 v[88:91], v[164:167], v[208:211], v[88:91]
	v_mfma_f32_16x16x32_bf16 v[76:79], v[156:159], v[216:219], v[76:79]
	v_mfma_f32_16x16x32_bf16 v[72:75], v[164:167], v[216:219], v[72:75]
	v_mfma_f32_16x16x32_bf16 v[116:119], v[168:171], v[184:187], v[116:119]
	v_mfma_f32_16x16x32_bf16 v[112:115], v[176:179], v[184:187], v[112:115]
	v_mfma_f32_16x16x32_bf16 v[100:103], v[168:171], v[192:195], v[100:103]
	v_mfma_f32_16x16x32_bf16 v[96:99], v[176:179], v[192:195], v[96:99]
	v_mfma_f32_16x16x32_bf16 v[84:87], v[168:171], v[204:207], v[84:87]
	v_mfma_f32_16x16x32_bf16 v[80:83], v[176:179], v[204:207], v[80:83]
	v_mfma_f32_16x16x32_bf16 v[68:71], v[168:171], v[212:215], v[68:71]
	v_mfma_f32_16x16x32_bf16 v[64:67], v[176:179], v[212:215], v[64:67]
	v_mfma_f32_16x16x32_bf16 v[116:119], v[172:175], v[188:191], v[116:119]
	v_mfma_f32_16x16x32_bf16 v[112:115], v[180:183], v[188:191], v[112:115]
	v_mfma_f32_16x16x32_bf16 v[100:103], v[172:175], v[200:203], v[100:103]
	v_mfma_f32_16x16x32_bf16 v[96:99], v[180:183], v[200:203], v[96:99]
	v_mfma_f32_16x16x32_bf16 v[84:87], v[172:175], v[208:211], v[84:87]
	v_mfma_f32_16x16x32_bf16 v[80:83], v[180:183], v[208:211], v[80:83]
	v_mfma_f32_16x16x32_bf16 v[68:71], v[172:175], v[216:219], v[68:71]
	v_mfma_f32_16x16x32_bf16 v[64:67], v[180:183], v[216:219], v[64:67]
	s_barrier
	s_setprio 0
	ds_read_b128 v[184:187], v155 offset:49152
	ds_read_b128 v[188:191], v155 offset:50176
	ds_read_b128 v[192:195], v155 offset:51200
	ds_read_b128 v[200:203], v155 offset:52224
	ds_read_b128 v[204:207], v155 offset:53248
	ds_read_b128 v[208:211], v155 offset:54272
	ds_read_b128 v[212:215], v155 offset:55296
	ds_read_b128 v[216:219], v155 offset:56320
	global_load_lds_dwordx4 v130, s[98:99]
	s_add_i32 m0, s74, 0x2000
	s_add_u32 s72, s72, 0x80080
	s_addc_u32 s73, s73, 0
	s_add_i32 s74, s89, s1
	global_load_lds_dwordx4 v134, s[98:99]
	s_mov_b32 m0, s74
	s_nop 0
	global_load_lds_dwordx4 v130, s[72:73]
	s_add_i32 m0, s74, 0x2000
	s_nop 0
	global_load_lds_dwordx4 v134, s[72:73]
	s_mov_b32 m0, s78
	s_nop 0
	global_load_lds_dwordx4 v128, s[100:101]
	s_mov_b32 m0, s79
	s_nop 0
	global_load_lds_dwordx4 v132, s[100:101]
	s_add_i32 s87, s87, 2
	s_add_u32 s70, s70, 0x100
	s_addc_u32 s71, s71, 0
	s_add_u32 s85, s85, 0x100
	s_addc_u32 s86, s86, 0
	s_cmp_gt_u32 s87, 29
	s_waitcnt vmcnt(8)
	s_waitcnt lgkmcnt(0)
	s_setprio 1
	s_barrier
	v_mfma_f32_16x16x32_bf16 v[60:63], v[144:147], v[184:187], v[60:63]
	v_mfma_f32_16x16x32_bf16 v[56:59], v[160:163], v[184:187], v[56:59]
	v_mfma_f32_16x16x32_bf16 v[44:47], v[144:147], v[192:195], v[44:47]
	v_mfma_f32_16x16x32_bf16 v[40:43], v[160:163], v[192:195], v[40:43]
	v_mfma_f32_16x16x32_bf16 v[28:31], v[144:147], v[204:207], v[28:31]
	v_mfma_f32_16x16x32_bf16 v[24:27], v[160:163], v[204:207], v[24:27]
	v_mfma_f32_16x16x32_bf16 v[12:15], v[144:147], v[212:215], v[12:15]
	v_mfma_f32_16x16x32_bf16 v[8:11], v[160:163], v[212:215], v[8:11]
	v_mfma_f32_16x16x32_bf16 v[60:63], v[156:159], v[188:191], v[60:63]
	v_mfma_f32_16x16x32_bf16 v[56:59], v[164:167], v[188:191], v[56:59]
	v_mfma_f32_16x16x32_bf16 v[44:47], v[156:159], v[200:203], v[44:47]
	v_mfma_f32_16x16x32_bf16 v[40:43], v[164:167], v[200:203], v[40:43]
	v_mfma_f32_16x16x32_bf16 v[28:31], v[156:159], v[208:211], v[28:31]
	v_mfma_f32_16x16x32_bf16 v[24:27], v[164:167], v[208:211], v[24:27]
	v_mfma_f32_16x16x32_bf16 v[12:15], v[156:159], v[216:219], v[12:15]
	v_mfma_f32_16x16x32_bf16 v[8:11], v[164:167], v[216:219], v[8:11]
	v_mfma_f32_16x16x32_bf16 v[52:55], v[168:171], v[184:187], v[52:55]
	v_mfma_f32_16x16x32_bf16 v[48:51], v[176:179], v[184:187], v[48:51]
	v_mfma_f32_16x16x32_bf16 v[36:39], v[168:171], v[192:195], v[36:39]
	v_mfma_f32_16x16x32_bf16 v[32:35], v[176:179], v[192:195], v[32:35]
	v_mfma_f32_16x16x32_bf16 v[20:23], v[168:171], v[204:207], v[20:23]
	v_mfma_f32_16x16x32_bf16 v[16:19], v[176:179], v[204:207], v[16:19]
	v_mfma_f32_16x16x32_bf16 v[4:7], v[168:171], v[212:215], v[4:7]
	v_mfma_f32_16x16x32_bf16 v[0:3], v[176:179], v[212:215], v[0:3]
	v_mfma_f32_16x16x32_bf16 v[52:55], v[172:175], v[188:191], v[52:55]
	v_mfma_f32_16x16x32_bf16 v[48:51], v[180:183], v[188:191], v[48:51]
	v_mfma_f32_16x16x32_bf16 v[36:39], v[172:175], v[200:203], v[36:39]
	v_mfma_f32_16x16x32_bf16 v[32:35], v[180:183], v[200:203], v[32:35]
	v_mfma_f32_16x16x32_bf16 v[20:23], v[172:175], v[208:211], v[20:23]
	v_mfma_f32_16x16x32_bf16 v[16:19], v[180:183], v[208:211], v[16:19]
	v_mfma_f32_16x16x32_bf16 v[4:7], v[172:175], v[216:219], v[4:7]
	v_mfma_f32_16x16x32_bf16 v[0:3], v[180:183], v[216:219], v[0:3]
	s_barrier
	s_setprio 0
	s_cbranch_scc0 .LBB0_245
	s_and_b64 vcc, exec, s[14:15]
	s_cbranch_vccz .LBB0_248
	s_barrier

; #define PG8_STAGE(bufoff, gbase, voff) do { _Pragma("unroll") for (int _i = 0; _i < 2; ++_i) \
;         __builtin_amdgcn_global_load_lds((const unsigned*)((const char*)(gbase) + (voff)[_i]), (PG8_LAS unsigned*)(lds + (bufoff) + ldsw + _i * 8192), 16, 0, 0); } while (0)
; #define PG8_LDA(dst, b, h) do { _Pragma("unroll") for (int m = 0; m < 4; ++m) _Pragma("unroll") for (int k = 0; k < 2; ++k) dst[m][k] = *(const PG8_LAS bf16x8*)(lds + PG8_SA(b, h) + aoff + m * 2048 + k * 1024); } while (0)
; #define PG8_LDB(dst, b, h) do { _Pragma("unroll") for (int n = 0; n < 2; ++n) _Pragma("unroll") for (int k = 0; k < 2; ++k) dst[n][k] = *(const PG8_LAS bf16x8*)(lds + PG8_SB(b, h) + boff + n * 2048 + k * 1024); } while (0)
; #define PG8_MMA(ai, bj, At, Bt) do { __builtin_amdgcn_s_setprio(1); _Pragma("unroll") for (int m = 0; m < 4; ++m) _Pragma("unroll") for (int n = 0; n < 2; ++n) _Pragma("unroll") for (int k = 0; k < 2; ++k) \
;         acc[ai][bj][m][n] = __builtin_amdgcn_mfma_f32_16x16x32_bf16(Bt[n][k], At[m][k], acc[ai][bj][m][n], 0, 0, 0); __builtin_amdgcn_s_setprio(0); } while (0)
; #define PG8_WAIT_V(n) asm volatile("s_waitcnt vmcnt(" #n ")" ::: "memory")
; #define PG8_WAIT_L(n) asm volatile("s_waitcnt lgkmcnt(" #n ")" ::: "memory")
; #define PG8_BAR __builtin_amdgcn_s_barrier()
; template <class Epi, class Sched, bool ALIGN_EPI = false, bool SP2 = false>
; __device__ __forceinline__ void gemm_phase(PG8_LAS unsigned char* lds, const Gemm g, const Sched& S, const Epi& E) {
;     ...
;             const char* a1 = cA + (size_t)(t + 1) * kstep;
;             const char* a2 = last ? nA : cA + (size_t)(t + 2) * kstep; const char* b2 = last ? nB : cB + (size_t)(t + 2) * kstep;
;             const char* a3 = a2 + kstep; const char* b3 = b2 + kstep;
;             if (last && has_next) S.a_ready(nxt);
;             if constexpr (SP2) {
;             PG8_LDB(B0, 0, 0); PG8_LDB(B1, 0, 1); PG8_SCHED; PG8_LDA(At, 0, 0); PG8_STAGE(PG8_SA(1, 1), a1 + hstep, voffA);
;             PG8_WAIT_V(8); PG8_WAIT_L(0); PG8_BAR; PG8_MMA(0, 0, At, B0); PG8_MMA(0, 1, At, B1); PG8_BAR; PG8_SCHED;
;             PG8_LDA(At, 0, 1); PG8_STAGE(PG8_SB(0, 0), b2, voffB); PG8_STAGE(PG8_SB(0, 1), b2 + hstep, voffB); PG8_STAGE(PG8_SA(0, 0), a2, voffA);
;             PG8_WAIT_V(8); PG8_WAIT_L(0); PG8_BAR; PG8_MMA(1, 0, At, B0); PG8_MMA(1, 1, At, B1); PG8_BAR; PG8_SCHED;
.LBB0_376:
	ds_read_b128 v[152:155], v149
	ds_read_b128 v[156:159], v149 offset:1024
	ds_read_b128 v[160:163], v149 offset:2048
	ds_read_b128 v[164:167], v149 offset:3072
	ds_read_b128 v[168:171], v150
	ds_read_b128 v[172:175], v150 offset:1024
	ds_read_b128 v[176:179], v150 offset:2048
	ds_read_b128 v[180:183], v150 offset:3072
	s_add_i32 m0, s33, 0xc000
	ds_read_b128 v[184:187], v151
	ds_read_b128 v[188:191], v151 offset:1024
	ds_read_b128 v[192:195], v151 offset:2048
	ds_read_b128 v[200:203], v151 offset:3072
	ds_read_b128 v[204:207], v151 offset:4096
	ds_read_b128 v[208:211], v151 offset:5120
	ds_read_b128 v[212:215], v151 offset:6144
	ds_read_b128 v[216:219], v151 offset:7168
	global_load_lds_dwordx4 v136, s[68:69]
	s_add_i32 m0, s33, 0xe000
	s_nop 0
	global_load_lds_dwordx4 v138, s[68:69]
	s_add_u32 s70, s68, 0xfff80080
	s_addc_u32 s71, s69, -1
	s_cmp_eq_u32 s88, 28
	s_cselect_b32 s73, s25, s71
	s_cselect_b32 s72, s61, s70
	s_cselect_b32 s71, s49, s87
	s_cselect_b32 s70, s85, s86
	s_add_i32 s89, s80, s1
	s_mov_b32 m0, s89
	s_waitcnt vmcnt(8)
	s_waitcnt lgkmcnt(0)
	s_setprio 1
	s_barrier
	v_mfma_f32_16x16x32_bf16 v[124:127], v[152:155], v[184:187], v[124:127]
	v_mfma_f32_16x16x32_bf16 v[120:123], v[160:163], v[184:187], v[120:123]
	v_mfma_f32_16x16x32_bf16 v[108:111], v[152:155], v[192:195], v[108:111]
	v_mfma_f32_16x16x32_bf16 v[104:107], v[160:163], v[192:195], v[104:107]
	v_mfma_f32_16x16x32_bf16 v[92:95], v[152:155], v[204:207], v[92:95]
	v_mfma_f32_16x16x32_bf16 v[88:91], v[160:163], v[204:207], v[88:91]
	v_mfma_f32_16x16x32_bf16 v[76:79], v[152:155], v[212:215], v[76:79]
	v_mfma_f32_16x16x32_bf16 v[72:75], v[160:163], v[212:215], v[72:75]
	v_mfma_f32_16x16x32_bf16 v[124:127], v[156:159], v[188:191], v[124:127]
	v_mfma_f32_16x16x32_bf16 v[120:123], v[164:167], v[188:191], v[120:123]
	v_mfma_f32_16x16x32_bf16 v[108:111], v[156:159], v[200:203], v[108:111]
	v_mfma_f32_16x16x32_bf16 v[104:107], v[164:167], v[200:203], v[104:107]
	v_mfma_f32_16x16x32_bf16 v[92:95], v[156:159], v[208:211], v[92:95]
	v_mfma_f32_16x16x32_bf16 v[88:91], v[164:167], v[208:211], v[88:91]
	v_mfma_f32_16x16x32_bf16 v[76:79], v[156:159], v[216:219], v[76:79]
	v_mfma_f32_16x16x32_bf16 v[72:75], v[164:167], v[216:219], v[72:75]
	v_mfma_f32_16x16x32_bf16 v[116:119], v[168:171], v[184:187], v[116:119]
	v_mfma_f32_16x16x32_bf16 v[112:115], v[176:179], v[184:187], v[112:115]
	v_mfma_f32_16x16x32_bf16 v[100:103], v[168:171], v[192:195], v[100:103]
	v_mfma_f32_16x16x32_bf16 v[96:99], v[176:179], v[192:195], v[96:99]
	v_mfma_f32_16x16x32_bf16 v[84:87], v[168:171], v[204:207], v[84:87]
	v_mfma_f32_16x16x32_bf16 v[80:83], v[176:179], v[204:207], v[80:83]
	v_mfma_f32_16x16x32_bf16 v[68:71], v[168:171], v[212:215], v[68:71]
	v_mfma_f32_16x16x32_bf16 v[64:67], v[176:179], v[212:215], v[64:67]
	v_mfma_f32_16x16x32_bf16 v[116:119], v[172:175], v[188:191], v[116:119]
	v_mfma_f32_16x16x32_bf16 v[112:115], v[180:183], v[188:191], v[112:115]
	v_mfma_f32_16x16x32_bf16 v[100:103], v[172:175], v[200:203], v[100:103]
	v_mfma_f32_16x16x32_bf16 v[96:99], v[180:183], v[200:203], v[96:99]
	v_mfma_f32_16x16x32_bf16 v[84:87], v[172:175], v[208:211], v[84:87]
	v_mfma_f32_16x16x32_bf16 v[80:83], v[180:183], v[208:211], v[80:83]
	v_mfma_f32_16x16x32_bf16 v[68:71], v[172:175], v[216:219], v[68:71]
	v_mfma_f32_16x16x32_bf16 v[64:67], v[180:183], v[216:219], v[64:67]
	s_barrier
	s_setprio 0
	ds_read_b128 v[184:187], v151 offset:16384
	ds_read_b128 v[188:191], v151 offset:17408
	ds_read_b128 v[192:195], v151 offset:18432
	ds_read_b128 v[200:203], v151 offset:19456
	ds_read_b128 v[204:207], v151 offset:20480
	ds_read_b128 v[208:211], v151 offset:21504
	ds_read_b128 v[212:215], v151 offset:22528
	ds_read_b128 v[216:219], v151 offset:23552
	global_load_lds_dwordx4 v130, s[70:71]
	s_add_i32 m0, s89, 0x2000
	s_add_u32 s96, s70, 0x80000
	s_addc_u32 s97, s71, 0
	s_add_i32 s89, s81, s1
	global_load_lds_dwordx4 v134, s[70:71]
	s_mov_b32 m0, s89
	s_nop 0
	global_load_lds_dwordx4 v130, s[96:97]
	s_add_i32 m0, s89, 0x2000
	s_nop 0
	global_load_lds_dwordx4 v134, s[96:97]
	s_mov_b32 m0, s33
	s_nop 0
	global_load_lds_dwordx4 v128, s[72:73]
	s_mov_b32 m0, s35
	s_nop 0
	global_load_lds_dwordx4 v132, s[72:73]
	s_waitcnt vmcnt(8)
	s_waitcnt lgkmcnt(0)
	s_setprio 1
	s_barrier
	v_mfma_f32_16x16x32_bf16 v[60:63], v[152:155], v[184:187], v[60:63]
	v_mfma_f32_16x16x32_bf16 v[56:59], v[160:163], v[184:187], v[56:59]
	v_mfma_f32_16x16x32_bf16 v[44:47], v[152:155], v[192:195], v[44:47]
	v_mfma_f32_16x16x32_bf16 v[40:43], v[160:163], v[192:195], v[40:43]
	v_mfma_f32_16x16x32_bf16 v[28:31], v[152:155], v[204:207], v[28:31]
	v_mfma_f32_16x16x32_bf16 v[24:27], v[160:163], v[204:207], v[24:27]
	v_mfma_f32_16x16x32_bf16 v[12:15], v[152:155], v[212:215], v[12:15]
	v_mfma_f32_16x16x32_bf16 v[8:11], v[160:163], v[212:215], v[8:11]
	v_mfma_f32_16x16x32_bf16 v[60:63], v[156:159], v[188:191], v[60:63]
	v_mfma_f32_16x16x32_bf16 v[56:59], v[164:167], v[188:191], v[56:59]
	v_mfma_f32_16x16x32_bf16 v[44:47], v[156:159], v[200:203], v[44:47]
	v_mfma_f32_16x16x32_bf16 v[40:43], v[164:167], v[200:203], v[40:43]
	v_mfma_f32_16x16x32_bf16 v[28:31], v[156:159], v[208:211], v[28:31]
	v_mfma_f32_16x16x32_bf16 v[24:27], v[164:167], v[208:211], v[24:27]
	v_mfma_f32_16x16x32_bf16 v[12:15], v[156:159], v[216:219], v[12:15]
	v_mfma_f32_16x16x32_bf16 v[8:11], v[164:167], v[216:219], v[8:11]
	v_mfma_f32_16x16x32_bf16 v[52:55], v[168:171], v[184:187], v[52:55]
	v_mfma_f32_16x16x32_bf16 v[48:51], v[176:179], v[184:187], v[48:51]
	v_mfma_f32_16x16x32_bf16 v[36:39], v[168:171], v[192:195], v[36:39]
	v_mfma_f32_16x16x32_bf16 v[32:35], v[176:179], v[192:195], v[32:35]
	v_mfma_f32_16x16x32_bf16 v[20:23], v[168:171], v[204:207], v[20:23]
	v_mfma_f32_16x16x32_bf16 v[16:19], v[176:179], v[204:207], v[16:19]
	v_mfma_f32_16x16x32_bf16 v[4:7], v[168:171], v[212:215], v[4:7]
	v_mfma_f32_16x16x32_bf16 v[0:3], v[176:179], v[212:215], v[0:3]
	v_mfma_f32_16x16x32_bf16 v[52:55], v[172:175], v[188:191], v[52:55]
	v_mfma_f32_16x16x32_bf16 v[48:51], v[180:183], v[188:191], v[48:51]
	v_mfma_f32_16x16x32_bf16 v[36:39], v[172:175], v[200:203], v[36:39]
	v_mfma_f32_16x16x32_bf16 v[32:35], v[180:183], v[200:203], v[32:35]
	v_mfma_f32_16x16x32_bf16 v[20:23], v[172:175], v[208:211], v[20:23]
	v_mfma_f32_16x16x32_bf16 v[16:19], v[180:183], v[208:211], v[16:19]
	v_mfma_f32_16x16x32_bf16 v[4:7], v[172:175], v[216:219], v[4:7]
	v_mfma_f32_16x16x32_bf16 v[0:3], v[180:183], v[216:219], v[0:3]
	s_barrier
; #define PG8_STAGE(bufoff, gbase, voff) do { _Pragma("unroll") for (int _i = 0; _i < 2; ++_i) \
;         __builtin_amdgcn_global_load_lds((const unsigned*)((const char*)(gbase) + (voff)[_i]), (PG8_LAS unsigned*)(lds + (bufoff) + ldsw + _i * 8192), 16, 0, 0); } while (0)
; #define PG8_LDA(dst, b, h) do { _Pragma("unroll") for (int m = 0; m < 4; ++m) _Pragma("unroll") for (int k = 0; k < 2; ++k) dst[m][k] = *(const PG8_LAS bf16x8*)(lds + PG8_SA(b, h) + aoff + m * 2048 + k * 1024); } while (0)
; #define PG8_LDB(dst, b, h) do { _Pragma("unroll") for (int n = 0; n < 2; ++n) _Pragma("unroll") for (int k = 0; k < 2; ++k) dst[n][k] = *(const PG8_LAS bf16x8*)(lds + PG8_SB(b, h) + boff + n * 2048 + k * 1024); } while (0)
; #define PG8_MMA(ai, bj, At, Bt) do { __builtin_amdgcn_s_setprio(1); _Pragma("unroll") for (int m = 0; m < 4; ++m) _Pragma("unroll") for (int n = 0; n < 2; ++n) _Pragma("unroll") for (int k = 0; k < 2; ++k) \
;         acc[ai][bj][m][n] = __builtin_amdgcn_mfma_f32_16x16x32_bf16(Bt[n][k], At[m][k], acc[ai][bj][m][n], 0, 0, 0); __builtin_amdgcn_s_setprio(0); } while (0)
; #define PG8_WAIT_V(n) asm volatile("s_waitcnt vmcnt(" #n ")" ::: "memory")
; #define PG8_WAIT_L(n) asm volatile("s_waitcnt lgkmcnt(" #n ")" ::: "memory")
; #define PG8_BAR __builtin_amdgcn_s_barrier()
; #define PG8_SCHED __builtin_amdgcn_sched_barrier(0)
; template <class Epi, class Sched, bool ALIGN_EPI = false, bool SP2 = false>
; __device__ __forceinline__ void gemm_phase(PG8_LAS unsigned char* lds, const Gemm g, const Sched& S, const Epi& E) {
;     ...
;             PG8_LDB(B0, 1, 0); PG8_LDB(B1, 1, 1); PG8_SCHED; PG8_LDA(At, 1, 0); PG8_STAGE(PG8_SA(0, 1), a2 + hstep, voffA);
;             PG8_WAIT_V(8); PG8_WAIT_L(0); PG8_BAR; PG8_MMA(0, 0, At, B0); PG8_MMA(0, 1, At, B1); PG8_BAR; PG8_SCHED;
;             PG8_LDA(At, 1, 1); PG8_STAGE(PG8_SB(1, 0), b3, voffB); PG8_STAGE(PG8_SB(1, 1), b3 + hstep, voffB); PG8_STAGE(PG8_SA(1, 0), a3, voffA);
;             PG8_WAIT_V(8); PG8_WAIT_L(0); PG8_BAR; PG8_MMA(1, 0, At, B0); PG8_MMA(1, 1, At, B1); PG8_BAR; PG8_SCHED;
;     ...
;         if constexpr (ALIGN_EPI) { if (wr == 0) PG8_BAR; }
	s_setprio 0
	ds_read_b128 v[152:155], v196
	ds_read_b128 v[156:159], v196 offset:1024
	ds_read_b128 v[160:163], v196 offset:2048
	ds_read_b128 v[164:167], v196 offset:3072
	ds_read_b128 v[168:171], v197
	ds_read_b128 v[172:175], v197 offset:1024
	ds_read_b128 v[176:179], v197 offset:2048
	ds_read_b128 v[180:183], v197 offset:3072
	ds_read_b128 v[184:187], v151 offset:32768
	ds_read_b128 v[188:191], v151 offset:33792
	ds_read_b128 v[192:195], v151 offset:34816
	ds_read_b128 v[200:203], v151 offset:35840
	ds_read_b128 v[204:207], v151 offset:36864
	ds_read_b128 v[208:211], v151 offset:37888
	ds_read_b128 v[212:215], v151 offset:38912
	ds_read_b128 v[216:219], v151 offset:39936
	s_add_u32 s98, s72, 0x80000
	s_addc_u32 s99, s73, 0
	s_mov_b32 m0, s67
	s_add_u32 s100, s72, 0x80
	s_addc_u32 s101, s73, 0
	global_load_lds_dwordx4 v128, s[98:99]
	s_mov_b32 m0, s74
	s_nop 0
	global_load_lds_dwordx4 v132, s[98:99]
	s_add_i32 s89, 0, 0x18000
	s_add_i32 s94, 0, 0x1c000
	s_add_u32 s98, s70, 0x80
	s_addc_u32 s99, s71, 0
	s_add_i32 s72, s89, s1
	s_mov_b32 m0, s72
	s_waitcnt vmcnt(8)
	s_waitcnt lgkmcnt(0)
	s_setprio 1
	s_barrier
	v_mfma_f32_16x16x32_bf16 v[124:127], v[152:155], v[184:187], v[124:127]
	v_mfma_f32_16x16x32_bf16 v[120:123], v[160:163], v[184:187], v[120:123]
	v_mfma_f32_16x16x32_bf16 v[108:111], v[152:155], v[192:195], v[108:111]
	v_mfma_f32_16x16x32_bf16 v[104:107], v[160:163], v[192:195], v[104:107]
	v_mfma_f32_16x16x32_bf16 v[92:95], v[152:155], v[204:207], v[92:95]
	v_mfma_f32_16x16x32_bf16 v[88:91], v[160:163], v[204:207], v[88:91]
	v_mfma_f32_16x16x32_bf16 v[76:79], v[152:155], v[212:215], v[76:79]
	v_mfma_f32_16x16x32_bf16 v[72:75], v[160:163], v[212:215], v[72:75]
	v_mfma_f32_16x16x32_bf16 v[124:127], v[156:159], v[188:191], v[124:127]
	v_mfma_f32_16x16x32_bf16 v[120:123], v[164:167], v[188:191], v[120:123]
	v_mfma_f32_16x16x32_bf16 v[108:111], v[156:159], v[200:203], v[108:111]
	v_mfma_f32_16x16x32_bf16 v[104:107], v[164:167], v[200:203], v[104:107]
	v_mfma_f32_16x16x32_bf16 v[92:95], v[156:159], v[208:211], v[92:95]
	v_mfma_f32_16x16x32_bf16 v[88:91], v[164:167], v[208:211], v[88:91]
	v_mfma_f32_16x16x32_bf16 v[76:79], v[156:159], v[216:219], v[76:79]
	v_mfma_f32_16x16x32_bf16 v[72:75], v[164:167], v[216:219], v[72:75]
	v_mfma_f32_16x16x32_bf16 v[116:119], v[168:171], v[184:187], v[116:119]
	v_mfma_f32_16x16x32_bf16 v[112:115], v[176:179], v[184:187], v[112:115]
	v_mfma_f32_16x16x32_bf16 v[100:103], v[168:171], v[192:195], v[100:103]
	v_mfma_f32_16x16x32_bf16 v[96:99], v[176:179], v[192:195], v[96:99]
	v_mfma_f32_16x16x32_bf16 v[84:87], v[168:171], v[204:207], v[84:87]
	v_mfma_f32_16x16x32_bf16 v[80:83], v[176:179], v[204:207], v[80:83]
	v_mfma_f32_16x16x32_bf16 v[68:71], v[168:171], v[212:215], v[68:71]
	v_mfma_f32_16x16x32_bf16 v[64:67], v[176:179], v[212:215], v[64:67]
	v_mfma_f32_16x16x32_bf16 v[116:119], v[172:175], v[188:191], v[116:119]
	v_mfma_f32_16x16x32_bf16 v[112:115], v[180:183], v[188:191], v[112:115]
	v_mfma_f32_16x16x32_bf16 v[100:103], v[172:175], v[200:203], v[100:103]
	v_mfma_f32_16x16x32_bf16 v[96:99], v[180:183], v[200:203], v[96:99]
	v_mfma_f32_16x16x32_bf16 v[84:87], v[172:175], v[208:211], v[84:87]
	v_mfma_f32_16x16x32_bf16 v[80:83], v[180:183], v[208:211], v[80:83]
	v_mfma_f32_16x16x32_bf16 v[68:71], v[172:175], v[216:219], v[68:71]
	v_mfma_f32_16x16x32_bf16 v[64:67], v[180:183], v[216:219], v[64:67]
	s_barrier
	s_setprio 0
	ds_read_b128 v[184:187], v151 offset:49152
	ds_read_b128 v[188:191], v151 offset:50176
	ds_read_b128 v[192:195], v151 offset:51200
	ds_read_b128 v[200:203], v151 offset:52224
	ds_read_b128 v[204:207], v151 offset:53248
	ds_read_b128 v[208:211], v151 offset:54272
	ds_read_b128 v[212:215], v151 offset:55296
	ds_read_b128 v[216:219], v151 offset:56320
	global_load_lds_dwordx4 v130, s[98:99]
	s_add_i32 m0, s72, 0x2000
	s_add_u32 s70, s70, 0x80080
	s_addc_u32 s71, s71, 0
	s_add_i32 s72, s94, s1
	global_load_lds_dwordx4 v134, s[98:99]
	s_mov_b32 m0, s72
	s_nop 0
	global_load_lds_dwordx4 v130, s[70:71]
	s_add_i32 m0, s72, 0x2000
	s_nop 0
	global_load_lds_dwordx4 v134, s[70:71]
	s_mov_b32 m0, s76
	s_nop 0
	global_load_lds_dwordx4 v128, s[100:101]
	s_mov_b32 m0, s77
	s_nop 0
	global_load_lds_dwordx4 v132, s[100:101]
	s_add_i32 s88, s88, 2
	s_add_u32 s68, s68, 0x100
	s_addc_u32 s69, s69, 0
	s_add_u32 s86, s86, 0x100
	s_addc_u32 s87, s87, 0
	s_cmp_gt_u32 s88, 29
	s_waitcnt vmcnt(8)
	s_waitcnt lgkmcnt(0)
	s_setprio 1
	s_barrier
	v_mfma_f32_16x16x32_bf16 v[60:63], v[152:155], v[184:187], v[60:63]
	v_mfma_f32_16x16x32_bf16 v[56:59], v[160:163], v[184:187], v[56:59]
	v_mfma_f32_16x16x32_bf16 v[44:47], v[152:155], v[192:195], v[44:47]
	v_mfma_f32_16x16x32_bf16 v[40:43], v[160:163], v[192:195], v[40:43]
	v_mfma_f32_16x16x32_bf16 v[28:31], v[152:155], v[204:207], v[28:31]
	v_mfma_f32_16x16x32_bf16 v[24:27], v[160:163], v[204:207], v[24:27]
	v_mfma_f32_16x16x32_bf16 v[12:15], v[152:155], v[212:215], v[12:15]
	v_mfma_f32_16x16x32_bf16 v[8:11], v[160:163], v[212:215], v[8:11]
	v_mfma_f32_16x16x32_bf16 v[60:63], v[156:159], v[188:191], v[60:63]
	v_mfma_f32_16x16x32_bf16 v[56:59], v[164:167], v[188:191], v[56:59]
	v_mfma_f32_16x16x32_bf16 v[44:47], v[156:159], v[200:203], v[44:47]
	v_mfma_f32_16x16x32_bf16 v[40:43], v[164:167], v[200:203], v[40:43]
	v_mfma_f32_16x16x32_bf16 v[28:31], v[156:159], v[208:211], v[28:31]
	v_mfma_f32_16x16x32_bf16 v[24:27], v[164:167], v[208:211], v[24:27]
	v_mfma_f32_16x16x32_bf16 v[12:15], v[156:159], v[216:219], v[12:15]
	v_mfma_f32_16x16x32_bf16 v[8:11], v[164:167], v[216:219], v[8:11]
	v_mfma_f32_16x16x32_bf16 v[52:55], v[168:171], v[184:187], v[52:55]
	v_mfma_f32_16x16x32_bf16 v[48:51], v[176:179], v[184:187], v[48:51]
	v_mfma_f32_16x16x32_bf16 v[36:39], v[168:171], v[192:195], v[36:39]
	v_mfma_f32_16x16x32_bf16 v[32:35], v[176:179], v[192:195], v[32:35]
	v_mfma_f32_16x16x32_bf16 v[20:23], v[168:171], v[204:207], v[20:23]
	v_mfma_f32_16x16x32_bf16 v[16:19], v[176:179], v[204:207], v[16:19]
	v_mfma_f32_16x16x32_bf16 v[4:7], v[168:171], v[212:215], v[4:7]
	v_mfma_f32_16x16x32_bf16 v[0:3], v[176:179], v[212:215], v[0:3]
	v_mfma_f32_16x16x32_bf16 v[52:55], v[172:175], v[188:191], v[52:55]
	v_mfma_f32_16x16x32_bf16 v[48:51], v[180:183], v[188:191], v[48:51]
	v_mfma_f32_16x16x32_bf16 v[36:39], v[172:175], v[200:203], v[36:39]
	v_mfma_f32_16x16x32_bf16 v[32:35], v[180:183], v[200:203], v[32:35]
	v_mfma_f32_16x16x32_bf16 v[20:23], v[172:175], v[208:211], v[20:23]
	v_mfma_f32_16x16x32_bf16 v[16:19], v[180:183], v[208:211], v[16:19]
	v_mfma_f32_16x16x32_bf16 v[4:7], v[172:175], v[216:219], v[4:7]
	v_mfma_f32_16x16x32_bf16 v[0:3], v[180:183], v[216:219], v[0:3]
	s_barrier
	s_setprio 0
	s_cbranch_scc0 .LBB0_376
	s_and_b64 vcc, exec, s[14:15]
	s_cbranch_vccz .LBB0_379
	s_barrier

; #define PG8_STAGE(bufoff, gbase, voff) do { _Pragma("unroll") for (int _i = 0; _i < 2; ++_i) \
;         __builtin_amdgcn_global_load_lds((const unsigned*)((const char*)(gbase) + (voff)[_i]), (PG8_LAS unsigned*)(lds + (bufoff) + ldsw + _i * 8192), 16, 0, 0); } while (0)
; #define PG8_LDA(dst, b, h) do { _Pragma("unroll") for (int m = 0; m < 4; ++m) _Pragma("unroll") for (int k = 0; k < 2; ++k) dst[m][k] = *(const PG8_LAS bf16x8*)(lds + PG8_SA(b, h) + aoff + m * 2048 + k * 1024); } while (0)
; #define PG8_LDB(dst, b, h) do { _Pragma("unroll") for (int n = 0; n < 2; ++n) _Pragma("unroll") for (int k = 0; k < 2; ++k) dst[n][k] = *(const PG8_LAS bf16x8*)(lds + PG8_SB(b, h) + boff + n * 2048 + k * 1024); } while (0)
; #define PG8_MMA(ai, bj, At, Bt) do { __builtin_amdgcn_s_setprio(1); _Pragma("unroll") for (int m = 0; m < 4; ++m) _Pragma("unroll") for (int n = 0; n < 2; ++n) _Pragma("unroll") for (int k = 0; k < 2; ++k) \
;         acc[ai][bj][m][n] = __builtin_amdgcn_mfma_f32_16x16x32_bf16(Bt[n][k], At[m][k], acc[ai][bj][m][n], 0, 0, 0); __builtin_amdgcn_s_setprio(0); } while (0)
; #define PG8_WAIT_V(n) asm volatile("s_waitcnt vmcnt(" #n ")" ::: "memory")
; #define PG8_WAIT_L(n) asm volatile("s_waitcnt lgkmcnt(" #n ")" ::: "memory")
; #define PG8_BAR __builtin_amdgcn_s_barrier()
; template <class Epi, class Sched, bool ALIGN_EPI = false, bool SP2 = false>
; __device__ __forceinline__ void gemm_phase(PG8_LAS unsigned char* lds, const Gemm g, const Sched& S, const Epi& E) {
;     ...
;             const char* a1 = cA + (size_t)(t + 1) * kstep;
;             const char* a2 = last ? nA : cA + (size_t)(t + 2) * kstep; const char* b2 = last ? nB : cB + (size_t)(t + 2) * kstep;
;             const char* a3 = a2 + kstep; const char* b3 = b2 + kstep;
;             if (last && has_next) S.a_ready(nxt);
;             if constexpr (SP2) {
;             PG8_LDB(B0, 0, 0); PG8_LDB(B1, 0, 1); PG8_SCHED; PG8_LDA(At, 0, 0); PG8_STAGE(PG8_SA(1, 1), a1 + hstep, voffA);
;             PG8_WAIT_V(8); PG8_WAIT_L(0); PG8_BAR; PG8_MMA(0, 0, At, B0); PG8_MMA(0, 1, At, B1); PG8_BAR; PG8_SCHED;
;             PG8_LDA(At, 0, 1); PG8_STAGE(PG8_SB(0, 0), b2, voffB); PG8_STAGE(PG8_SB(0, 1), b2 + hstep, voffB); PG8_STAGE(PG8_SA(0, 0), a2, voffA);
;             PG8_WAIT_V(8); PG8_WAIT_L(0); PG8_BAR; PG8_MMA(1, 0, At, B0); PG8_MMA(1, 1, At, B1); PG8_BAR; PG8_SCHED;
.LBB0_452:
	ds_read_b128 v[128:131], v202
	ds_read_b128 v[132:135], v202 offset:1024
	ds_read_b128 v[136:139], v202 offset:2048
	ds_read_b128 v[140:143], v202 offset:3072
	ds_read_b128 v[144:147], v203
	ds_read_b128 v[148:151], v203 offset:1024
	ds_read_b128 v[152:155], v203 offset:2048
	ds_read_b128 v[156:159], v203 offset:3072
	s_add_i32 m0, s33, 0xc000
	ds_read_b128 v[160:163], v204
	ds_read_b128 v[164:167], v204 offset:1024
	ds_read_b128 v[184:187], v204 offset:2048
	ds_read_b128 v[188:191], v204 offset:3072
	ds_read_b128 v[192:195], v204 offset:4096
	ds_read_b128 v[206:209], v204 offset:5120
	ds_read_b128 v[210:213], v204 offset:6144
	ds_read_b128 v[214:217], v204 offset:7168
	global_load_lds_dwordx4 v176, s[70:71]
	s_add_i32 m0, s33, 0xe000
	s_nop 0
	global_load_lds_dwordx4 v178, s[70:71]
	s_add_u32 s72, s70, 0xffe00080
	s_addc_u32 s73, s71, -1
	s_cmpk_eq_i32 s87, 0x7c
	s_cselect_b32 s75, s25, s73
	s_cselect_b32 s74, s63, s72
	s_cselect_b32 s73, s61, s86
	s_cselect_b32 s72, s84, s85
	s_add_i32 s88, s82, s1
	s_mov_b32 m0, s88
	s_waitcnt vmcnt(8)
	s_waitcnt lgkmcnt(0)
	s_setprio 1
	s_barrier
	v_mfma_f32_16x16x32_bf16 v[124:127], v[128:131], v[160:163], v[124:127]
	v_mfma_f32_16x16x32_bf16 v[120:123], v[136:139], v[160:163], v[120:123]
	v_mfma_f32_16x16x32_bf16 v[116:119], v[128:131], v[184:187], v[116:119]
	v_mfma_f32_16x16x32_bf16 v[108:111], v[136:139], v[184:187], v[108:111]
	v_mfma_f32_16x16x32_bf16 v[92:95], v[128:131], v[192:195], v[92:95]
	v_mfma_f32_16x16x32_bf16 v[88:91], v[136:139], v[192:195], v[88:91]
	v_mfma_f32_16x16x32_bf16 v[76:79], v[128:131], v[210:213], v[76:79]
	v_mfma_f32_16x16x32_bf16 v[72:75], v[136:139], v[210:213], v[72:75]
	v_mfma_f32_16x16x32_bf16 v[124:127], v[132:135], v[164:167], v[124:127]
	v_mfma_f32_16x16x32_bf16 v[120:123], v[140:143], v[164:167], v[120:123]
	v_mfma_f32_16x16x32_bf16 v[116:119], v[132:135], v[188:191], v[116:119]
	v_mfma_f32_16x16x32_bf16 v[108:111], v[140:143], v[188:191], v[108:111]
	v_mfma_f32_16x16x32_bf16 v[92:95], v[132:135], v[206:209], v[92:95]
	v_mfma_f32_16x16x32_bf16 v[88:91], v[140:143], v[206:209], v[88:91]
	v_mfma_f32_16x16x32_bf16 v[76:79], v[132:135], v[214:217], v[76:79]
	v_mfma_f32_16x16x32_bf16 v[72:75], v[140:143], v[214:217], v[72:75]
	v_mfma_f32_16x16x32_bf16 v[112:115], v[144:147], v[160:163], v[112:115]
	v_mfma_f32_16x16x32_bf16 v[104:107], v[152:155], v[160:163], v[104:107]
	v_mfma_f32_16x16x32_bf16 v[100:103], v[144:147], v[184:187], v[100:103]
	v_mfma_f32_16x16x32_bf16 v[96:99], v[152:155], v[184:187], v[96:99]
	v_mfma_f32_16x16x32_bf16 v[84:87], v[144:147], v[192:195], v[84:87]
	v_mfma_f32_16x16x32_bf16 v[80:83], v[152:155], v[192:195], v[80:83]
	v_mfma_f32_16x16x32_bf16 v[68:71], v[144:147], v[210:213], v[68:71]
	v_mfma_f32_16x16x32_bf16 v[64:67], v[152:155], v[210:213], v[64:67]
	v_mfma_f32_16x16x32_bf16 v[112:115], v[148:151], v[164:167], v[112:115]
	v_mfma_f32_16x16x32_bf16 v[104:107], v[156:159], v[164:167], v[104:107]
	v_mfma_f32_16x16x32_bf16 v[100:103], v[148:151], v[188:191], v[100:103]
	v_mfma_f32_16x16x32_bf16 v[96:99], v[156:159], v[188:191], v[96:99]
	v_mfma_f32_16x16x32_bf16 v[84:87], v[148:151], v[206:209], v[84:87]
	v_mfma_f32_16x16x32_bf16 v[80:83], v[156:159], v[206:209], v[80:83]
	v_mfma_f32_16x16x32_bf16 v[68:71], v[148:151], v[214:217], v[68:71]
	v_mfma_f32_16x16x32_bf16 v[64:67], v[156:159], v[214:217], v[64:67]
	s_barrier
	s_setprio 0
	ds_read_b128 v[160:163], v204 offset:16384
	ds_read_b128 v[164:167], v204 offset:17408
	ds_read_b128 v[184:187], v204 offset:18432
	ds_read_b128 v[188:191], v204 offset:19456
	ds_read_b128 v[192:195], v204 offset:20480
	ds_read_b128 v[206:209], v204 offset:21504
	ds_read_b128 v[210:213], v204 offset:22528
	ds_read_b128 v[214:217], v204 offset:23552
	global_load_lds_dwordx4 v170, s[72:73]
	s_add_i32 m0, s88, 0x2000
	s_add_u32 s88, s72, 0x200000
	s_addc_u32 s89, s73, 0
	s_add_i32 s94, s83, s1
	global_load_lds_dwordx4 v174, s[72:73]
	s_mov_b32 m0, s94
	s_nop 0
	global_load_lds_dwordx4 v170, s[88:89]
	s_add_i32 m0, s94, 0x2000
	s_nop 0
	global_load_lds_dwordx4 v174, s[88:89]
	s_mov_b32 m0, s33
	s_nop 0
	global_load_lds_dwordx4 v168, s[74:75]
	s_mov_b32 m0, s35
	s_nop 0
	global_load_lds_dwordx4 v172, s[74:75]
	s_waitcnt vmcnt(8)
	s_waitcnt lgkmcnt(0)
	s_setprio 1
	s_barrier
	v_mfma_f32_16x16x32_bf16 v[60:63], v[128:131], v[160:163], v[60:63]
	v_mfma_f32_16x16x32_bf16 v[56:59], v[136:139], v[160:163], v[56:59]
	v_mfma_f32_16x16x32_bf16 v[44:47], v[128:131], v[184:187], v[44:47]
	v_mfma_f32_16x16x32_bf16 v[40:43], v[136:139], v[184:187], v[40:43]
	v_mfma_f32_16x16x32_bf16 v[28:31], v[128:131], v[192:195], v[28:31]
	v_mfma_f32_16x16x32_bf16 v[24:27], v[136:139], v[192:195], v[24:27]
	v_mfma_f32_16x16x32_bf16 v[12:15], v[128:131], v[210:213], v[12:15]
	v_mfma_f32_16x16x32_bf16 v[8:11], v[136:139], v[210:213], v[8:11]
	v_mfma_f32_16x16x32_bf16 v[60:63], v[132:135], v[164:167], v[60:63]
	v_mfma_f32_16x16x32_bf16 v[56:59], v[140:143], v[164:167], v[56:59]
	v_mfma_f32_16x16x32_bf16 v[44:47], v[132:135], v[188:191], v[44:47]
	v_mfma_f32_16x16x32_bf16 v[40:43], v[140:143], v[188:191], v[40:43]
	v_mfma_f32_16x16x32_bf16 v[28:31], v[132:135], v[206:209], v[28:31]
	v_mfma_f32_16x16x32_bf16 v[24:27], v[140:143], v[206:209], v[24:27]
	v_mfma_f32_16x16x32_bf16 v[12:15], v[132:135], v[214:217], v[12:15]
	v_mfma_f32_16x16x32_bf16 v[8:11], v[140:143], v[214:217], v[8:11]
	v_mfma_f32_16x16x32_bf16 v[52:55], v[144:147], v[160:163], v[52:55]
	v_mfma_f32_16x16x32_bf16 v[48:51], v[152:155], v[160:163], v[48:51]
	v_mfma_f32_16x16x32_bf16 v[36:39], v[144:147], v[184:187], v[36:39]
	v_mfma_f32_16x16x32_bf16 v[32:35], v[152:155], v[184:187], v[32:35]
	v_mfma_f32_16x16x32_bf16 v[20:23], v[144:147], v[192:195], v[20:23]
	v_mfma_f32_16x16x32_bf16 v[16:19], v[152:155], v[192:195], v[16:19]
	v_mfma_f32_16x16x32_bf16 v[4:7], v[144:147], v[210:213], v[4:7]
	v_mfma_f32_16x16x32_bf16 v[0:3], v[152:155], v[210:213], v[0:3]
	v_mfma_f32_16x16x32_bf16 v[52:55], v[148:151], v[164:167], v[52:55]
	v_mfma_f32_16x16x32_bf16 v[48:51], v[156:159], v[164:167], v[48:51]
	v_mfma_f32_16x16x32_bf16 v[36:39], v[148:151], v[188:191], v[36:39]
	v_mfma_f32_16x16x32_bf16 v[32:35], v[156:159], v[188:191], v[32:35]
	v_mfma_f32_16x16x32_bf16 v[20:23], v[148:151], v[206:209], v[20:23]
	v_mfma_f32_16x16x32_bf16 v[16:19], v[156:159], v[206:209], v[16:19]
	v_mfma_f32_16x16x32_bf16 v[4:7], v[148:151], v[214:217], v[4:7]
	v_mfma_f32_16x16x32_bf16 v[0:3], v[156:159], v[214:217], v[0:3]
	s_barrier
; #define PG8_STAGE(bufoff, gbase, voff) do { _Pragma("unroll") for (int _i = 0; _i < 2; ++_i) \
;         __builtin_amdgcn_global_load_lds((const unsigned*)((const char*)(gbase) + (voff)[_i]), (PG8_LAS unsigned*)(lds + (bufoff) + ldsw + _i * 8192), 16, 0, 0); } while (0)
; #define PG8_LDA(dst, b, h) do { _Pragma("unroll") for (int m = 0; m < 4; ++m) _Pragma("unroll") for (int k = 0; k < 2; ++k) dst[m][k] = *(const PG8_LAS bf16x8*)(lds + PG8_SA(b, h) + aoff + m * 2048 + k * 1024); } while (0)
; #define PG8_LDB(dst, b, h) do { _Pragma("unroll") for (int n = 0; n < 2; ++n) _Pragma("unroll") for (int k = 0; k < 2; ++k) dst[n][k] = *(const PG8_LAS bf16x8*)(lds + PG8_SB(b, h) + boff + n * 2048 + k * 1024); } while (0)
; #define PG8_MMA(ai, bj, At, Bt) do { __builtin_amdgcn_s_setprio(1); _Pragma("unroll") for (int m = 0; m < 4; ++m) _Pragma("unroll") for (int n = 0; n < 2; ++n) _Pragma("unroll") for (int k = 0; k < 2; ++k) \
;         acc[ai][bj][m][n] = __builtin_amdgcn_mfma_f32_16x16x32_bf16(Bt[n][k], At[m][k], acc[ai][bj][m][n], 0, 0, 0); __builtin_amdgcn_s_setprio(0); } while (0)
; #define PG8_WAIT_V(n) asm volatile("s_waitcnt vmcnt(" #n ")" ::: "memory")
; #define PG8_WAIT_L(n) asm volatile("s_waitcnt lgkmcnt(" #n ")" ::: "memory")
; #define PG8_BAR __builtin_amdgcn_s_barrier()
; #define PG8_SCHED __builtin_amdgcn_sched_barrier(0)
; template <class Epi, class Sched, bool ALIGN_EPI = false, bool SP2 = false>
; __device__ __forceinline__ void gemm_phase(PG8_LAS unsigned char* lds, const Gemm g, const Sched& S, const Epi& E) {
;     ...
;             PG8_LDB(B0, 1, 0); PG8_LDB(B1, 1, 1); PG8_SCHED; PG8_LDA(At, 1, 0); PG8_STAGE(PG8_SA(0, 1), a2 + hstep, voffA);
;             PG8_WAIT_V(8); PG8_WAIT_L(0); PG8_BAR; PG8_MMA(0, 0, At, B0); PG8_MMA(0, 1, At, B1); PG8_BAR; PG8_SCHED;
;             PG8_LDA(At, 1, 1); PG8_STAGE(PG8_SB(1, 0), b3, voffB); PG8_STAGE(PG8_SB(1, 1), b3 + hstep, voffB); PG8_STAGE(PG8_SA(1, 0), a3, voffA);
;             PG8_WAIT_V(8); PG8_WAIT_L(0); PG8_BAR; PG8_MMA(1, 0, At, B0); PG8_MMA(1, 1, At, B1); PG8_BAR; PG8_SCHED;
;     ...
;         if constexpr (ALIGN_EPI) { if (wr == 0) PG8_BAR; }
	s_setprio 0
	ds_read_b128 v[128:131], v218
	ds_read_b128 v[132:135], v218 offset:1024
	ds_read_b128 v[136:139], v218 offset:2048
	ds_read_b128 v[140:143], v218 offset:3072
	ds_read_b128 v[144:147], v219
	ds_read_b128 v[148:151], v219 offset:1024
	ds_read_b128 v[152:155], v219 offset:2048
	ds_read_b128 v[156:159], v219 offset:3072
	ds_read_b128 v[160:163], v204 offset:32768
	ds_read_b128 v[164:167], v204 offset:33792
	ds_read_b128 v[184:187], v204 offset:34816
	ds_read_b128 v[188:191], v204 offset:35840
	ds_read_b128 v[192:195], v204 offset:36864
	ds_read_b128 v[206:209], v204 offset:37888
	ds_read_b128 v[210:213], v204 offset:38912
	ds_read_b128 v[214:217], v204 offset:39936
	s_add_u32 s98, s74, 0x200000
	s_addc_u32 s99, s75, 0
	s_mov_b32 m0, s69
	s_add_u32 s100, s74, 0x80
	s_addc_u32 s101, s75, 0
	global_load_lds_dwordx4 v168, s[98:99]
	s_mov_b32 m0, s76
	s_nop 0
	global_load_lds_dwordx4 v172, s[98:99]
	s_add_i32 s88, 0, 0x18000
	s_add_i32 s89, 0, 0x1c000
	s_add_u32 s98, s72, 0x80
	s_addc_u32 s99, s73, 0
	s_add_i32 s74, s88, s1
	s_mov_b32 m0, s74
	s_waitcnt vmcnt(8)
	s_waitcnt lgkmcnt(0)
	s_setprio 1
	s_barrier
	v_mfma_f32_16x16x32_bf16 v[124:127], v[128:131], v[160:163], v[124:127]
	v_mfma_f32_16x16x32_bf16 v[120:123], v[136:139], v[160:163], v[120:123]
	v_mfma_f32_16x16x32_bf16 v[116:119], v[128:131], v[184:187], v[116:119]
	v_mfma_f32_16x16x32_bf16 v[108:111], v[136:139], v[184:187], v[108:111]
	v_mfma_f32_16x16x32_bf16 v[92:95], v[128:131], v[192:195], v[92:95]
	v_mfma_f32_16x16x32_bf16 v[88:91], v[136:139], v[192:195], v[88:91]
	v_mfma_f32_16x16x32_bf16 v[76:79], v[128:131], v[210:213], v[76:79]
	v_mfma_f32_16x16x32_bf16 v[72:75], v[136:139], v[210:213], v[72:75]
	v_mfma_f32_16x16x32_bf16 v[124:127], v[132:135], v[164:167], v[124:127]
	v_mfma_f32_16x16x32_bf16 v[120:123], v[140:143], v[164:167], v[120:123]
	v_mfma_f32_16x16x32_bf16 v[116:119], v[132:135], v[188:191], v[116:119]
	v_mfma_f32_16x16x32_bf16 v[108:111], v[140:143], v[188:191], v[108:111]
	v_mfma_f32_16x16x32_bf16 v[92:95], v[132:135], v[206:209], v[92:95]
	v_mfma_f32_16x16x32_bf16 v[88:91], v[140:143], v[206:209], v[88:91]
	v_mfma_f32_16x16x32_bf16 v[76:79], v[132:135], v[214:217], v[76:79]
	v_mfma_f32_16x16x32_bf16 v[72:75], v[140:143], v[214:217], v[72:75]
	v_mfma_f32_16x16x32_bf16 v[112:115], v[144:147], v[160:163], v[112:115]
	v_mfma_f32_16x16x32_bf16 v[104:107], v[152:155], v[160:163], v[104:107]
	v_mfma_f32_16x16x32_bf16 v[100:103], v[144:147], v[184:187], v[100:103]
	v_mfma_f32_16x16x32_bf16 v[96:99], v[152:155], v[184:187], v[96:99]
	v_mfma_f32_16x16x32_bf16 v[84:87], v[144:147], v[192:195], v[84:87]
	v_mfma_f32_16x16x32_bf16 v[80:83], v[152:155], v[192:195], v[80:83]
	v_mfma_f32_16x16x32_bf16 v[68:71], v[144:147], v[210:213], v[68:71]
	v_mfma_f32_16x16x32_bf16 v[64:67], v[152:155], v[210:213], v[64:67]
	v_mfma_f32_16x16x32_bf16 v[112:115], v[148:151], v[164:167], v[112:115]
	v_mfma_f32_16x16x32_bf16 v[104:107], v[156:159], v[164:167], v[104:107]
	v_mfma_f32_16x16x32_bf16 v[100:103], v[148:151], v[188:191], v[100:103]
	v_mfma_f32_16x16x32_bf16 v[96:99], v[156:159], v[188:191], v[96:99]
	v_mfma_f32_16x16x32_bf16 v[84:87], v[148:151], v[206:209], v[84:87]
	v_mfma_f32_16x16x32_bf16 v[80:83], v[156:159], v[206:209], v[80:83]
	v_mfma_f32_16x16x32_bf16 v[68:71], v[148:151], v[214:217], v[68:71]
	v_mfma_f32_16x16x32_bf16 v[64:67], v[156:159], v[214:217], v[64:67]
	s_barrier
	s_setprio 0
	ds_read_b128 v[160:163], v204 offset:49152
	ds_read_b128 v[164:167], v204 offset:50176
	ds_read_b128 v[184:187], v204 offset:51200
	ds_read_b128 v[188:191], v204 offset:52224
	ds_read_b128 v[192:195], v204 offset:53248
	ds_read_b128 v[206:209], v204 offset:54272
	ds_read_b128 v[210:213], v204 offset:55296
	ds_read_b128 v[214:217], v204 offset:56320
	global_load_lds_dwordx4 v170, s[98:99]
	s_add_i32 m0, s74, 0x2000
	s_add_u32 s72, s72, 0x200080
	s_addc_u32 s73, s73, 0
	s_add_i32 s74, s89, s1
	global_load_lds_dwordx4 v174, s[98:99]
	s_mov_b32 m0, s74
	s_nop 0
	global_load_lds_dwordx4 v170, s[72:73]
	s_add_i32 m0, s74, 0x2000
	s_nop 0
	global_load_lds_dwordx4 v174, s[72:73]
	s_mov_b32 m0, s78
	s_nop 0
	global_load_lds_dwordx4 v168, s[100:101]
	s_mov_b32 m0, s79
	s_nop 0
	global_load_lds_dwordx4 v172, s[100:101]
	s_add_i32 s87, s87, 2
	s_add_u32 s70, s70, 0x100
	s_addc_u32 s71, s71, 0
	s_add_u32 s85, s85, 0x100
	s_addc_u32 s86, s86, 0
	s_cmpk_gt_u32 s87, 0x7d
	s_waitcnt vmcnt(8)
	s_waitcnt lgkmcnt(0)
	s_setprio 1
	s_barrier
	v_mfma_f32_16x16x32_bf16 v[60:63], v[128:131], v[160:163], v[60:63]
	v_mfma_f32_16x16x32_bf16 v[56:59], v[136:139], v[160:163], v[56:59]
	v_mfma_f32_16x16x32_bf16 v[44:47], v[128:131], v[184:187], v[44:47]
	v_mfma_f32_16x16x32_bf16 v[40:43], v[136:139], v[184:187], v[40:43]
	v_mfma_f32_16x16x32_bf16 v[28:31], v[128:131], v[192:195], v[28:31]
	v_mfma_f32_16x16x32_bf16 v[24:27], v[136:139], v[192:195], v[24:27]
	v_mfma_f32_16x16x32_bf16 v[12:15], v[128:131], v[210:213], v[12:15]
	v_mfma_f32_16x16x32_bf16 v[8:11], v[136:139], v[210:213], v[8:11]
	v_mfma_f32_16x16x32_bf16 v[60:63], v[132:135], v[164:167], v[60:63]
	v_mfma_f32_16x16x32_bf16 v[56:59], v[140:143], v[164:167], v[56:59]
	v_mfma_f32_16x16x32_bf16 v[44:47], v[132:135], v[188:191], v[44:47]
	v_mfma_f32_16x16x32_bf16 v[40:43], v[140:143], v[188:191], v[40:43]
	v_mfma_f32_16x16x32_bf16 v[28:31], v[132:135], v[206:209], v[28:31]
	v_mfma_f32_16x16x32_bf16 v[24:27], v[140:143], v[206:209], v[24:27]
	v_mfma_f32_16x16x32_bf16 v[12:15], v[132:135], v[214:217], v[12:15]
	v_mfma_f32_16x16x32_bf16 v[8:11], v[140:143], v[214:217], v[8:11]
	v_mfma_f32_16x16x32_bf16 v[52:55], v[144:147], v[160:163], v[52:55]
	v_mfma_f32_16x16x32_bf16 v[48:51], v[152:155], v[160:163], v[48:51]
	v_mfma_f32_16x16x32_bf16 v[36:39], v[144:147], v[184:187], v[36:39]
	v_mfma_f32_16x16x32_bf16 v[32:35], v[152:155], v[184:187], v[32:35]
	v_mfma_f32_16x16x32_bf16 v[20:23], v[144:147], v[192:195], v[20:23]
	v_mfma_f32_16x16x32_bf16 v[16:19], v[152:155], v[192:195], v[16:19]
	v_mfma_f32_16x16x32_bf16 v[4:7], v[144:147], v[210:213], v[4:7]
	v_mfma_f32_16x16x32_bf16 v[0:3], v[152:155], v[210:213], v[0:3]
	v_mfma_f32_16x16x32_bf16 v[52:55], v[148:151], v[164:167], v[52:55]
	v_mfma_f32_16x16x32_bf16 v[48:51], v[156:159], v[164:167], v[48:51]
	v_mfma_f32_16x16x32_bf16 v[36:39], v[148:151], v[188:191], v[36:39]
	v_mfma_f32_16x16x32_bf16 v[32:35], v[156:159], v[188:191], v[32:35]
	v_mfma_f32_16x16x32_bf16 v[20:23], v[148:151], v[206:209], v[20:23]
	v_mfma_f32_16x16x32_bf16 v[16:19], v[156:159], v[206:209], v[16:19]
	v_mfma_f32_16x16x32_bf16 v[4:7], v[148:151], v[214:217], v[4:7]
	v_mfma_f32_16x16x32_bf16 v[0:3], v[156:159], v[214:217], v[0:3]
	s_barrier
	s_setprio 0
	s_cbranch_scc0 .LBB0_452
	s_and_b64 vcc, exec, s[36:37]
	s_cbranch_vccz .LBB0_455
	s_barrier

; #define PG8_STAGE(bufoff, gbase, voff) do { _Pragma("unroll") for (int _i = 0; _i < 2; ++_i) \
;         __builtin_amdgcn_global_load_lds((const unsigned*)((const char*)(gbase) + (voff)[_i]), (PG8_LAS unsigned*)(lds + (bufoff) + ldsw + _i * 8192), 16, 0, 0); } while (0)
; #define PG8_LDA(dst, b, h) do { _Pragma("unroll") for (int m = 0; m < 4; ++m) _Pragma("unroll") for (int k = 0; k < 2; ++k) dst[m][k] = *(const PG8_LAS bf16x8*)(lds + PG8_SA(b, h) + aoff + m * 2048 + k * 1024); } while (0)
; #define PG8_LDB(dst, b, h) do { _Pragma("unroll") for (int n = 0; n < 2; ++n) _Pragma("unroll") for (int k = 0; k < 2; ++k) dst[n][k] = *(const PG8_LAS bf16x8*)(lds + PG8_SB(b, h) + boff + n * 2048 + k * 1024); } while (0)
; #define PG8_MMA(ai, bj, At, Bt) do { __builtin_amdgcn_s_setprio(1); _Pragma("unroll") for (int m = 0; m < 4; ++m) _Pragma("unroll") for (int n = 0; n < 2; ++n) _Pragma("unroll") for (int k = 0; k < 2; ++k) \
;         acc[ai][bj][m][n] = __builtin_amdgcn_mfma_f32_16x16x32_bf16(Bt[n][k], At[m][k], acc[ai][bj][m][n], 0, 0, 0); __builtin_amdgcn_s_setprio(0); } while (0)
; #define PG8_WAIT_V(n) asm volatile("s_waitcnt vmcnt(" #n ")" ::: "memory")
; #define PG8_WAIT_L(n) asm volatile("s_waitcnt lgkmcnt(" #n ")" ::: "memory")
; #define PG8_BAR __builtin_amdgcn_s_barrier()
; template <class Epi, class Sched, bool ALIGN_EPI = false, bool SP2 = false>
; __device__ __forceinline__ void gemm_phase(PG8_LAS unsigned char* lds, const Gemm g, const Sched& S, const Epi& E) {
;     ...
;             const char* a1 = cA + (size_t)(t + 1) * kstep;
;             const char* a2 = last ? nA : cA + (size_t)(t + 2) * kstep; const char* b2 = last ? nB : cB + (size_t)(t + 2) * kstep;
;             const char* a3 = a2 + kstep; const char* b3 = b2 + kstep;
;             if (last && has_next) S.a_ready(nxt);
;             if constexpr (SP2) {
;             PG8_LDB(B0, 0, 0); PG8_LDB(B1, 0, 1); PG8_SCHED; PG8_LDA(At, 0, 0); PG8_STAGE(PG8_SA(1, 1), a1 + hstep, voffA);
;             PG8_WAIT_V(8); PG8_WAIT_L(0); PG8_BAR; PG8_MMA(0, 0, At, B0); PG8_MMA(0, 1, At, B1); PG8_BAR; PG8_SCHED;
;             PG8_LDA(At, 0, 1); PG8_STAGE(PG8_SB(0, 0), b2, voffB); PG8_STAGE(PG8_SB(0, 1), b2 + hstep, voffB); PG8_STAGE(PG8_SA(0, 0), a2, voffA);
;             PG8_WAIT_V(8); PG8_WAIT_L(0); PG8_BAR; PG8_MMA(1, 0, At, B0); PG8_MMA(1, 1, At, B1); PG8_BAR; PG8_SCHED;
.LBB0_528:
	ds_read_b128 v[152:155], v149
	ds_read_b128 v[156:159], v149 offset:1024
	ds_read_b128 v[160:163], v149 offset:2048
	ds_read_b128 v[164:167], v149 offset:3072
	ds_read_b128 v[168:171], v150
	ds_read_b128 v[172:175], v150 offset:1024
	ds_read_b128 v[176:179], v150 offset:2048
	ds_read_b128 v[180:183], v150 offset:3072
	s_add_i32 m0, s14, 0xc000
	ds_read_b128 v[184:187], v151
	ds_read_b128 v[188:191], v151 offset:1024
	ds_read_b128 v[192:195], v151 offset:2048
	ds_read_b128 v[200:203], v151 offset:3072
	ds_read_b128 v[204:207], v151 offset:4096
	ds_read_b128 v[208:211], v151 offset:5120
	ds_read_b128 v[212:215], v151 offset:6144
	ds_read_b128 v[216:219], v151 offset:7168
	global_load_lds_dwordx4 v136, s[70:71]
	s_add_i32 m0, s14, 0xe000
	s_nop 0
	global_load_lds_dwordx4 v138, s[70:71]
	s_add_u32 s72, s70, 0xfff80080
	s_addc_u32 s73, s71, -1
	s_cmp_eq_u32 s86, 28
	s_cselect_b32 s75, s25, s73
	s_cselect_b32 s74, s63, s72
	s_cselect_b32 s73, s61, s85
	s_cselect_b32 s72, s83, s84
	s_add_i32 s87, s80, s1
	s_mov_b32 m0, s87
	s_waitcnt vmcnt(8)
	s_waitcnt lgkmcnt(0)
	s_setprio 1
	s_barrier
	v_mfma_f32_16x16x32_bf16 v[124:127], v[152:155], v[184:187], v[124:127]
	v_mfma_f32_16x16x32_bf16 v[120:123], v[160:163], v[184:187], v[120:123]
	v_mfma_f32_16x16x32_bf16 v[108:111], v[152:155], v[192:195], v[108:111]
	v_mfma_f32_16x16x32_bf16 v[104:107], v[160:163], v[192:195], v[104:107]
	v_mfma_f32_16x16x32_bf16 v[92:95], v[152:155], v[204:207], v[92:95]
	v_mfma_f32_16x16x32_bf16 v[88:91], v[160:163], v[204:207], v[88:91]
	v_mfma_f32_16x16x32_bf16 v[76:79], v[152:155], v[212:215], v[76:79]
	v_mfma_f32_16x16x32_bf16 v[72:75], v[160:163], v[212:215], v[72:75]
	v_mfma_f32_16x16x32_bf16 v[124:127], v[156:159], v[188:191], v[124:127]
	v_mfma_f32_16x16x32_bf16 v[120:123], v[164:167], v[188:191], v[120:123]
	v_mfma_f32_16x16x32_bf16 v[108:111], v[156:159], v[200:203], v[108:111]
	v_mfma_f32_16x16x32_bf16 v[104:107], v[164:167], v[200:203], v[104:107]
	v_mfma_f32_16x16x32_bf16 v[92:95], v[156:159], v[208:211], v[92:95]
	v_mfma_f32_16x16x32_bf16 v[88:91], v[164:167], v[208:211], v[88:91]
	v_mfma_f32_16x16x32_bf16 v[76:79], v[156:159], v[216:219], v[76:79]
	v_mfma_f32_16x16x32_bf16 v[72:75], v[164:167], v[216:219], v[72:75]
	v_mfma_f32_16x16x32_bf16 v[116:119], v[168:171], v[184:187], v[116:119]
	v_mfma_f32_16x16x32_bf16 v[112:115], v[176:179], v[184:187], v[112:115]
	v_mfma_f32_16x16x32_bf16 v[100:103], v[168:171], v[192:195], v[100:103]
	v_mfma_f32_16x16x32_bf16 v[96:99], v[176:179], v[192:195], v[96:99]
	v_mfma_f32_16x16x32_bf16 v[84:87], v[168:171], v[204:207], v[84:87]
	v_mfma_f32_16x16x32_bf16 v[80:83], v[176:179], v[204:207], v[80:83]
	v_mfma_f32_16x16x32_bf16 v[68:71], v[168:171], v[212:215], v[68:71]
	v_mfma_f32_16x16x32_bf16 v[64:67], v[176:179], v[212:215], v[64:67]
	v_mfma_f32_16x16x32_bf16 v[116:119], v[172:175], v[188:191], v[116:119]
	v_mfma_f32_16x16x32_bf16 v[112:115], v[180:183], v[188:191], v[112:115]
	v_mfma_f32_16x16x32_bf16 v[100:103], v[172:175], v[200:203], v[100:103]
	v_mfma_f32_16x16x32_bf16 v[96:99], v[180:183], v[200:203], v[96:99]
	v_mfma_f32_16x16x32_bf16 v[84:87], v[172:175], v[208:211], v[84:87]
	v_mfma_f32_16x16x32_bf16 v[80:83], v[180:183], v[208:211], v[80:83]
	v_mfma_f32_16x16x32_bf16 v[68:71], v[172:175], v[216:219], v[68:71]
	v_mfma_f32_16x16x32_bf16 v[64:67], v[180:183], v[216:219], v[64:67]
	s_barrier
	s_setprio 0
	ds_read_b128 v[184:187], v151 offset:16384
	ds_read_b128 v[188:191], v151 offset:17408
	ds_read_b128 v[192:195], v151 offset:18432
	ds_read_b128 v[200:203], v151 offset:19456
	ds_read_b128 v[204:207], v151 offset:20480
	ds_read_b128 v[208:211], v151 offset:21504
	ds_read_b128 v[212:215], v151 offset:22528
	ds_read_b128 v[216:219], v151 offset:23552
	global_load_lds_dwordx4 v130, s[72:73]
	s_add_i32 m0, s87, 0x2000
	s_add_u32 s88, s72, 0x80000
	s_addc_u32 s89, s73, 0
	s_add_i32 s87, s81, s1
	global_load_lds_dwordx4 v134, s[72:73]
	s_mov_b32 m0, s87
	s_nop 0
	global_load_lds_dwordx4 v130, s[88:89]
	s_add_i32 m0, s87, 0x2000
	s_nop 0
	global_load_lds_dwordx4 v134, s[88:89]
	s_mov_b32 m0, s14
	s_nop 0
	global_load_lds_dwordx4 v128, s[74:75]
	s_mov_b32 m0, s15
	s_nop 0
	global_load_lds_dwordx4 v132, s[74:75]
	s_waitcnt vmcnt(8)
	s_waitcnt lgkmcnt(0)
	s_setprio 1
	s_barrier
	v_mfma_f32_16x16x32_bf16 v[60:63], v[152:155], v[184:187], v[60:63]
	v_mfma_f32_16x16x32_bf16 v[56:59], v[160:163], v[184:187], v[56:59]
	v_mfma_f32_16x16x32_bf16 v[44:47], v[152:155], v[192:195], v[44:47]
	v_mfma_f32_16x16x32_bf16 v[40:43], v[160:163], v[192:195], v[40:43]
	v_mfma_f32_16x16x32_bf16 v[28:31], v[152:155], v[204:207], v[28:31]
	v_mfma_f32_16x16x32_bf16 v[24:27], v[160:163], v[204:207], v[24:27]
	v_mfma_f32_16x16x32_bf16 v[12:15], v[152:155], v[212:215], v[12:15]
	v_mfma_f32_16x16x32_bf16 v[8:11], v[160:163], v[212:215], v[8:11]
	v_mfma_f32_16x16x32_bf16 v[60:63], v[156:159], v[188:191], v[60:63]
	v_mfma_f32_16x16x32_bf16 v[56:59], v[164:167], v[188:191], v[56:59]
	v_mfma_f32_16x16x32_bf16 v[44:47], v[156:159], v[200:203], v[44:47]
	v_mfma_f32_16x16x32_bf16 v[40:43], v[164:167], v[200:203], v[40:43]
	v_mfma_f32_16x16x32_bf16 v[28:31], v[156:159], v[208:211], v[28:31]
	v_mfma_f32_16x16x32_bf16 v[24:27], v[164:167], v[208:211], v[24:27]
	v_mfma_f32_16x16x32_bf16 v[12:15], v[156:159], v[216:219], v[12:15]
	v_mfma_f32_16x16x32_bf16 v[8:11], v[164:167], v[216:219], v[8:11]
	v_mfma_f32_16x16x32_bf16 v[52:55], v[168:171], v[184:187], v[52:55]
	v_mfma_f32_16x16x32_bf16 v[48:51], v[176:179], v[184:187], v[48:51]
	v_mfma_f32_16x16x32_bf16 v[36:39], v[168:171], v[192:195], v[36:39]
	v_mfma_f32_16x16x32_bf16 v[32:35], v[176:179], v[192:195], v[32:35]
	v_mfma_f32_16x16x32_bf16 v[20:23], v[168:171], v[204:207], v[20:23]
	v_mfma_f32_16x16x32_bf16 v[16:19], v[176:179], v[204:207], v[16:19]
	v_mfma_f32_16x16x32_bf16 v[4:7], v[168:171], v[212:215], v[4:7]
	v_mfma_f32_16x16x32_bf16 v[0:3], v[176:179], v[212:215], v[0:3]
	v_mfma_f32_16x16x32_bf16 v[52:55], v[172:175], v[188:191], v[52:55]
	v_mfma_f32_16x16x32_bf16 v[48:51], v[180:183], v[188:191], v[48:51]
	v_mfma_f32_16x16x32_bf16 v[36:39], v[172:175], v[200:203], v[36:39]
	v_mfma_f32_16x16x32_bf16 v[32:35], v[180:183], v[200:203], v[32:35]
	v_mfma_f32_16x16x32_bf16 v[20:23], v[172:175], v[208:211], v[20:23]
	v_mfma_f32_16x16x32_bf16 v[16:19], v[180:183], v[208:211], v[16:19]
	v_mfma_f32_16x16x32_bf16 v[4:7], v[172:175], v[216:219], v[4:7]
	v_mfma_f32_16x16x32_bf16 v[0:3], v[180:183], v[216:219], v[0:3]
	s_barrier
; #define PG8_STAGE(bufoff, gbase, voff) do { _Pragma("unroll") for (int _i = 0; _i < 2; ++_i) \
;         __builtin_amdgcn_global_load_lds((const unsigned*)((const char*)(gbase) + (voff)[_i]), (PG8_LAS unsigned*)(lds + (bufoff) + ldsw + _i * 8192), 16, 0, 0); } while (0)
; #define PG8_LDA(dst, b, h) do { _Pragma("unroll") for (int m = 0; m < 4; ++m) _Pragma("unroll") for (int k = 0; k < 2; ++k) dst[m][k] = *(const PG8_LAS bf16x8*)(lds + PG8_SA(b, h) + aoff + m * 2048 + k * 1024); } while (0)
; #define PG8_LDB(dst, b, h) do { _Pragma("unroll") for (int n = 0; n < 2; ++n) _Pragma("unroll") for (int k = 0; k < 2; ++k) dst[n][k] = *(const PG8_LAS bf16x8*)(lds + PG8_SB(b, h) + boff + n * 2048 + k * 1024); } while (0)
; #define PG8_MMA(ai, bj, At, Bt) do { __builtin_amdgcn_s_setprio(1); _Pragma("unroll") for (int m = 0; m < 4; ++m) _Pragma("unroll") for (int n = 0; n < 2; ++n) _Pragma("unroll") for (int k = 0; k < 2; ++k) \
;         acc[ai][bj][m][n] = __builtin_amdgcn_mfma_f32_16x16x32_bf16(Bt[n][k], At[m][k], acc[ai][bj][m][n], 0, 0, 0); __builtin_amdgcn_s_setprio(0); } while (0)
; #define PG8_WAIT_V(n) asm volatile("s_waitcnt vmcnt(" #n ")" ::: "memory")
; #define PG8_WAIT_L(n) asm volatile("s_waitcnt lgkmcnt(" #n ")" ::: "memory")
; #define PG8_BAR __builtin_amdgcn_s_barrier()
; #define PG8_SCHED __builtin_amdgcn_sched_barrier(0)
; template <class Epi, class Sched, bool ALIGN_EPI = false, bool SP2 = false>
; __device__ __forceinline__ void gemm_phase(PG8_LAS unsigned char* lds, const Gemm g, const Sched& S, const Epi& E) {
;     ...
;             PG8_LDB(B0, 1, 0); PG8_LDB(B1, 1, 1); PG8_SCHED; PG8_LDA(At, 1, 0); PG8_STAGE(PG8_SA(0, 1), a2 + hstep, voffA);
;             PG8_WAIT_V(8); PG8_WAIT_L(0); PG8_BAR; PG8_MMA(0, 0, At, B0); PG8_MMA(0, 1, At, B1); PG8_BAR; PG8_SCHED;
;             PG8_LDA(At, 1, 1); PG8_STAGE(PG8_SB(1, 0), b3, voffB); PG8_STAGE(PG8_SB(1, 1), b3 + hstep, voffB); PG8_STAGE(PG8_SA(1, 0), a3, voffA);
;             PG8_WAIT_V(8); PG8_WAIT_L(0); PG8_BAR; PG8_MMA(1, 0, At, B0); PG8_MMA(1, 1, At, B1); PG8_BAR; PG8_SCHED;
;     ...
;         if constexpr (ALIGN_EPI) { if (wr == 0) PG8_BAR; }
	s_setprio 0
	ds_read_b128 v[152:155], v196
	ds_read_b128 v[156:159], v196 offset:1024
	ds_read_b128 v[160:163], v196 offset:2048
	ds_read_b128 v[164:167], v196 offset:3072
	ds_read_b128 v[168:171], v197
	ds_read_b128 v[172:175], v197 offset:1024
	ds_read_b128 v[176:179], v197 offset:2048
	ds_read_b128 v[180:183], v197 offset:3072
	ds_read_b128 v[184:187], v151 offset:32768
	ds_read_b128 v[188:191], v151 offset:33792
	ds_read_b128 v[192:195], v151 offset:34816
	ds_read_b128 v[200:203], v151 offset:35840
	ds_read_b128 v[204:207], v151 offset:36864
	ds_read_b128 v[208:211], v151 offset:37888
	ds_read_b128 v[212:215], v151 offset:38912
	ds_read_b128 v[216:219], v151 offset:39936
	s_add_u32 s98, s74, 0x80000
	s_addc_u32 s99, s75, 0
	s_mov_b32 m0, s33
	s_add_u32 s100, s74, 0x80
	s_addc_u32 s101, s75, 0
	global_load_lds_dwordx4 v128, s[98:99]
	s_mov_b32 m0, s35
	s_nop 0
	global_load_lds_dwordx4 v132, s[98:99]
	s_add_i32 s87, 0, 0x18000
	s_add_i32 s88, 0, 0x1c000
	s_add_u32 s98, s72, 0x80
	s_addc_u32 s99, s73, 0
	s_add_i32 s74, s87, s1
	s_mov_b32 m0, s74
	s_waitcnt vmcnt(8)
	s_waitcnt lgkmcnt(0)
	s_setprio 1
	s_barrier
	v_mfma_f32_16x16x32_bf16 v[124:127], v[152:155], v[184:187], v[124:127]
	v_mfma_f32_16x16x32_bf16 v[120:123], v[160:163], v[184:187], v[120:123]
	v_mfma_f32_16x16x32_bf16 v[108:111], v[152:155], v[192:195], v[108:111]
	v_mfma_f32_16x16x32_bf16 v[104:107], v[160:163], v[192:195], v[104:107]
	v_mfma_f32_16x16x32_bf16 v[92:95], v[152:155], v[204:207], v[92:95]
	v_mfma_f32_16x16x32_bf16 v[88:91], v[160:163], v[204:207], v[88:91]
	v_mfma_f32_16x16x32_bf16 v[76:79], v[152:155], v[212:215], v[76:79]
	v_mfma_f32_16x16x32_bf16 v[72:75], v[160:163], v[212:215], v[72:75]
	v_mfma_f32_16x16x32_bf16 v[124:127], v[156:159], v[188:191], v[124:127]
	v_mfma_f32_16x16x32_bf16 v[120:123], v[164:167], v[188:191], v[120:123]
	v_mfma_f32_16x16x32_bf16 v[108:111], v[156:159], v[200:203], v[108:111]
	v_mfma_f32_16x16x32_bf16 v[104:107], v[164:167], v[200:203], v[104:107]
	v_mfma_f32_16x16x32_bf16 v[92:95], v[156:159], v[208:211], v[92:95]
	v_mfma_f32_16x16x32_bf16 v[88:91], v[164:167], v[208:211], v[88:91]
	v_mfma_f32_16x16x32_bf16 v[76:79], v[156:159], v[216:219], v[76:79]
	v_mfma_f32_16x16x32_bf16 v[72:75], v[164:167], v[216:219], v[72:75]
	v_mfma_f32_16x16x32_bf16 v[116:119], v[168:171], v[184:187], v[116:119]
	v_mfma_f32_16x16x32_bf16 v[112:115], v[176:179], v[184:187], v[112:115]
	v_mfma_f32_16x16x32_bf16 v[100:103], v[168:171], v[192:195], v[100:103]
	v_mfma_f32_16x16x32_bf16 v[96:99], v[176:179], v[192:195], v[96:99]
	v_mfma_f32_16x16x32_bf16 v[84:87], v[168:171], v[204:207], v[84:87]
	v_mfma_f32_16x16x32_bf16 v[80:83], v[176:179], v[204:207], v[80:83]
	v_mfma_f32_16x16x32_bf16 v[68:71], v[168:171], v[212:215], v[68:71]
	v_mfma_f32_16x16x32_bf16 v[64:67], v[176:179], v[212:215], v[64:67]
	v_mfma_f32_16x16x32_bf16 v[116:119], v[172:175], v[188:191], v[116:119]
	v_mfma_f32_16x16x32_bf16 v[112:115], v[180:183], v[188:191], v[112:115]
	v_mfma_f32_16x16x32_bf16 v[100:103], v[172:175], v[200:203], v[100:103]
	v_mfma_f32_16x16x32_bf16 v[96:99], v[180:183], v[200:203], v[96:99]
	v_mfma_f32_16x16x32_bf16 v[84:87], v[172:175], v[208:211], v[84:87]
	v_mfma_f32_16x16x32_bf16 v[80:83], v[180:183], v[208:211], v[80:83]
	v_mfma_f32_16x16x32_bf16 v[68:71], v[172:175], v[216:219], v[68:71]
	v_mfma_f32_16x16x32_bf16 v[64:67], v[180:183], v[216:219], v[64:67]
	s_barrier
	s_setprio 0
	ds_read_b128 v[184:187], v151 offset:49152
	ds_read_b128 v[188:191], v151 offset:50176
	ds_read_b128 v[192:195], v151 offset:51200
	ds_read_b128 v[200:203], v151 offset:52224
	ds_read_b128 v[204:207], v151 offset:53248
	ds_read_b128 v[208:211], v151 offset:54272
	ds_read_b128 v[212:215], v151 offset:55296
	ds_read_b128 v[216:219], v151 offset:56320
	global_load_lds_dwordx4 v130, s[98:99]
	s_add_i32 m0, s74, 0x2000
	s_add_u32 s72, s72, 0x80080
	s_addc_u32 s73, s73, 0
	s_add_i32 s74, s88, s1
	global_load_lds_dwordx4 v134, s[98:99]
	s_mov_b32 m0, s74
	s_nop 0
	global_load_lds_dwordx4 v130, s[72:73]
	s_add_i32 m0, s74, 0x2000
	s_nop 0
	global_load_lds_dwordx4 v134, s[72:73]
	s_mov_b32 m0, s76
	s_nop 0
	global_load_lds_dwordx4 v128, s[100:101]
	s_mov_b32 m0, s77
	s_nop 0
	global_load_lds_dwordx4 v132, s[100:101]
	s_add_i32 s86, s86, 2
	s_add_u32 s70, s70, 0x100
	s_addc_u32 s71, s71, 0
	s_add_u32 s84, s84, 0x100
	s_addc_u32 s85, s85, 0
	s_cmp_gt_u32 s86, 29
	s_waitcnt vmcnt(8)
	s_waitcnt lgkmcnt(0)
	s_setprio 1
	s_barrier
	v_mfma_f32_16x16x32_bf16 v[60:63], v[152:155], v[184:187], v[60:63]
	v_mfma_f32_16x16x32_bf16 v[56:59], v[160:163], v[184:187], v[56:59]
	v_mfma_f32_16x16x32_bf16 v[44:47], v[152:155], v[192:195], v[44:47]
	v_mfma_f32_16x16x32_bf16 v[40:43], v[160:163], v[192:195], v[40:43]
	v_mfma_f32_16x16x32_bf16 v[28:31], v[152:155], v[204:207], v[28:31]
	v_mfma_f32_16x16x32_bf16 v[24:27], v[160:163], v[204:207], v[24:27]
	v_mfma_f32_16x16x32_bf16 v[12:15], v[152:155], v[212:215], v[12:15]
	v_mfma_f32_16x16x32_bf16 v[8:11], v[160:163], v[212:215], v[8:11]
	v_mfma_f32_16x16x32_bf16 v[60:63], v[156:159], v[188:191], v[60:63]
	v_mfma_f32_16x16x32_bf16 v[56:59], v[164:167], v[188:191], v[56:59]
	v_mfma_f32_16x16x32_bf16 v[44:47], v[156:159], v[200:203], v[44:47]
	v_mfma_f32_16x16x32_bf16 v[40:43], v[164:167], v[200:203], v[40:43]
	v_mfma_f32_16x16x32_bf16 v[28:31], v[156:159], v[208:211], v[28:31]
	v_mfma_f32_16x16x32_bf16 v[24:27], v[164:167], v[208:211], v[24:27]
	v_mfma_f32_16x16x32_bf16 v[12:15], v[156:159], v[216:219], v[12:15]
	v_mfma_f32_16x16x32_bf16 v[8:11], v[164:167], v[216:219], v[8:11]
	v_mfma_f32_16x16x32_bf16 v[52:55], v[168:171], v[184:187], v[52:55]
	v_mfma_f32_16x16x32_bf16 v[48:51], v[176:179], v[184:187], v[48:51]
	v_mfma_f32_16x16x32_bf16 v[36:39], v[168:171], v[192:195], v[36:39]
	v_mfma_f32_16x16x32_bf16 v[32:35], v[176:179], v[192:195], v[32:35]
	v_mfma_f32_16x16x32_bf16 v[20:23], v[168:171], v[204:207], v[20:23]
	v_mfma_f32_16x16x32_bf16 v[16:19], v[176:179], v[204:207], v[16:19]
	v_mfma_f32_16x16x32_bf16 v[4:7], v[168:171], v[212:215], v[4:7]
	v_mfma_f32_16x16x32_bf16 v[0:3], v[176:179], v[212:215], v[0:3]
	v_mfma_f32_16x16x32_bf16 v[52:55], v[172:175], v[188:191], v[52:55]
	v_mfma_f32_16x16x32_bf16 v[48:51], v[180:183], v[188:191], v[48:51]
	v_mfma_f32_16x16x32_bf16 v[36:39], v[172:175], v[200:203], v[36:39]
	v_mfma_f32_16x16x32_bf16 v[32:35], v[180:183], v[200:203], v[32:35]
	v_mfma_f32_16x16x32_bf16 v[20:23], v[172:175], v[208:211], v[20:23]
	v_mfma_f32_16x16x32_bf16 v[16:19], v[180:183], v[208:211], v[16:19]
	v_mfma_f32_16x16x32_bf16 v[4:7], v[172:175], v[216:219], v[4:7]
	v_mfma_f32_16x16x32_bf16 v[0:3], v[180:183], v[216:219], v[0:3]
	s_barrier
	s_setprio 0
	s_cbranch_scc0 .LBB0_528
	s_and_b64 vcc, exec, s[44:45]
	s_cbranch_vccz .LBB0_531
	s_barrier

; #define PG8_STAGE(bufoff, gbase, voff) do { _Pragma("unroll") for (int _i = 0; _i < 2; ++_i) \
;         __builtin_amdgcn_global_load_lds((const unsigned*)((const char*)(gbase) + (voff)[_i]), (PG8_LAS unsigned*)(lds + (bufoff) + ldsw + _i * 8192), 16, 0, 0); } while (0)
; #define PG8_LDA(dst, b, h) do { _Pragma("unroll") for (int m = 0; m < 4; ++m) _Pragma("unroll") for (int k = 0; k < 2; ++k) dst[m][k] = *(const PG8_LAS bf16x8*)(lds + PG8_SA(b, h) + aoff + m * 2048 + k * 1024); } while (0)
; #define PG8_LDB(dst, b, h) do { _Pragma("unroll") for (int n = 0; n < 2; ++n) _Pragma("unroll") for (int k = 0; k < 2; ++k) dst[n][k] = *(const PG8_LAS bf16x8*)(lds + PG8_SB(b, h) + boff + n * 2048 + k * 1024); } while (0)
; #define PG8_MMA(ai, bj, At, Bt) do { __builtin_amdgcn_s_setprio(1); _Pragma("unroll") for (int m = 0; m < 4; ++m) _Pragma("unroll") for (int n = 0; n < 2; ++n) _Pragma("unroll") for (int k = 0; k < 2; ++k) \
;         acc[ai][bj][m][n] = __builtin_amdgcn_mfma_f32_16x16x32_bf16(Bt[n][k], At[m][k], acc[ai][bj][m][n], 0, 0, 0); __builtin_amdgcn_s_setprio(0); } while (0)
; #define PG8_WAIT_V(n) asm volatile("s_waitcnt vmcnt(" #n ")" ::: "memory")
; #define PG8_WAIT_L(n) asm volatile("s_waitcnt lgkmcnt(" #n ")" ::: "memory")
; #define PG8_BAR __builtin_amdgcn_s_barrier()
; template <class Epi, class Sched, bool ALIGN_EPI = false, bool SP2 = false>
; __device__ __forceinline__ void gemm_phase(PG8_LAS unsigned char* lds, const Gemm g, const Sched& S, const Epi& E) {
;     ...
;             const char* a1 = cA + (size_t)(t + 1) * kstep;
;             const char* a2 = last ? nA : cA + (size_t)(t + 2) * kstep; const char* b2 = last ? nB : cB + (size_t)(t + 2) * kstep;
;             const char* a3 = a2 + kstep; const char* b3 = b2 + kstep;
;             if (last && has_next) S.a_ready(nxt);
;             if constexpr (SP2) {
;             PG8_LDB(B0, 0, 0); PG8_LDB(B1, 0, 1); PG8_SCHED; PG8_LDA(At, 0, 0); PG8_STAGE(PG8_SA(1, 1), a1 + hstep, voffA);
;             PG8_WAIT_V(8); PG8_WAIT_L(0); PG8_BAR; PG8_MMA(0, 0, At, B0); PG8_MMA(0, 1, At, B1); PG8_BAR; PG8_SCHED;
;             PG8_LDA(At, 0, 1); PG8_STAGE(PG8_SB(0, 0), b2, voffB); PG8_STAGE(PG8_SB(0, 1), b2 + hstep, voffB); PG8_STAGE(PG8_SA(0, 0), a2, voffA);
;             PG8_WAIT_V(8); PG8_WAIT_L(0); PG8_BAR; PG8_MMA(1, 0, At, B0); PG8_MMA(1, 1, At, B1); PG8_BAR; PG8_SCHED;
.LBB0_604:
	ds_read_b128 v[128:131], v202
	ds_read_b128 v[132:135], v202 offset:1024
	ds_read_b128 v[136:139], v202 offset:2048
	ds_read_b128 v[140:143], v202 offset:3072
	ds_read_b128 v[144:147], v203
	ds_read_b128 v[148:151], v203 offset:1024
	ds_read_b128 v[152:155], v203 offset:2048
	ds_read_b128 v[156:159], v203 offset:3072
	s_add_i32 m0, s4, 0xc000
	ds_read_b128 v[160:163], v204
	ds_read_b128 v[164:167], v204 offset:1024
	ds_read_b128 v[184:187], v204 offset:2048
	ds_read_b128 v[188:191], v204 offset:3072
	ds_read_b128 v[192:195], v204 offset:4096
	ds_read_b128 v[206:209], v204 offset:5120
	ds_read_b128 v[210:213], v204 offset:6144
	ds_read_b128 v[214:217], v204 offset:7168
	global_load_lds_dwordx4 v176, s[72:73]
	s_add_i32 m0, s4, 0xe000
	s_nop 0
	global_load_lds_dwordx4 v178, s[72:73]
	s_add_u32 s74, s72, 0xffe00080
	s_addc_u32 s75, s73, -1
	s_cmpk_eq_i32 s85, 0x7c
	s_cselect_b32 s77, s25, s75
	s_cselect_b32 s76, s65, s74
	s_cselect_b32 s75, s63, s84
	s_cselect_b32 s74, s82, s83
	s_add_i32 s86, s80, s1
	s_mov_b32 m0, s86
	s_waitcnt vmcnt(8)
	s_waitcnt lgkmcnt(0)
	s_setprio 1
	s_barrier
	v_mfma_f32_16x16x32_bf16 v[124:127], v[128:131], v[160:163], v[124:127]
	v_mfma_f32_16x16x32_bf16 v[120:123], v[136:139], v[160:163], v[120:123]
	v_mfma_f32_16x16x32_bf16 v[116:119], v[128:131], v[184:187], v[116:119]
	v_mfma_f32_16x16x32_bf16 v[108:111], v[136:139], v[184:187], v[108:111]
	v_mfma_f32_16x16x32_bf16 v[92:95], v[128:131], v[192:195], v[92:95]
	v_mfma_f32_16x16x32_bf16 v[88:91], v[136:139], v[192:195], v[88:91]
	v_mfma_f32_16x16x32_bf16 v[76:79], v[128:131], v[210:213], v[76:79]
	v_mfma_f32_16x16x32_bf16 v[72:75], v[136:139], v[210:213], v[72:75]
	v_mfma_f32_16x16x32_bf16 v[124:127], v[132:135], v[164:167], v[124:127]
	v_mfma_f32_16x16x32_bf16 v[120:123], v[140:143], v[164:167], v[120:123]
	v_mfma_f32_16x16x32_bf16 v[116:119], v[132:135], v[188:191], v[116:119]
	v_mfma_f32_16x16x32_bf16 v[108:111], v[140:143], v[188:191], v[108:111]
	v_mfma_f32_16x16x32_bf16 v[92:95], v[132:135], v[206:209], v[92:95]
	v_mfma_f32_16x16x32_bf16 v[88:91], v[140:143], v[206:209], v[88:91]
	v_mfma_f32_16x16x32_bf16 v[76:79], v[132:135], v[214:217], v[76:79]
	v_mfma_f32_16x16x32_bf16 v[72:75], v[140:143], v[214:217], v[72:75]
	v_mfma_f32_16x16x32_bf16 v[112:115], v[144:147], v[160:163], v[112:115]
	v_mfma_f32_16x16x32_bf16 v[104:107], v[152:155], v[160:163], v[104:107]
	v_mfma_f32_16x16x32_bf16 v[100:103], v[144:147], v[184:187], v[100:103]
	v_mfma_f32_16x16x32_bf16 v[96:99], v[152:155], v[184:187], v[96:99]
	v_mfma_f32_16x16x32_bf16 v[84:87], v[144:147], v[192:195], v[84:87]
	v_mfma_f32_16x16x32_bf16 v[80:83], v[152:155], v[192:195], v[80:83]
	v_mfma_f32_16x16x32_bf16 v[68:71], v[144:147], v[210:213], v[68:71]
	v_mfma_f32_16x16x32_bf16 v[64:67], v[152:155], v[210:213], v[64:67]
	v_mfma_f32_16x16x32_bf16 v[112:115], v[148:151], v[164:167], v[112:115]
	v_mfma_f32_16x16x32_bf16 v[104:107], v[156:159], v[164:167], v[104:107]
	v_mfma_f32_16x16x32_bf16 v[100:103], v[148:151], v[188:191], v[100:103]
	v_mfma_f32_16x16x32_bf16 v[96:99], v[156:159], v[188:191], v[96:99]
	v_mfma_f32_16x16x32_bf16 v[84:87], v[148:151], v[206:209], v[84:87]
	v_mfma_f32_16x16x32_bf16 v[80:83], v[156:159], v[206:209], v[80:83]
	v_mfma_f32_16x16x32_bf16 v[68:71], v[148:151], v[214:217], v[68:71]
	v_mfma_f32_16x16x32_bf16 v[64:67], v[156:159], v[214:217], v[64:67]
	s_barrier
	s_setprio 0
	ds_read_b128 v[160:163], v204 offset:16384
	ds_read_b128 v[164:167], v204 offset:17408
	ds_read_b128 v[184:187], v204 offset:18432
	ds_read_b128 v[188:191], v204 offset:19456
	ds_read_b128 v[192:195], v204 offset:20480
	ds_read_b128 v[206:209], v204 offset:21504
	ds_read_b128 v[210:213], v204 offset:22528
	ds_read_b128 v[214:217], v204 offset:23552
	global_load_lds_dwordx4 v170, s[74:75]
	s_add_i32 m0, s86, 0x2000
	s_add_u32 s86, s74, 0x200000
	s_addc_u32 s87, s75, 0
	s_add_i32 s88, s81, s1
	global_load_lds_dwordx4 v174, s[74:75]
	s_mov_b32 m0, s88
	s_nop 0
	global_load_lds_dwordx4 v170, s[86:87]
	s_add_i32 m0, s88, 0x2000
	s_nop 0
	global_load_lds_dwordx4 v174, s[86:87]
	s_mov_b32 m0, s4
	s_nop 0
	global_load_lds_dwordx4 v168, s[76:77]
	s_mov_b32 m0, s5
	s_nop 0
	global_load_lds_dwordx4 v172, s[76:77]
	s_waitcnt vmcnt(8)
	s_waitcnt lgkmcnt(0)
	s_setprio 1
	s_barrier
	v_mfma_f32_16x16x32_bf16 v[60:63], v[128:131], v[160:163], v[60:63]
	v_mfma_f32_16x16x32_bf16 v[56:59], v[136:139], v[160:163], v[56:59]
	v_mfma_f32_16x16x32_bf16 v[44:47], v[128:131], v[184:187], v[44:47]
	v_mfma_f32_16x16x32_bf16 v[40:43], v[136:139], v[184:187], v[40:43]
	v_mfma_f32_16x16x32_bf16 v[28:31], v[128:131], v[192:195], v[28:31]
	v_mfma_f32_16x16x32_bf16 v[24:27], v[136:139], v[192:195], v[24:27]
	v_mfma_f32_16x16x32_bf16 v[12:15], v[128:131], v[210:213], v[12:15]
	v_mfma_f32_16x16x32_bf16 v[8:11], v[136:139], v[210:213], v[8:11]
	v_mfma_f32_16x16x32_bf16 v[60:63], v[132:135], v[164:167], v[60:63]
	v_mfma_f32_16x16x32_bf16 v[56:59], v[140:143], v[164:167], v[56:59]
	v_mfma_f32_16x16x32_bf16 v[44:47], v[132:135], v[188:191], v[44:47]
	v_mfma_f32_16x16x32_bf16 v[40:43], v[140:143], v[188:191], v[40:43]
	v_mfma_f32_16x16x32_bf16 v[28:31], v[132:135], v[206:209], v[28:31]
	v_mfma_f32_16x16x32_bf16 v[24:27], v[140:143], v[206:209], v[24:27]
	v_mfma_f32_16x16x32_bf16 v[12:15], v[132:135], v[214:217], v[12:15]
	v_mfma_f32_16x16x32_bf16 v[8:11], v[140:143], v[214:217], v[8:11]
	v_mfma_f32_16x16x32_bf16 v[52:55], v[144:147], v[160:163], v[52:55]
	v_mfma_f32_16x16x32_bf16 v[48:51], v[152:155], v[160:163], v[48:51]
	v_mfma_f32_16x16x32_bf16 v[36:39], v[144:147], v[184:187], v[36:39]
	v_mfma_f32_16x16x32_bf16 v[32:35], v[152:155], v[184:187], v[32:35]
	v_mfma_f32_16x16x32_bf16 v[20:23], v[144:147], v[192:195], v[20:23]
	v_mfma_f32_16x16x32_bf16 v[16:19], v[152:155], v[192:195], v[16:19]
	v_mfma_f32_16x16x32_bf16 v[4:7], v[144:147], v[210:213], v[4:7]
	v_mfma_f32_16x16x32_bf16 v[0:3], v[152:155], v[210:213], v[0:3]
	v_mfma_f32_16x16x32_bf16 v[52:55], v[148:151], v[164:167], v[52:55]
	v_mfma_f32_16x16x32_bf16 v[48:51], v[156:159], v[164:167], v[48:51]
	v_mfma_f32_16x16x32_bf16 v[36:39], v[148:151], v[188:191], v[36:39]
	v_mfma_f32_16x16x32_bf16 v[32:35], v[156:159], v[188:191], v[32:35]
	v_mfma_f32_16x16x32_bf16 v[20:23], v[148:151], v[206:209], v[20:23]
	v_mfma_f32_16x16x32_bf16 v[16:19], v[156:159], v[206:209], v[16:19]
	v_mfma_f32_16x16x32_bf16 v[4:7], v[148:151], v[214:217], v[4:7]
	v_mfma_f32_16x16x32_bf16 v[0:3], v[156:159], v[214:217], v[0:3]
	s_barrier
; #define PG8_STAGE(bufoff, gbase, voff) do { _Pragma("unroll") for (int _i = 0; _i < 2; ++_i) \
;         __builtin_amdgcn_global_load_lds((const unsigned*)((const char*)(gbase) + (voff)[_i]), (PG8_LAS unsigned*)(lds + (bufoff) + ldsw + _i * 8192), 16, 0, 0); } while (0)
; #define PG8_LDA(dst, b, h) do { _Pragma("unroll") for (int m = 0; m < 4; ++m) _Pragma("unroll") for (int k = 0; k < 2; ++k) dst[m][k] = *(const PG8_LAS bf16x8*)(lds + PG8_SA(b, h) + aoff + m * 2048 + k * 1024); } while (0)
; #define PG8_LDB(dst, b, h) do { _Pragma("unroll") for (int n = 0; n < 2; ++n) _Pragma("unroll") for (int k = 0; k < 2; ++k) dst[n][k] = *(const PG8_LAS bf16x8*)(lds + PG8_SB(b, h) + boff + n * 2048 + k * 1024); } while (0)
; #define PG8_MMA(ai, bj, At, Bt) do { __builtin_amdgcn_s_setprio(1); _Pragma("unroll") for (int m = 0; m < 4; ++m) _Pragma("unroll") for (int n = 0; n < 2; ++n) _Pragma("unroll") for (int k = 0; k < 2; ++k) \
;         acc[ai][bj][m][n] = __builtin_amdgcn_mfma_f32_16x16x32_bf16(Bt[n][k], At[m][k], acc[ai][bj][m][n], 0, 0, 0); __builtin_amdgcn_s_setprio(0); } while (0)
; #define PG8_WAIT_V(n) asm volatile("s_waitcnt vmcnt(" #n ")" ::: "memory")
; #define PG8_WAIT_L(n) asm volatile("s_waitcnt lgkmcnt(" #n ")" ::: "memory")
; #define PG8_BAR __builtin_amdgcn_s_barrier()
; #define PG8_SCHED __builtin_amdgcn_sched_barrier(0)
; template <class Epi, class Sched, bool ALIGN_EPI = false, bool SP2 = false>
; __device__ __forceinline__ void gemm_phase(PG8_LAS unsigned char* lds, const Gemm g, const Sched& S, const Epi& E) {
;     ...
;             PG8_LDB(B0, 1, 0); PG8_LDB(B1, 1, 1); PG8_SCHED; PG8_LDA(At, 1, 0); PG8_STAGE(PG8_SA(0, 1), a2 + hstep, voffA);
;             PG8_WAIT_V(8); PG8_WAIT_L(0); PG8_BAR; PG8_MMA(0, 0, At, B0); PG8_MMA(0, 1, At, B1); PG8_BAR; PG8_SCHED;
;             PG8_LDA(At, 1, 1); PG8_STAGE(PG8_SB(1, 0), b3, voffB); PG8_STAGE(PG8_SB(1, 1), b3 + hstep, voffB); PG8_STAGE(PG8_SA(1, 0), a3, voffA);
;             PG8_WAIT_V(8); PG8_WAIT_L(0); PG8_BAR; PG8_MMA(1, 0, At, B0); PG8_MMA(1, 1, At, B1); PG8_BAR; PG8_SCHED;
;     ...
;         if constexpr (ALIGN_EPI) { if (wr == 0) PG8_BAR; }
	s_setprio 0
	ds_read_b128 v[128:131], v218
	ds_read_b128 v[132:135], v218 offset:1024
	ds_read_b128 v[136:139], v218 offset:2048
	ds_read_b128 v[140:143], v218 offset:3072
	ds_read_b128 v[144:147], v219
	ds_read_b128 v[148:151], v219 offset:1024
	ds_read_b128 v[152:155], v219 offset:2048
	ds_read_b128 v[156:159], v219 offset:3072
	ds_read_b128 v[160:163], v204 offset:32768
	ds_read_b128 v[164:167], v204 offset:33792
	ds_read_b128 v[184:187], v204 offset:34816
	ds_read_b128 v[188:191], v204 offset:35840
	ds_read_b128 v[192:195], v204 offset:36864
	ds_read_b128 v[206:209], v204 offset:37888
	ds_read_b128 v[210:213], v204 offset:38912
	ds_read_b128 v[214:217], v204 offset:39936
	s_add_u32 s98, s76, 0x200000
	s_addc_u32 s99, s77, 0
	s_mov_b32 m0, s14
	s_add_u32 s100, s76, 0x80
	s_addc_u32 s101, s77, 0
	global_load_lds_dwordx4 v168, s[98:99]
	s_mov_b32 m0, s15
	s_nop 0
	global_load_lds_dwordx4 v172, s[98:99]
	s_add_i32 s86, 0, 0x18000
	s_add_i32 s87, 0, 0x1c000
	s_add_u32 s98, s74, 0x80
	s_addc_u32 s99, s75, 0
	s_add_i32 s76, s86, s1
	s_mov_b32 m0, s76
	s_waitcnt vmcnt(8)
	s_waitcnt lgkmcnt(0)
	s_setprio 1
	s_barrier
	v_mfma_f32_16x16x32_bf16 v[124:127], v[128:131], v[160:163], v[124:127]
	v_mfma_f32_16x16x32_bf16 v[120:123], v[136:139], v[160:163], v[120:123]
	v_mfma_f32_16x16x32_bf16 v[116:119], v[128:131], v[184:187], v[116:119]
	v_mfma_f32_16x16x32_bf16 v[108:111], v[136:139], v[184:187], v[108:111]
	v_mfma_f32_16x16x32_bf16 v[92:95], v[128:131], v[192:195], v[92:95]
	v_mfma_f32_16x16x32_bf16 v[88:91], v[136:139], v[192:195], v[88:91]
	v_mfma_f32_16x16x32_bf16 v[76:79], v[128:131], v[210:213], v[76:79]
	v_mfma_f32_16x16x32_bf16 v[72:75], v[136:139], v[210:213], v[72:75]
	v_mfma_f32_16x16x32_bf16 v[124:127], v[132:135], v[164:167], v[124:127]
	v_mfma_f32_16x16x32_bf16 v[120:123], v[140:143], v[164:167], v[120:123]
	v_mfma_f32_16x16x32_bf16 v[116:119], v[132:135], v[188:191], v[116:119]
	v_mfma_f32_16x16x32_bf16 v[108:111], v[140:143], v[188:191], v[108:111]
	v_mfma_f32_16x16x32_bf16 v[92:95], v[132:135], v[206:209], v[92:95]
	v_mfma_f32_16x16x32_bf16 v[88:91], v[140:143], v[206:209], v[88:91]
	v_mfma_f32_16x16x32_bf16 v[76:79], v[132:135], v[214:217], v[76:79]
	v_mfma_f32_16x16x32_bf16 v[72:75], v[140:143], v[214:217], v[72:75]
	v_mfma_f32_16x16x32_bf16 v[112:115], v[144:147], v[160:163], v[112:115]
	v_mfma_f32_16x16x32_bf16 v[104:107], v[152:155], v[160:163], v[104:107]
	v_mfma_f32_16x16x32_bf16 v[100:103], v[144:147], v[184:187], v[100:103]
	v_mfma_f32_16x16x32_bf16 v[96:99], v[152:155], v[184:187], v[96:99]
	v_mfma_f32_16x16x32_bf16 v[84:87], v[144:147], v[192:195], v[84:87]
	v_mfma_f32_16x16x32_bf16 v[80:83], v[152:155], v[192:195], v[80:83]
	v_mfma_f32_16x16x32_bf16 v[68:71], v[144:147], v[210:213], v[68:71]
	v_mfma_f32_16x16x32_bf16 v[64:67], v[152:155], v[210:213], v[64:67]
	v_mfma_f32_16x16x32_bf16 v[112:115], v[148:151], v[164:167], v[112:115]
	v_mfma_f32_16x16x32_bf16 v[104:107], v[156:159], v[164:167], v[104:107]
	v_mfma_f32_16x16x32_bf16 v[100:103], v[148:151], v[188:191], v[100:103]
	v_mfma_f32_16x16x32_bf16 v[96:99], v[156:159], v[188:191], v[96:99]
	v_mfma_f32_16x16x32_bf16 v[84:87], v[148:151], v[206:209], v[84:87]
	v_mfma_f32_16x16x32_bf16 v[80:83], v[156:159], v[206:209], v[80:83]
	v_mfma_f32_16x16x32_bf16 v[68:71], v[148:151], v[214:217], v[68:71]
	v_mfma_f32_16x16x32_bf16 v[64:67], v[156:159], v[214:217], v[64:67]
	s_barrier
	s_setprio 0
	ds_read_b128 v[160:163], v204 offset:49152
	ds_read_b128 v[164:167], v204 offset:50176
	ds_read_b128 v[184:187], v204 offset:51200
	ds_read_b128 v[188:191], v204 offset:52224
	ds_read_b128 v[192:195], v204 offset:53248
	ds_read_b128 v[206:209], v204 offset:54272
	ds_read_b128 v[210:213], v204 offset:55296
	ds_read_b128 v[214:217], v204 offset:56320
	global_load_lds_dwordx4 v170, s[98:99]
	s_add_i32 m0, s76, 0x2000
	s_add_u32 s74, s74, 0x200080
	s_addc_u32 s75, s75, 0
	s_add_i32 s76, s87, s1
	global_load_lds_dwordx4 v174, s[98:99]
	s_mov_b32 m0, s76
	s_nop 0
	global_load_lds_dwordx4 v170, s[74:75]
	s_add_i32 m0, s76, 0x2000
	s_nop 0
	global_load_lds_dwordx4 v174, s[74:75]
	s_mov_b32 m0, s35
	s_nop 0
	global_load_lds_dwordx4 v168, s[100:101]
	s_mov_b32 m0, s71
	s_nop 0
	global_load_lds_dwordx4 v172, s[100:101]
	s_add_i32 s85, s85, 2
	s_add_u32 s72, s72, 0x100
	s_addc_u32 s73, s73, 0
	s_add_u32 s83, s83, 0x100
	s_addc_u32 s84, s84, 0
	s_cmpk_gt_u32 s85, 0x7d
	s_waitcnt vmcnt(8)
	s_waitcnt lgkmcnt(0)
	s_setprio 1
	s_barrier
	v_mfma_f32_16x16x32_bf16 v[60:63], v[128:131], v[160:163], v[60:63]
	v_mfma_f32_16x16x32_bf16 v[56:59], v[136:139], v[160:163], v[56:59]
	v_mfma_f32_16x16x32_bf16 v[44:47], v[128:131], v[184:187], v[44:47]
	v_mfma_f32_16x16x32_bf16 v[40:43], v[136:139], v[184:187], v[40:43]
	v_mfma_f32_16x16x32_bf16 v[28:31], v[128:131], v[192:195], v[28:31]
	v_mfma_f32_16x16x32_bf16 v[24:27], v[136:139], v[192:195], v[24:27]
	v_mfma_f32_16x16x32_bf16 v[12:15], v[128:131], v[210:213], v[12:15]
	v_mfma_f32_16x16x32_bf16 v[8:11], v[136:139], v[210:213], v[8:11]
	v_mfma_f32_16x16x32_bf16 v[60:63], v[132:135], v[164:167], v[60:63]
	v_mfma_f32_16x16x32_bf16 v[56:59], v[140:143], v[164:167], v[56:59]
	v_mfma_f32_16x16x32_bf16 v[44:47], v[132:135], v[188:191], v[44:47]
	v_mfma_f32_16x16x32_bf16 v[40:43], v[140:143], v[188:191], v[40:43]
	v_mfma_f32_16x16x32_bf16 v[28:31], v[132:135], v[206:209], v[28:31]
	v_mfma_f32_16x16x32_bf16 v[24:27], v[140:143], v[206:209], v[24:27]
	v_mfma_f32_16x16x32_bf16 v[12:15], v[132:135], v[214:217], v[12:15]
	v_mfma_f32_16x16x32_bf16 v[8:11], v[140:143], v[214:217], v[8:11]
	v_mfma_f32_16x16x32_bf16 v[52:55], v[144:147], v[160:163], v[52:55]
	v_mfma_f32_16x16x32_bf16 v[48:51], v[152:155], v[160:163], v[48:51]
	v_mfma_f32_16x16x32_bf16 v[36:39], v[144:147], v[184:187], v[36:39]
	v_mfma_f32_16x16x32_bf16 v[32:35], v[152:155], v[184:187], v[32:35]
	v_mfma_f32_16x16x32_bf16 v[20:23], v[144:147], v[192:195], v[20:23]
	v_mfma_f32_16x16x32_bf16 v[16:19], v[152:155], v[192:195], v[16:19]
	v_mfma_f32_16x16x32_bf16 v[4:7], v[144:147], v[210:213], v[4:7]
	v_mfma_f32_16x16x32_bf16 v[0:3], v[152:155], v[210:213], v[0:3]
	v_mfma_f32_16x16x32_bf16 v[52:55], v[148:151], v[164:167], v[52:55]
	v_mfma_f32_16x16x32_bf16 v[48:51], v[156:159], v[164:167], v[48:51]
	v_mfma_f32_16x16x32_bf16 v[36:39], v[148:151], v[188:191], v[36:39]
	v_mfma_f32_16x16x32_bf16 v[32:35], v[156:159], v[188:191], v[32:35]
	v_mfma_f32_16x16x32_bf16 v[20:23], v[148:151], v[206:209], v[20:23]
	v_mfma_f32_16x16x32_bf16 v[16:19], v[156:159], v[206:209], v[16:19]
	v_mfma_f32_16x16x32_bf16 v[4:7], v[148:151], v[214:217], v[4:7]
	v_mfma_f32_16x16x32_bf16 v[0:3], v[156:159], v[214:217], v[0:3]
	s_barrier
	s_setprio 0
	s_cbranch_scc0 .LBB0_604
	s_and_b64 vcc, exec, s[48:49]
	s_cbranch_vccz .LBB0_607
	s_barrier

; #define PG8_STAGE(bufoff, gbase, voff) do { _Pragma("unroll") for (int _i = 0; _i < 2; ++_i) \
;         __builtin_amdgcn_global_load_lds((const unsigned*)((const char*)(gbase) + (voff)[_i]), (PG8_LAS unsigned*)(lds + (bufoff) + ldsw + _i * 8192), 16, 0, 0); } while (0)
; #define PG8_LDA(dst, b, h) do { _Pragma("unroll") for (int m = 0; m < 4; ++m) _Pragma("unroll") for (int k = 0; k < 2; ++k) dst[m][k] = *(const PG8_LAS bf16x8*)(lds + PG8_SA(b, h) + aoff + m * 2048 + k * 1024); } while (0)
; #define PG8_LDB(dst, b, h) do { _Pragma("unroll") for (int n = 0; n < 2; ++n) _Pragma("unroll") for (int k = 0; k < 2; ++k) dst[n][k] = *(const PG8_LAS bf16x8*)(lds + PG8_SB(b, h) + boff + n * 2048 + k * 1024); } while (0)
; #define PG8_MMA(ai, bj, At, Bt) do { __builtin_amdgcn_s_setprio(1); _Pragma("unroll") for (int m = 0; m < 4; ++m) _Pragma("unroll") for (int n = 0; n < 2; ++n) _Pragma("unroll") for (int k = 0; k < 2; ++k) \
;         acc[ai][bj][m][n] = __builtin_amdgcn_mfma_f32_16x16x32_bf16(Bt[n][k], At[m][k], acc[ai][bj][m][n], 0, 0, 0); __builtin_amdgcn_s_setprio(0); } while (0)
; #define PG8_WAIT_V(n) asm volatile("s_waitcnt vmcnt(" #n ")" ::: "memory")
; #define PG8_WAIT_L(n) asm volatile("s_waitcnt lgkmcnt(" #n ")" ::: "memory")
; #define PG8_BAR __builtin_amdgcn_s_barrier()
; template <class Epi, class Sched, bool ALIGN_EPI = false, bool SP2 = false>
; __device__ __forceinline__ void gemm_phase(PG8_LAS unsigned char* lds, const Gemm g, const Sched& S, const Epi& E) {
;     ...
;             const char* a1 = cA + (size_t)(t + 1) * kstep;
;             const char* a2 = last ? nA : cA + (size_t)(t + 2) * kstep; const char* b2 = last ? nB : cB + (size_t)(t + 2) * kstep;
;             const char* a3 = a2 + kstep; const char* b3 = b2 + kstep;
;             if (last && has_next) S.a_ready(nxt);
;             if constexpr (SP2) {
;             PG8_LDB(B0, 0, 0); PG8_LDB(B1, 0, 1); PG8_SCHED; PG8_LDA(At, 0, 0); PG8_STAGE(PG8_SA(1, 1), a1 + hstep, voffA);
;             PG8_WAIT_V(8); PG8_WAIT_L(0); PG8_BAR; PG8_MMA(0, 0, At, B0); PG8_MMA(0, 1, At, B1); PG8_BAR; PG8_SCHED;
;             PG8_LDA(At, 0, 1); PG8_STAGE(PG8_SB(0, 0), b2, voffB); PG8_STAGE(PG8_SB(0, 1), b2 + hstep, voffB); PG8_STAGE(PG8_SA(0, 0), a2, voffA);
;             PG8_WAIT_V(8); PG8_WAIT_L(0); PG8_BAR; PG8_MMA(1, 0, At, B0); PG8_MMA(1, 1, At, B1); PG8_BAR; PG8_SCHED;
.LBB0_735:
	ds_read_b128 v[156:159], v151
	ds_read_b128 v[160:163], v151 offset:1024
	ds_read_b128 v[164:167], v151 offset:2048
	ds_read_b128 v[168:171], v151 offset:3072
	ds_read_b128 v[172:175], v152
	ds_read_b128 v[176:179], v152 offset:1024
	ds_read_b128 v[180:183], v152 offset:2048
	ds_read_b128 v[184:187], v152 offset:3072
	s_add_i32 m0, s4, 0xc000
	ds_read_b128 v[188:191], v153
	ds_read_b128 v[192:195], v153 offset:1024
	ds_read_b128 v[200:203], v153 offset:2048
	ds_read_b128 v[204:207], v153 offset:3072
	ds_read_b128 v[208:211], v153 offset:4096
	ds_read_b128 v[212:215], v153 offset:5120
	ds_read_b128 v[216:219], v153 offset:6144
	ds_read_b128 v[220:223], v153 offset:7168
	global_load_lds_dwordx4 v138, s[68:69]
	s_add_i32 m0, s4, 0xe000
	s_nop 0
	global_load_lds_dwordx4 v140, s[68:69]
	s_add_u32 s70, s68, 0xfff80080
	s_addc_u32 s71, s69, -1
	s_cmp_eq_u32 s82, 28
	s_cselect_b32 s73, s25, s71
	s_cselect_b32 s72, s61, s70
	s_cselect_b32 s71, s49, s81
	s_cselect_b32 s70, s79, s80
	s_add_i32 s83, s77, s1
	s_mov_b32 m0, s83
	s_waitcnt vmcnt(8)
	s_waitcnt lgkmcnt(0)
	s_setprio 1
	s_barrier
	v_mfma_f32_16x16x32_bf16 v[124:127], v[156:159], v[188:191], v[124:127]
	v_mfma_f32_16x16x32_bf16 v[120:123], v[164:167], v[188:191], v[120:123]
	v_mfma_f32_16x16x32_bf16 v[108:111], v[156:159], v[200:203], v[108:111]
	v_mfma_f32_16x16x32_bf16 v[104:107], v[164:167], v[200:203], v[104:107]
	v_mfma_f32_16x16x32_bf16 v[96:99], v[156:159], v[208:211], v[96:99]
	v_mfma_f32_16x16x32_bf16 v[88:91], v[164:167], v[208:211], v[88:91]
	v_mfma_f32_16x16x32_bf16 v[80:83], v[156:159], v[216:219], v[80:83]
	v_mfma_f32_16x16x32_bf16 v[72:75], v[164:167], v[216:219], v[72:75]
	v_mfma_f32_16x16x32_bf16 v[124:127], v[160:163], v[192:195], v[124:127]
	v_mfma_f32_16x16x32_bf16 v[120:123], v[168:171], v[192:195], v[120:123]
	v_mfma_f32_16x16x32_bf16 v[108:111], v[160:163], v[204:207], v[108:111]
	v_mfma_f32_16x16x32_bf16 v[104:107], v[168:171], v[204:207], v[104:107]
	v_mfma_f32_16x16x32_bf16 v[96:99], v[160:163], v[212:215], v[96:99]
	v_mfma_f32_16x16x32_bf16 v[88:91], v[168:171], v[212:215], v[88:91]
	v_mfma_f32_16x16x32_bf16 v[80:83], v[160:163], v[220:223], v[80:83]
	v_mfma_f32_16x16x32_bf16 v[72:75], v[168:171], v[220:223], v[72:75]
	v_mfma_f32_16x16x32_bf16 v[116:119], v[172:175], v[188:191], v[116:119]
	v_mfma_f32_16x16x32_bf16 v[112:115], v[180:183], v[188:191], v[112:115]
	v_mfma_f32_16x16x32_bf16 v[100:103], v[172:175], v[200:203], v[100:103]
	v_mfma_f32_16x16x32_bf16 v[92:95], v[180:183], v[200:203], v[92:95]
	v_mfma_f32_16x16x32_bf16 v[84:87], v[172:175], v[208:211], v[84:87]
	v_mfma_f32_16x16x32_bf16 v[76:79], v[180:183], v[208:211], v[76:79]
	v_mfma_f32_16x16x32_bf16 v[68:71], v[172:175], v[216:219], v[68:71]
	v_mfma_f32_16x16x32_bf16 v[64:67], v[180:183], v[216:219], v[64:67]
	v_mfma_f32_16x16x32_bf16 v[116:119], v[176:179], v[192:195], v[116:119]
	v_mfma_f32_16x16x32_bf16 v[112:115], v[184:187], v[192:195], v[112:115]
	v_mfma_f32_16x16x32_bf16 v[100:103], v[176:179], v[204:207], v[100:103]
	v_mfma_f32_16x16x32_bf16 v[92:95], v[184:187], v[204:207], v[92:95]
	v_mfma_f32_16x16x32_bf16 v[84:87], v[176:179], v[212:215], v[84:87]
	v_mfma_f32_16x16x32_bf16 v[76:79], v[184:187], v[212:215], v[76:79]
	v_mfma_f32_16x16x32_bf16 v[68:71], v[176:179], v[220:223], v[68:71]
	v_mfma_f32_16x16x32_bf16 v[64:67], v[184:187], v[220:223], v[64:67]
	s_barrier
	s_setprio 0
	ds_read_b128 v[188:191], v153 offset:16384
	ds_read_b128 v[192:195], v153 offset:17408
	ds_read_b128 v[200:203], v153 offset:18432
	ds_read_b128 v[204:207], v153 offset:19456
	ds_read_b128 v[208:211], v153 offset:20480
	ds_read_b128 v[212:215], v153 offset:21504
	ds_read_b128 v[216:219], v153 offset:22528
	ds_read_b128 v[220:223], v153 offset:23552
	global_load_lds_dwordx4 v130, s[70:71]
	s_add_i32 m0, s83, 0x2000
	s_add_u32 s84, s70, 0x80000
	s_addc_u32 s85, s71, 0
	s_add_i32 s83, s78, s1
	global_load_lds_dwordx4 v134, s[70:71]
	s_mov_b32 m0, s83
	s_nop 0
	global_load_lds_dwordx4 v130, s[84:85]
	s_add_i32 m0, s83, 0x2000
	s_nop 0
	global_load_lds_dwordx4 v134, s[84:85]
	s_mov_b32 m0, s4
	s_nop 0
	global_load_lds_dwordx4 v128, s[72:73]
	s_mov_b32 m0, s5
	s_nop 0
	global_load_lds_dwordx4 v132, s[72:73]
	s_waitcnt vmcnt(8)
	s_waitcnt lgkmcnt(0)
	s_setprio 1
	s_barrier
	v_mfma_f32_16x16x32_bf16 v[60:63], v[156:159], v[188:191], v[60:63]
	v_mfma_f32_16x16x32_bf16 v[56:59], v[164:167], v[188:191], v[56:59]
	v_mfma_f32_16x16x32_bf16 v[44:47], v[156:159], v[200:203], v[44:47]
	v_mfma_f32_16x16x32_bf16 v[40:43], v[164:167], v[200:203], v[40:43]
	v_mfma_f32_16x16x32_bf16 v[32:35], v[156:159], v[208:211], v[32:35]
	v_mfma_f32_16x16x32_bf16 v[24:27], v[164:167], v[208:211], v[24:27]
	v_mfma_f32_16x16x32_bf16 v[16:19], v[156:159], v[216:219], v[16:19]
	v_mfma_f32_16x16x32_bf16 v[8:11], v[164:167], v[216:219], v[8:11]
	v_mfma_f32_16x16x32_bf16 v[60:63], v[160:163], v[192:195], v[60:63]
	v_mfma_f32_16x16x32_bf16 v[56:59], v[168:171], v[192:195], v[56:59]
	v_mfma_f32_16x16x32_bf16 v[44:47], v[160:163], v[204:207], v[44:47]
	v_mfma_f32_16x16x32_bf16 v[40:43], v[168:171], v[204:207], v[40:43]
	v_mfma_f32_16x16x32_bf16 v[32:35], v[160:163], v[212:215], v[32:35]
	v_mfma_f32_16x16x32_bf16 v[24:27], v[168:171], v[212:215], v[24:27]
	v_mfma_f32_16x16x32_bf16 v[16:19], v[160:163], v[220:223], v[16:19]
	v_mfma_f32_16x16x32_bf16 v[8:11], v[168:171], v[220:223], v[8:11]
	v_mfma_f32_16x16x32_bf16 v[52:55], v[172:175], v[188:191], v[52:55]
	v_mfma_f32_16x16x32_bf16 v[48:51], v[180:183], v[188:191], v[48:51]
	v_mfma_f32_16x16x32_bf16 v[36:39], v[172:175], v[200:203], v[36:39]
	v_mfma_f32_16x16x32_bf16 v[28:31], v[180:183], v[200:203], v[28:31]
	v_mfma_f32_16x16x32_bf16 v[20:23], v[172:175], v[208:211], v[20:23]
	v_mfma_f32_16x16x32_bf16 v[12:15], v[180:183], v[208:211], v[12:15]
	v_mfma_f32_16x16x32_bf16 v[4:7], v[172:175], v[216:219], v[4:7]
	v_mfma_f32_16x16x32_bf16 v[0:3], v[180:183], v[216:219], v[0:3]
	v_mfma_f32_16x16x32_bf16 v[52:55], v[176:179], v[192:195], v[52:55]
	v_mfma_f32_16x16x32_bf16 v[48:51], v[184:187], v[192:195], v[48:51]
	v_mfma_f32_16x16x32_bf16 v[36:39], v[176:179], v[204:207], v[36:39]
	v_mfma_f32_16x16x32_bf16 v[28:31], v[184:187], v[204:207], v[28:31]
	v_mfma_f32_16x16x32_bf16 v[20:23], v[176:179], v[212:215], v[20:23]
	v_mfma_f32_16x16x32_bf16 v[12:15], v[184:187], v[212:215], v[12:15]
	v_mfma_f32_16x16x32_bf16 v[4:7], v[176:179], v[220:223], v[4:7]
	v_mfma_f32_16x16x32_bf16 v[0:3], v[184:187], v[220:223], v[0:3]
	s_barrier
; #define PG8_STAGE(bufoff, gbase, voff) do { _Pragma("unroll") for (int _i = 0; _i < 2; ++_i) \
;         __builtin_amdgcn_global_load_lds((const unsigned*)((const char*)(gbase) + (voff)[_i]), (PG8_LAS unsigned*)(lds + (bufoff) + ldsw + _i * 8192), 16, 0, 0); } while (0)
; #define PG8_LDA(dst, b, h) do { _Pragma("unroll") for (int m = 0; m < 4; ++m) _Pragma("unroll") for (int k = 0; k < 2; ++k) dst[m][k] = *(const PG8_LAS bf16x8*)(lds + PG8_SA(b, h) + aoff + m * 2048 + k * 1024); } while (0)
; #define PG8_LDB(dst, b, h) do { _Pragma("unroll") for (int n = 0; n < 2; ++n) _Pragma("unroll") for (int k = 0; k < 2; ++k) dst[n][k] = *(const PG8_LAS bf16x8*)(lds + PG8_SB(b, h) + boff + n * 2048 + k * 1024); } while (0)
; #define PG8_MMA(ai, bj, At, Bt) do { __builtin_amdgcn_s_setprio(1); _Pragma("unroll") for (int m = 0; m < 4; ++m) _Pragma("unroll") for (int n = 0; n < 2; ++n) _Pragma("unroll") for (int k = 0; k < 2; ++k) \
;         acc[ai][bj][m][n] = __builtin_amdgcn_mfma_f32_16x16x32_bf16(Bt[n][k], At[m][k], acc[ai][bj][m][n], 0, 0, 0); __builtin_amdgcn_s_setprio(0); } while (0)
; #define PG8_WAIT_V(n) asm volatile("s_waitcnt vmcnt(" #n ")" ::: "memory")
; #define PG8_WAIT_L(n) asm volatile("s_waitcnt lgkmcnt(" #n ")" ::: "memory")
; #define PG8_BAR __builtin_amdgcn_s_barrier()
; #define PG8_SCHED __builtin_amdgcn_sched_barrier(0)
; template <class Epi, class Sched, bool ALIGN_EPI = false, bool SP2 = false>
; __device__ __forceinline__ void gemm_phase(PG8_LAS unsigned char* lds, const Gemm g, const Sched& S, const Epi& E) {
;     ...
;             PG8_LDB(B0, 1, 0); PG8_LDB(B1, 1, 1); PG8_SCHED; PG8_LDA(At, 1, 0); PG8_STAGE(PG8_SA(0, 1), a2 + hstep, voffA);
;             PG8_WAIT_V(8); PG8_WAIT_L(0); PG8_BAR; PG8_MMA(0, 0, At, B0); PG8_MMA(0, 1, At, B1); PG8_BAR; PG8_SCHED;
;             PG8_LDA(At, 1, 1); PG8_STAGE(PG8_SB(1, 0), b3, voffB); PG8_STAGE(PG8_SB(1, 1), b3 + hstep, voffB); PG8_STAGE(PG8_SA(1, 0), a3, voffA);
;             PG8_WAIT_V(8); PG8_WAIT_L(0); PG8_BAR; PG8_MMA(1, 0, At, B0); PG8_MMA(1, 1, At, B1); PG8_BAR; PG8_SCHED;
;     ...
;         if constexpr (ALIGN_EPI) { if (wr == 0) PG8_BAR; }
	s_setprio 0
	ds_read_b128 v[156:159], v196
	ds_read_b128 v[160:163], v196 offset:1024
	ds_read_b128 v[164:167], v196 offset:2048
	ds_read_b128 v[168:171], v196 offset:3072
	ds_read_b128 v[172:175], v197
	ds_read_b128 v[176:179], v197 offset:1024
	ds_read_b128 v[180:183], v197 offset:2048
	ds_read_b128 v[184:187], v197 offset:3072
	ds_read_b128 v[188:191], v153 offset:32768
	ds_read_b128 v[192:195], v153 offset:33792
	ds_read_b128 v[200:203], v153 offset:34816
	ds_read_b128 v[204:207], v153 offset:35840
	ds_read_b128 v[208:211], v153 offset:36864
	ds_read_b128 v[212:215], v153 offset:37888
	ds_read_b128 v[216:219], v153 offset:38912
	ds_read_b128 v[220:223], v153 offset:39936
	s_add_u32 s98, s72, 0x80000
	s_addc_u32 s99, s73, 0
	s_mov_b32 m0, s14
	s_add_u32 s100, s72, 0x80
	s_addc_u32 s101, s73, 0
	global_load_lds_dwordx4 v128, s[98:99]
	s_mov_b32 m0, s15
	s_nop 0
	global_load_lds_dwordx4 v132, s[98:99]
	s_add_i32 s83, 0, 0x18000
	s_add_i32 s84, 0, 0x1c000
	s_add_u32 s98, s70, 0x80
	s_addc_u32 s99, s71, 0
	s_add_i32 s72, s83, s1
	s_mov_b32 m0, s72
	s_waitcnt vmcnt(8)
	s_waitcnt lgkmcnt(0)
	s_setprio 1
	s_barrier
	v_mfma_f32_16x16x32_bf16 v[124:127], v[156:159], v[188:191], v[124:127]
	v_mfma_f32_16x16x32_bf16 v[120:123], v[164:167], v[188:191], v[120:123]
	v_mfma_f32_16x16x32_bf16 v[108:111], v[156:159], v[200:203], v[108:111]
	v_mfma_f32_16x16x32_bf16 v[104:107], v[164:167], v[200:203], v[104:107]
	v_mfma_f32_16x16x32_bf16 v[96:99], v[156:159], v[208:211], v[96:99]
	v_mfma_f32_16x16x32_bf16 v[88:91], v[164:167], v[208:211], v[88:91]
	v_mfma_f32_16x16x32_bf16 v[80:83], v[156:159], v[216:219], v[80:83]
	v_mfma_f32_16x16x32_bf16 v[72:75], v[164:167], v[216:219], v[72:75]
	v_mfma_f32_16x16x32_bf16 v[124:127], v[160:163], v[192:195], v[124:127]
	v_mfma_f32_16x16x32_bf16 v[120:123], v[168:171], v[192:195], v[120:123]
	v_mfma_f32_16x16x32_bf16 v[108:111], v[160:163], v[204:207], v[108:111]
	v_mfma_f32_16x16x32_bf16 v[104:107], v[168:171], v[204:207], v[104:107]
	v_mfma_f32_16x16x32_bf16 v[96:99], v[160:163], v[212:215], v[96:99]
	v_mfma_f32_16x16x32_bf16 v[88:91], v[168:171], v[212:215], v[88:91]
	v_mfma_f32_16x16x32_bf16 v[80:83], v[160:163], v[220:223], v[80:83]
	v_mfma_f32_16x16x32_bf16 v[72:75], v[168:171], v[220:223], v[72:75]
	v_mfma_f32_16x16x32_bf16 v[116:119], v[172:175], v[188:191], v[116:119]
	v_mfma_f32_16x16x32_bf16 v[112:115], v[180:183], v[188:191], v[112:115]
	v_mfma_f32_16x16x32_bf16 v[100:103], v[172:175], v[200:203], v[100:103]
	v_mfma_f32_16x16x32_bf16 v[92:95], v[180:183], v[200:203], v[92:95]
	v_mfma_f32_16x16x32_bf16 v[84:87], v[172:175], v[208:211], v[84:87]
	v_mfma_f32_16x16x32_bf16 v[76:79], v[180:183], v[208:211], v[76:79]
	v_mfma_f32_16x16x32_bf16 v[68:71], v[172:175], v[216:219], v[68:71]
	v_mfma_f32_16x16x32_bf16 v[64:67], v[180:183], v[216:219], v[64:67]
	v_mfma_f32_16x16x32_bf16 v[116:119], v[176:179], v[192:195], v[116:119]
	v_mfma_f32_16x16x32_bf16 v[112:115], v[184:187], v[192:195], v[112:115]
	v_mfma_f32_16x16x32_bf16 v[100:103], v[176:179], v[204:207], v[100:103]
	v_mfma_f32_16x16x32_bf16 v[92:95], v[184:187], v[204:207], v[92:95]
	v_mfma_f32_16x16x32_bf16 v[84:87], v[176:179], v[212:215], v[84:87]
	v_mfma_f32_16x16x32_bf16 v[76:79], v[184:187], v[212:215], v[76:79]
	v_mfma_f32_16x16x32_bf16 v[68:71], v[176:179], v[220:223], v[68:71]
	v_mfma_f32_16x16x32_bf16 v[64:67], v[184:187], v[220:223], v[64:67]
	s_barrier
	s_setprio 0
	ds_read_b128 v[188:191], v153 offset:49152
	ds_read_b128 v[192:195], v153 offset:50176
	ds_read_b128 v[200:203], v153 offset:51200
	ds_read_b128 v[204:207], v153 offset:52224
	ds_read_b128 v[208:211], v153 offset:53248
	ds_read_b128 v[212:215], v153 offset:54272
	ds_read_b128 v[216:219], v153 offset:55296
	ds_read_b128 v[220:223], v153 offset:56320
	global_load_lds_dwordx4 v130, s[98:99]
	s_add_i32 m0, s72, 0x2000
	s_add_u32 s70, s70, 0x80080
	s_addc_u32 s71, s71, 0
	s_add_i32 s72, s84, s1
	global_load_lds_dwordx4 v134, s[98:99]
	s_mov_b32 m0, s72
	s_nop 0
	global_load_lds_dwordx4 v130, s[70:71]
	s_add_i32 m0, s72, 0x2000
	s_nop 0
	global_load_lds_dwordx4 v134, s[70:71]
	s_mov_b32 m0, s67
	s_nop 0
	global_load_lds_dwordx4 v128, s[100:101]
	s_mov_b32 m0, s74
	s_nop 0
	global_load_lds_dwordx4 v132, s[100:101]
	s_add_i32 s82, s82, 2
	s_add_u32 s68, s68, 0x100
	s_addc_u32 s69, s69, 0
	s_add_u32 s80, s80, 0x100
	s_addc_u32 s81, s81, 0
	s_cmp_gt_u32 s82, 29
	s_waitcnt vmcnt(8)
	s_waitcnt lgkmcnt(0)
	s_setprio 1
	s_barrier
	v_mfma_f32_16x16x32_bf16 v[60:63], v[156:159], v[188:191], v[60:63]
	v_mfma_f32_16x16x32_bf16 v[56:59], v[164:167], v[188:191], v[56:59]
	v_mfma_f32_16x16x32_bf16 v[44:47], v[156:159], v[200:203], v[44:47]
	v_mfma_f32_16x16x32_bf16 v[40:43], v[164:167], v[200:203], v[40:43]
	v_mfma_f32_16x16x32_bf16 v[32:35], v[156:159], v[208:211], v[32:35]
	v_mfma_f32_16x16x32_bf16 v[24:27], v[164:167], v[208:211], v[24:27]
	v_mfma_f32_16x16x32_bf16 v[16:19], v[156:159], v[216:219], v[16:19]
	v_mfma_f32_16x16x32_bf16 v[8:11], v[164:167], v[216:219], v[8:11]
	v_mfma_f32_16x16x32_bf16 v[60:63], v[160:163], v[192:195], v[60:63]
	v_mfma_f32_16x16x32_bf16 v[56:59], v[168:171], v[192:195], v[56:59]
	v_mfma_f32_16x16x32_bf16 v[44:47], v[160:163], v[204:207], v[44:47]
	v_mfma_f32_16x16x32_bf16 v[40:43], v[168:171], v[204:207], v[40:43]
	v_mfma_f32_16x16x32_bf16 v[32:35], v[160:163], v[212:215], v[32:35]
	v_mfma_f32_16x16x32_bf16 v[24:27], v[168:171], v[212:215], v[24:27]
	v_mfma_f32_16x16x32_bf16 v[16:19], v[160:163], v[220:223], v[16:19]
	v_mfma_f32_16x16x32_bf16 v[8:11], v[168:171], v[220:223], v[8:11]
	v_mfma_f32_16x16x32_bf16 v[52:55], v[172:175], v[188:191], v[52:55]
	v_mfma_f32_16x16x32_bf16 v[48:51], v[180:183], v[188:191], v[48:51]
	v_mfma_f32_16x16x32_bf16 v[36:39], v[172:175], v[200:203], v[36:39]
	v_mfma_f32_16x16x32_bf16 v[28:31], v[180:183], v[200:203], v[28:31]
	v_mfma_f32_16x16x32_bf16 v[20:23], v[172:175], v[208:211], v[20:23]
	v_mfma_f32_16x16x32_bf16 v[12:15], v[180:183], v[208:211], v[12:15]
	v_mfma_f32_16x16x32_bf16 v[4:7], v[172:175], v[216:219], v[4:7]
	v_mfma_f32_16x16x32_bf16 v[0:3], v[180:183], v[216:219], v[0:3]
	v_mfma_f32_16x16x32_bf16 v[52:55], v[176:179], v[192:195], v[52:55]
	v_mfma_f32_16x16x32_bf16 v[48:51], v[184:187], v[192:195], v[48:51]
	v_mfma_f32_16x16x32_bf16 v[36:39], v[176:179], v[204:207], v[36:39]
	v_mfma_f32_16x16x32_bf16 v[28:31], v[184:187], v[204:207], v[28:31]
	v_mfma_f32_16x16x32_bf16 v[20:23], v[176:179], v[212:215], v[20:23]
	v_mfma_f32_16x16x32_bf16 v[12:15], v[184:187], v[212:215], v[12:15]
	v_mfma_f32_16x16x32_bf16 v[4:7], v[176:179], v[220:223], v[4:7]
	v_mfma_f32_16x16x32_bf16 v[0:3], v[184:187], v[220:223], v[0:3]
	s_barrier
	s_setprio 0
	s_cbranch_scc0 .LBB0_735
	s_and_b64 vcc, exec, s[38:39]
	s_cbranch_vccz .LBB0_738
	s_barrier

; #define PG8_STAGE(bufoff, gbase, voff) do { _Pragma("unroll") for (int _i = 0; _i < 2; ++_i) \
;         __builtin_amdgcn_global_load_lds((const unsigned*)((const char*)(gbase) + (voff)[_i]), (PG8_LAS unsigned*)(lds + (bufoff) + ldsw + _i * 8192), 16, 0, 0); } while (0)
; #define PG8_LDA(dst, b, h) do { _Pragma("unroll") for (int m = 0; m < 4; ++m) _Pragma("unroll") for (int k = 0; k < 2; ++k) dst[m][k] = *(const PG8_LAS bf16x8*)(lds + PG8_SA(b, h) + aoff + m * 2048 + k * 1024); } while (0)
; #define PG8_LDB(dst, b, h) do { _Pragma("unroll") for (int n = 0; n < 2; ++n) _Pragma("unroll") for (int k = 0; k < 2; ++k) dst[n][k] = *(const PG8_LAS bf16x8*)(lds + PG8_SB(b, h) + boff + n * 2048 + k * 1024); } while (0)
; #define PG8_MMA(ai, bj, At, Bt) do { __builtin_amdgcn_s_setprio(1); _Pragma("unroll") for (int m = 0; m < 4; ++m) _Pragma("unroll") for (int n = 0; n < 2; ++n) _Pragma("unroll") for (int k = 0; k < 2; ++k) \
;         acc[ai][bj][m][n] = __builtin_amdgcn_mfma_f32_16x16x32_bf16(Bt[n][k], At[m][k], acc[ai][bj][m][n], 0, 0, 0); __builtin_amdgcn_s_setprio(0); } while (0)
; #define PG8_WAIT_V(n) asm volatile("s_waitcnt vmcnt(" #n ")" ::: "memory")
; #define PG8_WAIT_L(n) asm volatile("s_waitcnt lgkmcnt(" #n ")" ::: "memory")
; #define PG8_BAR __builtin_amdgcn_s_barrier()
; template <class Epi, class Sched, bool ALIGN_EPI = false, bool SP2 = false>
; __device__ __forceinline__ void gemm_phase(PG8_LAS unsigned char* lds, const Gemm g, const Sched& S, const Epi& E) {
;     ...
;             const char* a1 = cA + (size_t)(t + 1) * kstep;
;             const char* a2 = last ? nA : cA + (size_t)(t + 2) * kstep; const char* b2 = last ? nB : cB + (size_t)(t + 2) * kstep;
;             const char* a3 = a2 + kstep; const char* b3 = b2 + kstep;
;             if (last && has_next) S.a_ready(nxt);
;             if constexpr (SP2) {
;             PG8_LDB(B0, 0, 0); PG8_LDB(B1, 0, 1); PG8_SCHED; PG8_LDA(At, 0, 0); PG8_STAGE(PG8_SA(1, 1), a1 + hstep, voffA);
;             PG8_WAIT_V(8); PG8_WAIT_L(0); PG8_BAR; PG8_MMA(0, 0, At, B0); PG8_MMA(0, 1, At, B1); PG8_BAR; PG8_SCHED;
;             PG8_LDA(At, 0, 1); PG8_STAGE(PG8_SB(0, 0), b2, voffB); PG8_STAGE(PG8_SB(0, 1), b2 + hstep, voffB); PG8_STAGE(PG8_SA(0, 0), a2, voffA);
;             PG8_WAIT_V(8); PG8_WAIT_L(0); PG8_BAR; PG8_MMA(1, 0, At, B0); PG8_MMA(1, 1, At, B1); PG8_BAR; PG8_SCHED;
.LBB0_759:
	ds_read_b128 v[152:155], v149
	ds_read_b128 v[156:159], v149 offset:1024
	ds_read_b128 v[160:163], v149 offset:2048
	ds_read_b128 v[164:167], v149 offset:3072
	ds_read_b128 v[168:171], v150
	ds_read_b128 v[172:175], v150 offset:1024
	ds_read_b128 v[176:179], v150 offset:2048
	ds_read_b128 v[180:183], v150 offset:3072
	s_add_i32 m0, s6, 0xc000
	ds_read_b128 v[184:187], v151
	ds_read_b128 v[188:191], v151 offset:1024
	ds_read_b128 v[192:195], v151 offset:2048
	ds_read_b128 v[200:203], v151 offset:3072
	ds_read_b128 v[204:207], v151 offset:4096
	ds_read_b128 v[208:211], v151 offset:5120
	ds_read_b128 v[212:215], v151 offset:6144
	ds_read_b128 v[216:219], v151 offset:7168
	global_load_lds_dwordx4 v138, s[68:69]
	s_add_i32 m0, s6, 0xe000
	s_nop 0
	global_load_lds_dwordx4 v140, s[68:69]
	s_add_u32 s70, s68, 0xfff80080
	s_addc_u32 s71, s69, -1
	s_cmp_eq_u32 s83, 28
	s_cselect_b32 s73, s25, s71
	s_cselect_b32 s72, s61, s70
	s_cselect_b32 s71, s49, s82
	s_cselect_b32 s70, s80, s81
	s_add_i32 s84, s78, s5
	s_mov_b32 m0, s84
	s_waitcnt vmcnt(8)
	s_waitcnt lgkmcnt(0)
	s_setprio 1
	s_barrier
	v_mfma_f32_16x16x32_bf16 v[124:127], v[152:155], v[184:187], v[124:127]
	v_mfma_f32_16x16x32_bf16 v[120:123], v[160:163], v[184:187], v[120:123]
	v_mfma_f32_16x16x32_bf16 v[112:115], v[152:155], v[192:195], v[112:115]
	v_mfma_f32_16x16x32_bf16 v[104:107], v[160:163], v[192:195], v[104:107]
	v_mfma_f32_16x16x32_bf16 v[100:103], v[152:155], v[204:207], v[100:103]
	v_mfma_f32_16x16x32_bf16 v[92:95], v[160:163], v[204:207], v[92:95]
	v_mfma_f32_16x16x32_bf16 v[84:87], v[152:155], v[212:215], v[84:87]
	v_mfma_f32_16x16x32_bf16 v[76:79], v[160:163], v[212:215], v[76:79]
	v_mfma_f32_16x16x32_bf16 v[124:127], v[156:159], v[188:191], v[124:127]
	v_mfma_f32_16x16x32_bf16 v[120:123], v[164:167], v[188:191], v[120:123]
	v_mfma_f32_16x16x32_bf16 v[112:115], v[156:159], v[200:203], v[112:115]
	v_mfma_f32_16x16x32_bf16 v[104:107], v[164:167], v[200:203], v[104:107]
	v_mfma_f32_16x16x32_bf16 v[100:103], v[156:159], v[208:211], v[100:103]
	v_mfma_f32_16x16x32_bf16 v[92:95], v[164:167], v[208:211], v[92:95]
	v_mfma_f32_16x16x32_bf16 v[84:87], v[156:159], v[216:219], v[84:87]
	v_mfma_f32_16x16x32_bf16 v[76:79], v[164:167], v[216:219], v[76:79]
	v_mfma_f32_16x16x32_bf16 v[116:119], v[168:171], v[184:187], v[116:119]
	v_mfma_f32_16x16x32_bf16 v[108:111], v[176:179], v[184:187], v[108:111]
	v_mfma_f32_16x16x32_bf16 v[96:99], v[168:171], v[192:195], v[96:99]
	v_mfma_f32_16x16x32_bf16 v[88:91], v[176:179], v[192:195], v[88:91]
	v_mfma_f32_16x16x32_bf16 v[80:83], v[168:171], v[204:207], v[80:83]
	v_mfma_f32_16x16x32_bf16 v[72:75], v[176:179], v[204:207], v[72:75]
	v_mfma_f32_16x16x32_bf16 v[68:71], v[168:171], v[212:215], v[68:71]
	v_mfma_f32_16x16x32_bf16 v[64:67], v[176:179], v[212:215], v[64:67]
	v_mfma_f32_16x16x32_bf16 v[116:119], v[172:175], v[188:191], v[116:119]
	v_mfma_f32_16x16x32_bf16 v[108:111], v[180:183], v[188:191], v[108:111]
	v_mfma_f32_16x16x32_bf16 v[96:99], v[172:175], v[200:203], v[96:99]
	v_mfma_f32_16x16x32_bf16 v[88:91], v[180:183], v[200:203], v[88:91]
	v_mfma_f32_16x16x32_bf16 v[80:83], v[172:175], v[208:211], v[80:83]
	v_mfma_f32_16x16x32_bf16 v[72:75], v[180:183], v[208:211], v[72:75]
	v_mfma_f32_16x16x32_bf16 v[68:71], v[172:175], v[216:219], v[68:71]
	v_mfma_f32_16x16x32_bf16 v[64:67], v[180:183], v[216:219], v[64:67]
	s_barrier
	s_setprio 0
	ds_read_b128 v[184:187], v151 offset:16384
	ds_read_b128 v[188:191], v151 offset:17408
	ds_read_b128 v[192:195], v151 offset:18432
	ds_read_b128 v[200:203], v151 offset:19456
	ds_read_b128 v[204:207], v151 offset:20480
	ds_read_b128 v[208:211], v151 offset:21504
	ds_read_b128 v[212:215], v151 offset:22528
	ds_read_b128 v[216:219], v151 offset:23552
	global_load_lds_dwordx4 v130, s[70:71]
	s_add_i32 m0, s84, 0x2000
	s_add_u32 s84, s70, 0x80000
	s_addc_u32 s85, s71, 0
	s_add_i32 s86, s79, s5
	global_load_lds_dwordx4 v134, s[70:71]
	s_mov_b32 m0, s86
	s_nop 0
	global_load_lds_dwordx4 v130, s[84:85]
	s_add_i32 m0, s86, 0x2000
	s_nop 0
	global_load_lds_dwordx4 v134, s[84:85]
	s_mov_b32 m0, s6
	s_nop 0
	global_load_lds_dwordx4 v128, s[72:73]
	s_mov_b32 m0, s7
	s_nop 0
	global_load_lds_dwordx4 v132, s[72:73]
	s_waitcnt vmcnt(8)
	s_waitcnt lgkmcnt(0)
	s_setprio 1
	s_barrier
	v_mfma_f32_16x16x32_bf16 v[60:63], v[152:155], v[184:187], v[60:63]
	v_mfma_f32_16x16x32_bf16 v[56:59], v[160:163], v[184:187], v[56:59]
	v_mfma_f32_16x16x32_bf16 v[52:55], v[152:155], v[192:195], v[52:55]
	v_mfma_f32_16x16x32_bf16 v[44:47], v[160:163], v[192:195], v[44:47]
	v_mfma_f32_16x16x32_bf16 v[36:39], v[152:155], v[204:207], v[36:39]
	v_mfma_f32_16x16x32_bf16 v[28:31], v[160:163], v[204:207], v[28:31]
	v_mfma_f32_16x16x32_bf16 v[20:23], v[152:155], v[212:215], v[20:23]
	v_mfma_f32_16x16x32_bf16 v[12:15], v[160:163], v[212:215], v[12:15]
	v_mfma_f32_16x16x32_bf16 v[60:63], v[156:159], v[188:191], v[60:63]
	v_mfma_f32_16x16x32_bf16 v[56:59], v[164:167], v[188:191], v[56:59]
	v_mfma_f32_16x16x32_bf16 v[52:55], v[156:159], v[200:203], v[52:55]
	v_mfma_f32_16x16x32_bf16 v[44:47], v[164:167], v[200:203], v[44:47]
	v_mfma_f32_16x16x32_bf16 v[36:39], v[156:159], v[208:211], v[36:39]
	v_mfma_f32_16x16x32_bf16 v[28:31], v[164:167], v[208:211], v[28:31]
	v_mfma_f32_16x16x32_bf16 v[20:23], v[156:159], v[216:219], v[20:23]
	v_mfma_f32_16x16x32_bf16 v[12:15], v[164:167], v[216:219], v[12:15]
	v_mfma_f32_16x16x32_bf16 v[48:51], v[168:171], v[184:187], v[48:51]
	v_mfma_f32_16x16x32_bf16 v[40:43], v[176:179], v[184:187], v[40:43]
	v_mfma_f32_16x16x32_bf16 v[32:35], v[168:171], v[192:195], v[32:35]
	v_mfma_f32_16x16x32_bf16 v[24:27], v[176:179], v[192:195], v[24:27]
	v_mfma_f32_16x16x32_bf16 v[16:19], v[168:171], v[204:207], v[16:19]
	v_mfma_f32_16x16x32_bf16 v[8:11], v[176:179], v[204:207], v[8:11]
	v_mfma_f32_16x16x32_bf16 v[4:7], v[168:171], v[212:215], v[4:7]
	v_mfma_f32_16x16x32_bf16 v[0:3], v[176:179], v[212:215], v[0:3]
	v_mfma_f32_16x16x32_bf16 v[48:51], v[172:175], v[188:191], v[48:51]
	v_mfma_f32_16x16x32_bf16 v[40:43], v[180:183], v[188:191], v[40:43]
	v_mfma_f32_16x16x32_bf16 v[32:35], v[172:175], v[200:203], v[32:35]
	v_mfma_f32_16x16x32_bf16 v[24:27], v[180:183], v[200:203], v[24:27]
	v_mfma_f32_16x16x32_bf16 v[16:19], v[172:175], v[208:211], v[16:19]
	v_mfma_f32_16x16x32_bf16 v[8:11], v[180:183], v[208:211], v[8:11]
	v_mfma_f32_16x16x32_bf16 v[4:7], v[172:175], v[216:219], v[4:7]
	v_mfma_f32_16x16x32_bf16 v[0:3], v[180:183], v[216:219], v[0:3]
	s_barrier
; #define PG8_STAGE(bufoff, gbase, voff) do { _Pragma("unroll") for (int _i = 0; _i < 2; ++_i) \
;         __builtin_amdgcn_global_load_lds((const unsigned*)((const char*)(gbase) + (voff)[_i]), (PG8_LAS unsigned*)(lds + (bufoff) + ldsw + _i * 8192), 16, 0, 0); } while (0)
; #define PG8_LDA(dst, b, h) do { _Pragma("unroll") for (int m = 0; m < 4; ++m) _Pragma("unroll") for (int k = 0; k < 2; ++k) dst[m][k] = *(const PG8_LAS bf16x8*)(lds + PG8_SA(b, h) + aoff + m * 2048 + k * 1024); } while (0)
; #define PG8_LDB(dst, b, h) do { _Pragma("unroll") for (int n = 0; n < 2; ++n) _Pragma("unroll") for (int k = 0; k < 2; ++k) dst[n][k] = *(const PG8_LAS bf16x8*)(lds + PG8_SB(b, h) + boff + n * 2048 + k * 1024); } while (0)
; #define PG8_MMA(ai, bj, At, Bt) do { __builtin_amdgcn_s_setprio(1); _Pragma("unroll") for (int m = 0; m < 4; ++m) _Pragma("unroll") for (int n = 0; n < 2; ++n) _Pragma("unroll") for (int k = 0; k < 2; ++k) \
;         acc[ai][bj][m][n] = __builtin_amdgcn_mfma_f32_16x16x32_bf16(Bt[n][k], At[m][k], acc[ai][bj][m][n], 0, 0, 0); __builtin_amdgcn_s_setprio(0); } while (0)
; #define PG8_WAIT_V(n) asm volatile("s_waitcnt vmcnt(" #n ")" ::: "memory")
; #define PG8_WAIT_L(n) asm volatile("s_waitcnt lgkmcnt(" #n ")" ::: "memory")
; #define PG8_BAR __builtin_amdgcn_s_barrier()
; #define PG8_SCHED __builtin_amdgcn_sched_barrier(0)
; template <class Epi, class Sched, bool ALIGN_EPI = false, bool SP2 = false>
; __device__ __forceinline__ void gemm_phase(PG8_LAS unsigned char* lds, const Gemm g, const Sched& S, const Epi& E) {
;     ...
;             PG8_LDB(B0, 1, 0); PG8_LDB(B1, 1, 1); PG8_SCHED; PG8_LDA(At, 1, 0); PG8_STAGE(PG8_SA(0, 1), a2 + hstep, voffA);
;             PG8_WAIT_V(8); PG8_WAIT_L(0); PG8_BAR; PG8_MMA(0, 0, At, B0); PG8_MMA(0, 1, At, B1); PG8_BAR; PG8_SCHED;
;             PG8_LDA(At, 1, 1); PG8_STAGE(PG8_SB(1, 0), b3, voffB); PG8_STAGE(PG8_SB(1, 1), b3 + hstep, voffB); PG8_STAGE(PG8_SA(1, 0), a3, voffA);
;             PG8_WAIT_V(8); PG8_WAIT_L(0); PG8_BAR; PG8_MMA(1, 0, At, B0); PG8_MMA(1, 1, At, B1); PG8_BAR; PG8_SCHED;
;     ...
;         if constexpr (ALIGN_EPI) { if (wr == 0) PG8_BAR; }
	s_setprio 0
	ds_read_b128 v[152:155], v198
	ds_read_b128 v[156:159], v198 offset:1024
	ds_read_b128 v[160:163], v198 offset:2048
	ds_read_b128 v[164:167], v198 offset:3072
	ds_read_b128 v[168:171], v199
	ds_read_b128 v[172:175], v199 offset:1024
	ds_read_b128 v[176:179], v199 offset:2048
	ds_read_b128 v[180:183], v199 offset:3072
	ds_read_b128 v[184:187], v151 offset:32768
	ds_read_b128 v[188:191], v151 offset:33792
	ds_read_b128 v[192:195], v151 offset:34816
	ds_read_b128 v[200:203], v151 offset:35840
	ds_read_b128 v[204:207], v151 offset:36864
	ds_read_b128 v[208:211], v151 offset:37888
	ds_read_b128 v[212:215], v151 offset:38912
	ds_read_b128 v[216:219], v151 offset:39936
	s_add_u32 s98, s72, 0x80000
	s_addc_u32 s99, s73, 0
	s_mov_b32 m0, s14
	s_add_u32 s100, s72, 0x80
	s_addc_u32 s101, s73, 0
	global_load_lds_dwordx4 v128, s[98:99]
	s_mov_b32 m0, s15
	s_nop 0
	global_load_lds_dwordx4 v132, s[98:99]
	s_add_i32 s84, 0, 0x18000
	s_add_i32 s85, 0, 0x1c000
	s_add_u32 s98, s70, 0x80
	s_addc_u32 s99, s71, 0
	s_add_i32 s72, s84, s5
	s_mov_b32 m0, s72
	s_waitcnt vmcnt(8)
	s_waitcnt lgkmcnt(0)
	s_setprio 1
	s_barrier
	v_mfma_f32_16x16x32_bf16 v[124:127], v[152:155], v[184:187], v[124:127]
	v_mfma_f32_16x16x32_bf16 v[120:123], v[160:163], v[184:187], v[120:123]
	v_mfma_f32_16x16x32_bf16 v[112:115], v[152:155], v[192:195], v[112:115]
	v_mfma_f32_16x16x32_bf16 v[104:107], v[160:163], v[192:195], v[104:107]
	v_mfma_f32_16x16x32_bf16 v[100:103], v[152:155], v[204:207], v[100:103]
	v_mfma_f32_16x16x32_bf16 v[92:95], v[160:163], v[204:207], v[92:95]
	v_mfma_f32_16x16x32_bf16 v[84:87], v[152:155], v[212:215], v[84:87]
	v_mfma_f32_16x16x32_bf16 v[76:79], v[160:163], v[212:215], v[76:79]
	v_mfma_f32_16x16x32_bf16 v[124:127], v[156:159], v[188:191], v[124:127]
	v_mfma_f32_16x16x32_bf16 v[120:123], v[164:167], v[188:191], v[120:123]
	v_mfma_f32_16x16x32_bf16 v[112:115], v[156:159], v[200:203], v[112:115]
	v_mfma_f32_16x16x32_bf16 v[104:107], v[164:167], v[200:203], v[104:107]
	v_mfma_f32_16x16x32_bf16 v[100:103], v[156:159], v[208:211], v[100:103]
	v_mfma_f32_16x16x32_bf16 v[92:95], v[164:167], v[208:211], v[92:95]
	v_mfma_f32_16x16x32_bf16 v[84:87], v[156:159], v[216:219], v[84:87]
	v_mfma_f32_16x16x32_bf16 v[76:79], v[164:167], v[216:219], v[76:79]
	v_mfma_f32_16x16x32_bf16 v[116:119], v[168:171], v[184:187], v[116:119]
	v_mfma_f32_16x16x32_bf16 v[108:111], v[176:179], v[184:187], v[108:111]
	v_mfma_f32_16x16x32_bf16 v[96:99], v[168:171], v[192:195], v[96:99]
	v_mfma_f32_16x16x32_bf16 v[88:91], v[176:179], v[192:195], v[88:91]
	v_mfma_f32_16x16x32_bf16 v[80:83], v[168:171], v[204:207], v[80:83]
	v_mfma_f32_16x16x32_bf16 v[72:75], v[176:179], v[204:207], v[72:75]
	v_mfma_f32_16x16x32_bf16 v[68:71], v[168:171], v[212:215], v[68:71]
	v_mfma_f32_16x16x32_bf16 v[64:67], v[176:179], v[212:215], v[64:67]
	v_mfma_f32_16x16x32_bf16 v[116:119], v[172:175], v[188:191], v[116:119]
	v_mfma_f32_16x16x32_bf16 v[108:111], v[180:183], v[188:191], v[108:111]
	v_mfma_f32_16x16x32_bf16 v[96:99], v[172:175], v[200:203], v[96:99]
	v_mfma_f32_16x16x32_bf16 v[88:91], v[180:183], v[200:203], v[88:91]
	v_mfma_f32_16x16x32_bf16 v[80:83], v[172:175], v[208:211], v[80:83]
	v_mfma_f32_16x16x32_bf16 v[72:75], v[180:183], v[208:211], v[72:75]
	v_mfma_f32_16x16x32_bf16 v[68:71], v[172:175], v[216:219], v[68:71]
	v_mfma_f32_16x16x32_bf16 v[64:67], v[180:183], v[216:219], v[64:67]
	s_barrier
	s_setprio 0
	ds_read_b128 v[184:187], v151 offset:49152
	ds_read_b128 v[188:191], v151 offset:50176
	ds_read_b128 v[192:195], v151 offset:51200
	ds_read_b128 v[200:203], v151 offset:52224
	ds_read_b128 v[204:207], v151 offset:53248
	ds_read_b128 v[208:211], v151 offset:54272
	ds_read_b128 v[212:215], v151 offset:55296
	ds_read_b128 v[216:219], v151 offset:56320
	global_load_lds_dwordx4 v130, s[98:99]
	s_add_i32 m0, s72, 0x2000
	s_add_u32 s70, s70, 0x80080
	s_addc_u32 s71, s71, 0
	s_add_i32 s72, s85, s5
	global_load_lds_dwordx4 v134, s[98:99]
	s_mov_b32 m0, s72
	s_nop 0
	global_load_lds_dwordx4 v130, s[70:71]
	s_add_i32 m0, s72, 0x2000
	s_nop 0
	global_load_lds_dwordx4 v134, s[70:71]
	s_mov_b32 m0, s74
	s_nop 0
	global_load_lds_dwordx4 v128, s[100:101]
	s_mov_b32 m0, s75
	s_nop 0
	global_load_lds_dwordx4 v132, s[100:101]
	s_add_i32 s83, s83, 2
	s_add_u32 s68, s68, 0x100
	s_addc_u32 s69, s69, 0
	s_add_u32 s81, s81, 0x100
	s_addc_u32 s82, s82, 0
	s_cmp_gt_u32 s83, 29
	s_waitcnt vmcnt(8)
	s_waitcnt lgkmcnt(0)
	s_setprio 1
	s_barrier
	v_mfma_f32_16x16x32_bf16 v[60:63], v[152:155], v[184:187], v[60:63]
	v_mfma_f32_16x16x32_bf16 v[56:59], v[160:163], v[184:187], v[56:59]
	v_mfma_f32_16x16x32_bf16 v[52:55], v[152:155], v[192:195], v[52:55]
	v_mfma_f32_16x16x32_bf16 v[44:47], v[160:163], v[192:195], v[44:47]
	v_mfma_f32_16x16x32_bf16 v[36:39], v[152:155], v[204:207], v[36:39]
	v_mfma_f32_16x16x32_bf16 v[28:31], v[160:163], v[204:207], v[28:31]
	v_mfma_f32_16x16x32_bf16 v[20:23], v[152:155], v[212:215], v[20:23]
	v_mfma_f32_16x16x32_bf16 v[12:15], v[160:163], v[212:215], v[12:15]
	v_mfma_f32_16x16x32_bf16 v[60:63], v[156:159], v[188:191], v[60:63]
	v_mfma_f32_16x16x32_bf16 v[56:59], v[164:167], v[188:191], v[56:59]
	v_mfma_f32_16x16x32_bf16 v[52:55], v[156:159], v[200:203], v[52:55]
	v_mfma_f32_16x16x32_bf16 v[44:47], v[164:167], v[200:203], v[44:47]
	v_mfma_f32_16x16x32_bf16 v[36:39], v[156:159], v[208:211], v[36:39]
	v_mfma_f32_16x16x32_bf16 v[28:31], v[164:167], v[208:211], v[28:31]
	v_mfma_f32_16x16x32_bf16 v[20:23], v[156:159], v[216:219], v[20:23]
	v_mfma_f32_16x16x32_bf16 v[12:15], v[164:167], v[216:219], v[12:15]
	v_mfma_f32_16x16x32_bf16 v[48:51], v[168:171], v[184:187], v[48:51]
	v_mfma_f32_16x16x32_bf16 v[40:43], v[176:179], v[184:187], v[40:43]
	v_mfma_f32_16x16x32_bf16 v[32:35], v[168:171], v[192:195], v[32:35]
	v_mfma_f32_16x16x32_bf16 v[24:27], v[176:179], v[192:195], v[24:27]
	v_mfma_f32_16x16x32_bf16 v[16:19], v[168:171], v[204:207], v[16:19]
	v_mfma_f32_16x16x32_bf16 v[8:11], v[176:179], v[204:207], v[8:11]
	v_mfma_f32_16x16x32_bf16 v[4:7], v[168:171], v[212:215], v[4:7]
	v_mfma_f32_16x16x32_bf16 v[0:3], v[176:179], v[212:215], v[0:3]
	v_mfma_f32_16x16x32_bf16 v[48:51], v[172:175], v[188:191], v[48:51]
	v_mfma_f32_16x16x32_bf16 v[40:43], v[180:183], v[188:191], v[40:43]
	v_mfma_f32_16x16x32_bf16 v[32:35], v[172:175], v[200:203], v[32:35]
	v_mfma_f32_16x16x32_bf16 v[24:27], v[180:183], v[200:203], v[24:27]
	v_mfma_f32_16x16x32_bf16 v[16:19], v[172:175], v[208:211], v[16:19]
	v_mfma_f32_16x16x32_bf16 v[8:11], v[180:183], v[208:211], v[8:11]
	v_mfma_f32_16x16x32_bf16 v[4:7], v[172:175], v[216:219], v[4:7]
	v_mfma_f32_16x16x32_bf16 v[0:3], v[180:183], v[216:219], v[0:3]
	s_barrier
	s_setprio 0
	s_cbranch_scc0 .LBB0_759
	s_and_b64 vcc, exec, s[46:47]
	s_cbranch_vccz .LBB0_762
	s_barrier

; #define PG8_STAGE(bufoff, gbase, voff) do { _Pragma("unroll") for (int _i = 0; _i < 2; ++_i) \
;         __builtin_amdgcn_global_load_lds((const unsigned*)((const char*)(gbase) + (voff)[_i]), (PG8_LAS unsigned*)(lds + (bufoff) + ldsw + _i * 8192), 16, 0, 0); } while (0)
; #define PG8_LDA(dst, b, h) do { _Pragma("unroll") for (int m = 0; m < 4; ++m) _Pragma("unroll") for (int k = 0; k < 2; ++k) dst[m][k] = *(const PG8_LAS bf16x8*)(lds + PG8_SA(b, h) + aoff + m * 2048 + k * 1024); } while (0)
; #define PG8_LDB(dst, b, h) do { _Pragma("unroll") for (int n = 0; n < 2; ++n) _Pragma("unroll") for (int k = 0; k < 2; ++k) dst[n][k] = *(const PG8_LAS bf16x8*)(lds + PG8_SB(b, h) + boff + n * 2048 + k * 1024); } while (0)
; #define PG8_MMA(ai, bj, At, Bt) do { __builtin_amdgcn_s_setprio(1); _Pragma("unroll") for (int m = 0; m < 4; ++m) _Pragma("unroll") for (int n = 0; n < 2; ++n) _Pragma("unroll") for (int k = 0; k < 2; ++k) \
;         acc[ai][bj][m][n] = __builtin_amdgcn_mfma_f32_16x16x32_bf16(Bt[n][k], At[m][k], acc[ai][bj][m][n], 0, 0, 0); __builtin_amdgcn_s_setprio(0); } while (0)
; #define PG8_WAIT_V(n) asm volatile("s_waitcnt vmcnt(" #n ")" ::: "memory")
; #define PG8_WAIT_L(n) asm volatile("s_waitcnt lgkmcnt(" #n ")" ::: "memory")
; #define PG8_BAR __builtin_amdgcn_s_barrier()
; template <class Epi, class Sched, bool ALIGN_EPI = false, bool SP2 = false>
; __device__ __forceinline__ void gemm_phase(PG8_LAS unsigned char* lds, const Gemm g, const Sched& S, const Epi& E) {
;     ...
;             const char* a1 = cA + (size_t)(t + 1) * kstep;
;             const char* a2 = last ? nA : cA + (size_t)(t + 2) * kstep; const char* b2 = last ? nB : cB + (size_t)(t + 2) * kstep;
;             const char* a3 = a2 + kstep; const char* b3 = b2 + kstep;
;             if (last && has_next) S.a_ready(nxt);
;             if constexpr (SP2) {
;             PG8_LDB(B0, 0, 0); PG8_LDB(B1, 0, 1); PG8_SCHED; PG8_LDA(At, 0, 0); PG8_STAGE(PG8_SA(1, 1), a1 + hstep, voffA);
;             PG8_WAIT_V(8); PG8_WAIT_L(0); PG8_BAR; PG8_MMA(0, 0, At, B0); PG8_MMA(0, 1, At, B1); PG8_BAR; PG8_SCHED;
;             PG8_LDA(At, 0, 1); PG8_STAGE(PG8_SB(0, 0), b2, voffB); PG8_STAGE(PG8_SB(0, 1), b2 + hstep, voffB); PG8_STAGE(PG8_SA(0, 0), a2, voffA);
;             PG8_WAIT_V(8); PG8_WAIT_L(0); PG8_BAR; PG8_MMA(1, 0, At, B0); PG8_MMA(1, 1, At, B1); PG8_BAR; PG8_SCHED;
.LBB0_1053:
	ds_read_b128 v[128:131], v202
	ds_read_b128 v[132:135], v202 offset:1024
	ds_read_b128 v[136:139], v202 offset:2048
	ds_read_b128 v[140:143], v202 offset:3072
	ds_read_b128 v[144:147], v203
	ds_read_b128 v[148:151], v203 offset:1024
	ds_read_b128 v[152:155], v203 offset:2048
	ds_read_b128 v[156:159], v203 offset:3072
	s_add_i32 m0, s3, 0xc000
	ds_read_b128 v[160:163], v204
	ds_read_b128 v[164:167], v204 offset:1024
	ds_read_b128 v[184:187], v204 offset:2048
	ds_read_b128 v[188:191], v204 offset:3072
	ds_read_b128 v[192:195], v204 offset:4096
	ds_read_b128 v[206:209], v204 offset:5120
	ds_read_b128 v[210:213], v204 offset:6144
	ds_read_b128 v[214:217], v204 offset:7168
	global_load_lds_dwordx4 v176, s[60:61]
	s_add_i32 m0, s3, 0xe000
	s_nop 0
	global_load_lds_dwordx4 v178, s[60:61]
	s_add_u32 s62, s60, 0xfff80080
	s_addc_u32 s63, s61, -1
	s_cmp_eq_u32 s72, 28
	s_cselect_b32 s65, s25, s63
	s_cselect_b32 s64, s43, s62
	s_cselect_b32 s63, s39, s71
	s_cselect_b32 s62, s69, s70
	s_add_i32 s73, s67, s1
	s_mov_b32 m0, s73
	s_waitcnt vmcnt(8)
	s_waitcnt lgkmcnt(0)
	s_setprio 1
	s_barrier
	v_mfma_f32_16x16x32_bf16 v[124:127], v[128:131], v[160:163], v[124:127]
	v_mfma_f32_16x16x32_bf16 v[120:123], v[136:139], v[160:163], v[120:123]
	v_mfma_f32_16x16x32_bf16 v[116:119], v[128:131], v[184:187], v[116:119]
	v_mfma_f32_16x16x32_bf16 v[108:111], v[136:139], v[184:187], v[108:111]
	v_mfma_f32_16x16x32_bf16 v[92:95], v[128:131], v[192:195], v[92:95]
	v_mfma_f32_16x16x32_bf16 v[88:91], v[136:139], v[192:195], v[88:91]
	v_mfma_f32_16x16x32_bf16 v[76:79], v[128:131], v[210:213], v[76:79]
	v_mfma_f32_16x16x32_bf16 v[72:75], v[136:139], v[210:213], v[72:75]
	v_mfma_f32_16x16x32_bf16 v[124:127], v[132:135], v[164:167], v[124:127]
	v_mfma_f32_16x16x32_bf16 v[120:123], v[140:143], v[164:167], v[120:123]
	v_mfma_f32_16x16x32_bf16 v[116:119], v[132:135], v[188:191], v[116:119]
	v_mfma_f32_16x16x32_bf16 v[108:111], v[140:143], v[188:191], v[108:111]
	v_mfma_f32_16x16x32_bf16 v[92:95], v[132:135], v[206:209], v[92:95]
	v_mfma_f32_16x16x32_bf16 v[88:91], v[140:143], v[206:209], v[88:91]
	v_mfma_f32_16x16x32_bf16 v[76:79], v[132:135], v[214:217], v[76:79]
	v_mfma_f32_16x16x32_bf16 v[72:75], v[140:143], v[214:217], v[72:75]
	v_mfma_f32_16x16x32_bf16 v[112:115], v[144:147], v[160:163], v[112:115]
	v_mfma_f32_16x16x32_bf16 v[104:107], v[152:155], v[160:163], v[104:107]
	v_mfma_f32_16x16x32_bf16 v[100:103], v[144:147], v[184:187], v[100:103]
	v_mfma_f32_16x16x32_bf16 v[96:99], v[152:155], v[184:187], v[96:99]
	v_mfma_f32_16x16x32_bf16 v[84:87], v[144:147], v[192:195], v[84:87]
	v_mfma_f32_16x16x32_bf16 v[80:83], v[152:155], v[192:195], v[80:83]
	v_mfma_f32_16x16x32_bf16 v[68:71], v[144:147], v[210:213], v[68:71]
	v_mfma_f32_16x16x32_bf16 v[64:67], v[152:155], v[210:213], v[64:67]
	v_mfma_f32_16x16x32_bf16 v[112:115], v[148:151], v[164:167], v[112:115]
	v_mfma_f32_16x16x32_bf16 v[104:107], v[156:159], v[164:167], v[104:107]
	v_mfma_f32_16x16x32_bf16 v[100:103], v[148:151], v[188:191], v[100:103]
	v_mfma_f32_16x16x32_bf16 v[96:99], v[156:159], v[188:191], v[96:99]
	v_mfma_f32_16x16x32_bf16 v[84:87], v[148:151], v[206:209], v[84:87]
	v_mfma_f32_16x16x32_bf16 v[80:83], v[156:159], v[206:209], v[80:83]
	v_mfma_f32_16x16x32_bf16 v[68:71], v[148:151], v[214:217], v[68:71]
	v_mfma_f32_16x16x32_bf16 v[64:67], v[156:159], v[214:217], v[64:67]
	s_barrier
	s_setprio 0
	ds_read_b128 v[160:163], v204 offset:16384
	ds_read_b128 v[164:167], v204 offset:17408
	ds_read_b128 v[184:187], v204 offset:18432
	ds_read_b128 v[188:191], v204 offset:19456
	ds_read_b128 v[192:195], v204 offset:20480
	ds_read_b128 v[206:209], v204 offset:21504
	ds_read_b128 v[210:213], v204 offset:22528
	ds_read_b128 v[214:217], v204 offset:23552
	global_load_lds_dwordx4 v170, s[62:63]
	s_add_i32 m0, s73, 0x2000
	s_add_u32 s74, s62, 0x80000
	s_addc_u32 s75, s63, 0
	s_add_i32 s73, s68, s1
	global_load_lds_dwordx4 v174, s[62:63]
	s_mov_b32 m0, s73
	s_nop 0
	global_load_lds_dwordx4 v170, s[74:75]
	s_add_i32 m0, s73, 0x2000
	s_nop 0
	global_load_lds_dwordx4 v174, s[74:75]
	s_mov_b32 m0, s3
	s_nop 0
	global_load_lds_dwordx4 v168, s[64:65]
	s_mov_b32 m0, s4
	s_nop 0
	global_load_lds_dwordx4 v172, s[64:65]
	s_waitcnt vmcnt(8)
	s_waitcnt lgkmcnt(0)
	s_setprio 1
	s_barrier
	v_mfma_f32_16x16x32_bf16 v[60:63], v[128:131], v[160:163], v[60:63]
	v_mfma_f32_16x16x32_bf16 v[56:59], v[136:139], v[160:163], v[56:59]
	v_mfma_f32_16x16x32_bf16 v[44:47], v[128:131], v[184:187], v[44:47]
	v_mfma_f32_16x16x32_bf16 v[40:43], v[136:139], v[184:187], v[40:43]
	v_mfma_f32_16x16x32_bf16 v[28:31], v[128:131], v[192:195], v[28:31]
	v_mfma_f32_16x16x32_bf16 v[24:27], v[136:139], v[192:195], v[24:27]
	v_mfma_f32_16x16x32_bf16 v[12:15], v[128:131], v[210:213], v[12:15]
	v_mfma_f32_16x16x32_bf16 v[8:11], v[136:139], v[210:213], v[8:11]
	v_mfma_f32_16x16x32_bf16 v[60:63], v[132:135], v[164:167], v[60:63]
	v_mfma_f32_16x16x32_bf16 v[56:59], v[140:143], v[164:167], v[56:59]
	v_mfma_f32_16x16x32_bf16 v[44:47], v[132:135], v[188:191], v[44:47]
	v_mfma_f32_16x16x32_bf16 v[40:43], v[140:143], v[188:191], v[40:43]
	v_mfma_f32_16x16x32_bf16 v[28:31], v[132:135], v[206:209], v[28:31]
	v_mfma_f32_16x16x32_bf16 v[24:27], v[140:143], v[206:209], v[24:27]
	v_mfma_f32_16x16x32_bf16 v[12:15], v[132:135], v[214:217], v[12:15]
	v_mfma_f32_16x16x32_bf16 v[8:11], v[140:143], v[214:217], v[8:11]
	v_mfma_f32_16x16x32_bf16 v[52:55], v[144:147], v[160:163], v[52:55]
	v_mfma_f32_16x16x32_bf16 v[48:51], v[152:155], v[160:163], v[48:51]
	v_mfma_f32_16x16x32_bf16 v[36:39], v[144:147], v[184:187], v[36:39]
	v_mfma_f32_16x16x32_bf16 v[32:35], v[152:155], v[184:187], v[32:35]
	v_mfma_f32_16x16x32_bf16 v[20:23], v[144:147], v[192:195], v[20:23]
	v_mfma_f32_16x16x32_bf16 v[16:19], v[152:155], v[192:195], v[16:19]
	v_mfma_f32_16x16x32_bf16 v[4:7], v[144:147], v[210:213], v[4:7]
	v_mfma_f32_16x16x32_bf16 v[0:3], v[152:155], v[210:213], v[0:3]
	v_mfma_f32_16x16x32_bf16 v[52:55], v[148:151], v[164:167], v[52:55]
	v_mfma_f32_16x16x32_bf16 v[48:51], v[156:159], v[164:167], v[48:51]
	v_mfma_f32_16x16x32_bf16 v[36:39], v[148:151], v[188:191], v[36:39]
	v_mfma_f32_16x16x32_bf16 v[32:35], v[156:159], v[188:191], v[32:35]
	v_mfma_f32_16x16x32_bf16 v[20:23], v[148:151], v[206:209], v[20:23]
	v_mfma_f32_16x16x32_bf16 v[16:19], v[156:159], v[206:209], v[16:19]
	v_mfma_f32_16x16x32_bf16 v[4:7], v[148:151], v[214:217], v[4:7]
	v_mfma_f32_16x16x32_bf16 v[0:3], v[156:159], v[214:217], v[0:3]
	s_barrier
; #define PG8_STAGE(bufoff, gbase, voff) do { _Pragma("unroll") for (int _i = 0; _i < 2; ++_i) \
;         __builtin_amdgcn_global_load_lds((const unsigned*)((const char*)(gbase) + (voff)[_i]), (PG8_LAS unsigned*)(lds + (bufoff) + ldsw + _i * 8192), 16, 0, 0); } while (0)
; #define PG8_LDA(dst, b, h) do { _Pragma("unroll") for (int m = 0; m < 4; ++m) _Pragma("unroll") for (int k = 0; k < 2; ++k) dst[m][k] = *(const PG8_LAS bf16x8*)(lds + PG8_SA(b, h) + aoff + m * 2048 + k * 1024); } while (0)
; #define PG8_LDB(dst, b, h) do { _Pragma("unroll") for (int n = 0; n < 2; ++n) _Pragma("unroll") for (int k = 0; k < 2; ++k) dst[n][k] = *(const PG8_LAS bf16x8*)(lds + PG8_SB(b, h) + boff + n * 2048 + k * 1024); } while (0)
; #define PG8_MMA(ai, bj, At, Bt) do { __builtin_amdgcn_s_setprio(1); _Pragma("unroll") for (int m = 0; m < 4; ++m) _Pragma("unroll") for (int n = 0; n < 2; ++n) _Pragma("unroll") for (int k = 0; k < 2; ++k) \
;         acc[ai][bj][m][n] = __builtin_amdgcn_mfma_f32_16x16x32_bf16(Bt[n][k], At[m][k], acc[ai][bj][m][n], 0, 0, 0); __builtin_amdgcn_s_setprio(0); } while (0)
; #define PG8_WAIT_V(n) asm volatile("s_waitcnt vmcnt(" #n ")" ::: "memory")
; #define PG8_WAIT_L(n) asm volatile("s_waitcnt lgkmcnt(" #n ")" ::: "memory")
; #define PG8_BAR __builtin_amdgcn_s_barrier()
; #define PG8_SCHED __builtin_amdgcn_sched_barrier(0)
; template <class Epi, class Sched, bool ALIGN_EPI = false, bool SP2 = false>
; __device__ __forceinline__ void gemm_phase(PG8_LAS unsigned char* lds, const Gemm g, const Sched& S, const Epi& E) {
;     ...
;             PG8_LDB(B0, 1, 0); PG8_LDB(B1, 1, 1); PG8_SCHED; PG8_LDA(At, 1, 0); PG8_STAGE(PG8_SA(0, 1), a2 + hstep, voffA);
;             PG8_WAIT_V(8); PG8_WAIT_L(0); PG8_BAR; PG8_MMA(0, 0, At, B0); PG8_MMA(0, 1, At, B1); PG8_BAR; PG8_SCHED;
;             PG8_LDA(At, 1, 1); PG8_STAGE(PG8_SB(1, 0), b3, voffB); PG8_STAGE(PG8_SB(1, 1), b3 + hstep, voffB); PG8_STAGE(PG8_SA(1, 0), a3, voffA);
;             PG8_WAIT_V(8); PG8_WAIT_L(0); PG8_BAR; PG8_MMA(1, 0, At, B0); PG8_MMA(1, 1, At, B1); PG8_BAR; PG8_SCHED;
;     ...
;         if constexpr (ALIGN_EPI) { if (wr == 0) PG8_BAR; }
	s_setprio 0
	ds_read_b128 v[128:131], v218
	ds_read_b128 v[132:135], v218 offset:1024
	ds_read_b128 v[136:139], v218 offset:2048
	ds_read_b128 v[140:143], v218 offset:3072
	ds_read_b128 v[144:147], v219
	ds_read_b128 v[148:151], v219 offset:1024
	ds_read_b128 v[152:155], v219 offset:2048
	ds_read_b128 v[156:159], v219 offset:3072
	ds_read_b128 v[160:163], v204 offset:32768
	ds_read_b128 v[164:167], v204 offset:33792
	ds_read_b128 v[184:187], v204 offset:34816
	ds_read_b128 v[188:191], v204 offset:35840
	ds_read_b128 v[192:195], v204 offset:36864
	ds_read_b128 v[206:209], v204 offset:37888
	ds_read_b128 v[210:213], v204 offset:38912
	ds_read_b128 v[214:217], v204 offset:39936
	s_add_u32 s98, s64, 0x80000
	s_addc_u32 s99, s65, 0
	s_mov_b32 m0, s5
	s_add_u32 s100, s64, 0x80
	s_addc_u32 s101, s65, 0
	global_load_lds_dwordx4 v168, s[98:99]
	s_mov_b32 m0, s14
	s_nop 0
	global_load_lds_dwordx4 v172, s[98:99]
	s_add_i32 s73, 0, 0x18000
	s_add_i32 s74, 0, 0x1c000
	s_add_u32 s98, s62, 0x80
	s_addc_u32 s99, s63, 0
	s_add_i32 s64, s73, s1
	s_mov_b32 m0, s64
	s_waitcnt vmcnt(8)
	s_waitcnt lgkmcnt(0)
	s_setprio 1
	s_barrier
	v_mfma_f32_16x16x32_bf16 v[124:127], v[128:131], v[160:163], v[124:127]
	v_mfma_f32_16x16x32_bf16 v[120:123], v[136:139], v[160:163], v[120:123]
	v_mfma_f32_16x16x32_bf16 v[116:119], v[128:131], v[184:187], v[116:119]
	v_mfma_f32_16x16x32_bf16 v[108:111], v[136:139], v[184:187], v[108:111]
	v_mfma_f32_16x16x32_bf16 v[92:95], v[128:131], v[192:195], v[92:95]
	v_mfma_f32_16x16x32_bf16 v[88:91], v[136:139], v[192:195], v[88:91]
	v_mfma_f32_16x16x32_bf16 v[76:79], v[128:131], v[210:213], v[76:79]
	v_mfma_f32_16x16x32_bf16 v[72:75], v[136:139], v[210:213], v[72:75]
	v_mfma_f32_16x16x32_bf16 v[124:127], v[132:135], v[164:167], v[124:127]
	v_mfma_f32_16x16x32_bf16 v[120:123], v[140:143], v[164:167], v[120:123]
	v_mfma_f32_16x16x32_bf16 v[116:119], v[132:135], v[188:191], v[116:119]
	v_mfma_f32_16x16x32_bf16 v[108:111], v[140:143], v[188:191], v[108:111]
	v_mfma_f32_16x16x32_bf16 v[92:95], v[132:135], v[206:209], v[92:95]
	v_mfma_f32_16x16x32_bf16 v[88:91], v[140:143], v[206:209], v[88:91]
	v_mfma_f32_16x16x32_bf16 v[76:79], v[132:135], v[214:217], v[76:79]
	v_mfma_f32_16x16x32_bf16 v[72:75], v[140:143], v[214:217], v[72:75]
	v_mfma_f32_16x16x32_bf16 v[112:115], v[144:147], v[160:163], v[112:115]
	v_mfma_f32_16x16x32_bf16 v[104:107], v[152:155], v[160:163], v[104:107]
	v_mfma_f32_16x16x32_bf16 v[100:103], v[144:147], v[184:187], v[100:103]
	v_mfma_f32_16x16x32_bf16 v[96:99], v[152:155], v[184:187], v[96:99]
	v_mfma_f32_16x16x32_bf16 v[84:87], v[144:147], v[192:195], v[84:87]
	v_mfma_f32_16x16x32_bf16 v[80:83], v[152:155], v[192:195], v[80:83]
	v_mfma_f32_16x16x32_bf16 v[68:71], v[144:147], v[210:213], v[68:71]
	v_mfma_f32_16x16x32_bf16 v[64:67], v[152:155], v[210:213], v[64:67]
	v_mfma_f32_16x16x32_bf16 v[112:115], v[148:151], v[164:167], v[112:115]
	v_mfma_f32_16x16x32_bf16 v[104:107], v[156:159], v[164:167], v[104:107]
	v_mfma_f32_16x16x32_bf16 v[100:103], v[148:151], v[188:191], v[100:103]
	v_mfma_f32_16x16x32_bf16 v[96:99], v[156:159], v[188:191], v[96:99]
	v_mfma_f32_16x16x32_bf16 v[84:87], v[148:151], v[206:209], v[84:87]
	v_mfma_f32_16x16x32_bf16 v[80:83], v[156:159], v[206:209], v[80:83]
	v_mfma_f32_16x16x32_bf16 v[68:71], v[148:151], v[214:217], v[68:71]
	v_mfma_f32_16x16x32_bf16 v[64:67], v[156:159], v[214:217], v[64:67]
	s_barrier
	s_setprio 0
	ds_read_b128 v[160:163], v204 offset:49152
	ds_read_b128 v[164:167], v204 offset:50176
	ds_read_b128 v[184:187], v204 offset:51200
	ds_read_b128 v[188:191], v204 offset:52224
	ds_read_b128 v[192:195], v204 offset:53248
	ds_read_b128 v[206:209], v204 offset:54272
	ds_read_b128 v[210:213], v204 offset:55296
	ds_read_b128 v[214:217], v204 offset:56320
	global_load_lds_dwordx4 v170, s[98:99]
	s_add_i32 m0, s64, 0x2000
	s_add_u32 s62, s62, 0x80080
	s_addc_u32 s63, s63, 0
	s_add_i32 s64, s74, s1
	global_load_lds_dwordx4 v174, s[98:99]
	s_mov_b32 m0, s64
	s_nop 0
	global_load_lds_dwordx4 v170, s[62:63]
	s_add_i32 m0, s64, 0x2000
	s_nop 0
	global_load_lds_dwordx4 v174, s[62:63]
	s_mov_b32 m0, s33
	s_nop 0
	global_load_lds_dwordx4 v168, s[100:101]
	s_mov_b32 m0, s35
	s_nop 0
	global_load_lds_dwordx4 v172, s[100:101]
	s_add_i32 s72, s72, 2
	s_add_u32 s60, s60, 0x100
	s_addc_u32 s61, s61, 0
	s_add_u32 s70, s70, 0x100
	s_addc_u32 s71, s71, 0
	s_cmp_gt_u32 s72, 29
	s_waitcnt vmcnt(8)
	s_waitcnt lgkmcnt(0)
	s_setprio 1
	s_barrier
	v_mfma_f32_16x16x32_bf16 v[60:63], v[128:131], v[160:163], v[60:63]
	v_mfma_f32_16x16x32_bf16 v[56:59], v[136:139], v[160:163], v[56:59]
	v_mfma_f32_16x16x32_bf16 v[44:47], v[128:131], v[184:187], v[44:47]
	v_mfma_f32_16x16x32_bf16 v[40:43], v[136:139], v[184:187], v[40:43]
	v_mfma_f32_16x16x32_bf16 v[28:31], v[128:131], v[192:195], v[28:31]
	v_mfma_f32_16x16x32_bf16 v[24:27], v[136:139], v[192:195], v[24:27]
	v_mfma_f32_16x16x32_bf16 v[12:15], v[128:131], v[210:213], v[12:15]
	v_mfma_f32_16x16x32_bf16 v[8:11], v[136:139], v[210:213], v[8:11]
	v_mfma_f32_16x16x32_bf16 v[60:63], v[132:135], v[164:167], v[60:63]
	v_mfma_f32_16x16x32_bf16 v[56:59], v[140:143], v[164:167], v[56:59]
	v_mfma_f32_16x16x32_bf16 v[44:47], v[132:135], v[188:191], v[44:47]
	v_mfma_f32_16x16x32_bf16 v[40:43], v[140:143], v[188:191], v[40:43]
	v_mfma_f32_16x16x32_bf16 v[28:31], v[132:135], v[206:209], v[28:31]
	v_mfma_f32_16x16x32_bf16 v[24:27], v[140:143], v[206:209], v[24:27]
	v_mfma_f32_16x16x32_bf16 v[12:15], v[132:135], v[214:217], v[12:15]
	v_mfma_f32_16x16x32_bf16 v[8:11], v[140:143], v[214:217], v[8:11]
	v_mfma_f32_16x16x32_bf16 v[52:55], v[144:147], v[160:163], v[52:55]
	v_mfma_f32_16x16x32_bf16 v[48:51], v[152:155], v[160:163], v[48:51]
	v_mfma_f32_16x16x32_bf16 v[36:39], v[144:147], v[184:187], v[36:39]
	v_mfma_f32_16x16x32_bf16 v[32:35], v[152:155], v[184:187], v[32:35]
	v_mfma_f32_16x16x32_bf16 v[20:23], v[144:147], v[192:195], v[20:23]
	v_mfma_f32_16x16x32_bf16 v[16:19], v[152:155], v[192:195], v[16:19]
	v_mfma_f32_16x16x32_bf16 v[4:7], v[144:147], v[210:213], v[4:7]
	v_mfma_f32_16x16x32_bf16 v[0:3], v[152:155], v[210:213], v[0:3]
	v_mfma_f32_16x16x32_bf16 v[52:55], v[148:151], v[164:167], v[52:55]
	v_mfma_f32_16x16x32_bf16 v[48:51], v[156:159], v[164:167], v[48:51]
	v_mfma_f32_16x16x32_bf16 v[36:39], v[148:151], v[188:191], v[36:39]
	v_mfma_f32_16x16x32_bf16 v[32:35], v[156:159], v[188:191], v[32:35]
	v_mfma_f32_16x16x32_bf16 v[20:23], v[148:151], v[206:209], v[20:23]
	v_mfma_f32_16x16x32_bf16 v[16:19], v[156:159], v[206:209], v[16:19]
	v_mfma_f32_16x16x32_bf16 v[4:7], v[148:151], v[214:217], v[4:7]
	v_mfma_f32_16x16x32_bf16 v[0:3], v[156:159], v[214:217], v[0:3]
	s_barrier
	s_setprio 0
	s_cbranch_scc0 .LBB0_1053
	s_and_b64 vcc, exec, s[16:17]
	s_cbranch_vccz .LBB0_1056
	s_barrier

; #define PG8_STAGE(bufoff, gbase, voff) do { _Pragma("unroll") for (int _i = 0; _i < 2; ++_i) \
;         __builtin_amdgcn_global_load_lds((const unsigned*)((const char*)(gbase) + (voff)[_i]), (PG8_LAS unsigned*)(lds + (bufoff) + ldsw + _i * 8192), 16, 0, 0); } while (0)
; #define PG8_LDA(dst, b, h) do { _Pragma("unroll") for (int m = 0; m < 4; ++m) _Pragma("unroll") for (int k = 0; k < 2; ++k) dst[m][k] = *(const PG8_LAS bf16x8*)(lds + PG8_SA(b, h) + aoff + m * 2048 + k * 1024); } while (0)
; #define PG8_LDB(dst, b, h) do { _Pragma("unroll") for (int n = 0; n < 2; ++n) _Pragma("unroll") for (int k = 0; k < 2; ++k) dst[n][k] = *(const PG8_LAS bf16x8*)(lds + PG8_SB(b, h) + boff + n * 2048 + k * 1024); } while (0)
; #define PG8_MMA(ai, bj, At, Bt) do { __builtin_amdgcn_s_setprio(1); _Pragma("unroll") for (int m = 0; m < 4; ++m) _Pragma("unroll") for (int n = 0; n < 2; ++n) _Pragma("unroll") for (int k = 0; k < 2; ++k) \
;         acc[ai][bj][m][n] = __builtin_amdgcn_mfma_f32_16x16x32_bf16(Bt[n][k], At[m][k], acc[ai][bj][m][n], 0, 0, 0); __builtin_amdgcn_s_setprio(0); } while (0)
; #define PG8_WAIT_V(n) asm volatile("s_waitcnt vmcnt(" #n ")" ::: "memory")
; #define PG8_WAIT_L(n) asm volatile("s_waitcnt lgkmcnt(" #n ")" ::: "memory")
; #define PG8_BAR __builtin_amdgcn_s_barrier()
; template <class Epi, class Sched, bool ALIGN_EPI = false, bool SP2 = false>
; __device__ __forceinline__ void gemm_phase(PG8_LAS unsigned char* lds, const Gemm g, const Sched& S, const Epi& E) {
;     ...
;             const char* a1 = cA + (size_t)(t + 1) * kstep;
;             const char* a2 = last ? nA : cA + (size_t)(t + 2) * kstep; const char* b2 = last ? nB : cB + (size_t)(t + 2) * kstep;
;             const char* a3 = a2 + kstep; const char* b3 = b2 + kstep;
;             if (last && has_next) S.a_ready(nxt);
;             if constexpr (SP2) {
;             PG8_LDB(B0, 0, 0); PG8_LDB(B1, 0, 1); PG8_SCHED; PG8_LDA(At, 0, 0); PG8_STAGE(PG8_SA(1, 1), a1 + hstep, voffA);
;             PG8_WAIT_V(8); PG8_WAIT_L(0); PG8_BAR; PG8_MMA(0, 0, At, B0); PG8_MMA(0, 1, At, B1); PG8_BAR; PG8_SCHED;
;             PG8_LDA(At, 0, 1); PG8_STAGE(PG8_SB(0, 0), b2, voffB); PG8_STAGE(PG8_SB(0, 1), b2 + hstep, voffB); PG8_STAGE(PG8_SA(0, 0), a2, voffA);
;             PG8_WAIT_V(8); PG8_WAIT_L(0); PG8_BAR; PG8_MMA(1, 0, At, B0); PG8_MMA(1, 1, At, B1); PG8_BAR; PG8_SCHED;
.LBB0_1184:
	ds_read_b128 v[152:155], v149
	ds_read_b128 v[156:159], v149 offset:1024
	ds_read_b128 v[160:163], v149 offset:2048
	ds_read_b128 v[164:167], v149 offset:3072
	ds_read_b128 v[168:171], v150
	ds_read_b128 v[172:175], v150 offset:1024
	ds_read_b128 v[176:179], v150 offset:2048
	ds_read_b128 v[180:183], v150 offset:3072
	s_add_i32 m0, s3, 0xc000
	ds_read_b128 v[184:187], v151
	ds_read_b128 v[188:191], v151 offset:1024
	ds_read_b128 v[192:195], v151 offset:2048
	ds_read_b128 v[196:199], v151 offset:3072
	ds_read_b128 v[200:203], v151 offset:4096
	ds_read_b128 v[204:207], v151 offset:5120
	ds_read_b128 v[208:211], v151 offset:6144
	ds_read_b128 v[212:215], v151 offset:7168
	global_load_lds_dwordx4 v136, s[50:51]
	s_add_i32 m0, s3, 0xe000
	s_nop 0
	global_load_lds_dwordx4 v138, s[50:51]
	s_add_u32 s58, s50, 0xfff80080
	s_addc_u32 s59, s51, -1
	s_cmp_eq_u32 s74, 28
	s_cselect_b32 s61, s25, s59
	s_cselect_b32 s60, s41, s58
	s_cselect_b32 s59, s39, s73
	s_cselect_b32 s58, s71, s72
	s_add_i32 s75, s65, s1
	s_mov_b32 m0, s75
	s_waitcnt vmcnt(8)
	s_waitcnt lgkmcnt(0)
	s_setprio 1
	s_barrier
	v_mfma_f32_16x16x32_bf16 v[124:127], v[152:155], v[184:187], v[124:127]
	v_mfma_f32_16x16x32_bf16 v[120:123], v[160:163], v[184:187], v[120:123]
	v_mfma_f32_16x16x32_bf16 v[108:111], v[152:155], v[192:195], v[108:111]
	v_mfma_f32_16x16x32_bf16 v[104:107], v[160:163], v[192:195], v[104:107]
	v_mfma_f32_16x16x32_bf16 v[92:95], v[152:155], v[200:203], v[92:95]
	v_mfma_f32_16x16x32_bf16 v[88:91], v[160:163], v[200:203], v[88:91]
	v_mfma_f32_16x16x32_bf16 v[76:79], v[152:155], v[208:211], v[76:79]
	v_mfma_f32_16x16x32_bf16 v[72:75], v[160:163], v[208:211], v[72:75]
	v_mfma_f32_16x16x32_bf16 v[124:127], v[156:159], v[188:191], v[124:127]
	v_mfma_f32_16x16x32_bf16 v[120:123], v[164:167], v[188:191], v[120:123]
	v_mfma_f32_16x16x32_bf16 v[108:111], v[156:159], v[196:199], v[108:111]
	v_mfma_f32_16x16x32_bf16 v[104:107], v[164:167], v[196:199], v[104:107]
	v_mfma_f32_16x16x32_bf16 v[92:95], v[156:159], v[204:207], v[92:95]
	v_mfma_f32_16x16x32_bf16 v[88:91], v[164:167], v[204:207], v[88:91]
	v_mfma_f32_16x16x32_bf16 v[76:79], v[156:159], v[212:215], v[76:79]
	v_mfma_f32_16x16x32_bf16 v[72:75], v[164:167], v[212:215], v[72:75]
	v_mfma_f32_16x16x32_bf16 v[116:119], v[168:171], v[184:187], v[116:119]
	v_mfma_f32_16x16x32_bf16 v[112:115], v[176:179], v[184:187], v[112:115]
	v_mfma_f32_16x16x32_bf16 v[100:103], v[168:171], v[192:195], v[100:103]
	v_mfma_f32_16x16x32_bf16 v[96:99], v[176:179], v[192:195], v[96:99]
	v_mfma_f32_16x16x32_bf16 v[84:87], v[168:171], v[200:203], v[84:87]
	v_mfma_f32_16x16x32_bf16 v[80:83], v[176:179], v[200:203], v[80:83]
	v_mfma_f32_16x16x32_bf16 v[68:71], v[168:171], v[208:211], v[68:71]
	v_mfma_f32_16x16x32_bf16 v[64:67], v[176:179], v[208:211], v[64:67]
	v_mfma_f32_16x16x32_bf16 v[116:119], v[172:175], v[188:191], v[116:119]
	v_mfma_f32_16x16x32_bf16 v[112:115], v[180:183], v[188:191], v[112:115]
	v_mfma_f32_16x16x32_bf16 v[100:103], v[172:175], v[196:199], v[100:103]
	v_mfma_f32_16x16x32_bf16 v[96:99], v[180:183], v[196:199], v[96:99]
	v_mfma_f32_16x16x32_bf16 v[84:87], v[172:175], v[204:207], v[84:87]
	v_mfma_f32_16x16x32_bf16 v[80:83], v[180:183], v[204:207], v[80:83]
	v_mfma_f32_16x16x32_bf16 v[68:71], v[172:175], v[212:215], v[68:71]
	v_mfma_f32_16x16x32_bf16 v[64:67], v[180:183], v[212:215], v[64:67]
	s_barrier
	s_setprio 0
	ds_read_b128 v[184:187], v151 offset:16384
	ds_read_b128 v[188:191], v151 offset:17408
	ds_read_b128 v[192:195], v151 offset:18432
	ds_read_b128 v[196:199], v151 offset:19456
	ds_read_b128 v[200:203], v151 offset:20480
	ds_read_b128 v[204:207], v151 offset:21504
	ds_read_b128 v[208:211], v151 offset:22528
	ds_read_b128 v[212:215], v151 offset:23552
	global_load_lds_dwordx4 v130, s[58:59]
	s_add_i32 m0, s75, 0x2000
	s_add_u32 s76, s58, 0x80000
	s_addc_u32 s77, s59, 0
	s_add_i32 s75, s66, s1
	global_load_lds_dwordx4 v134, s[58:59]
	s_mov_b32 m0, s75
	s_nop 0
	global_load_lds_dwordx4 v130, s[76:77]
	s_add_i32 m0, s75, 0x2000
	s_nop 0
	global_load_lds_dwordx4 v134, s[76:77]
	s_mov_b32 m0, s3
	s_nop 0
	global_load_lds_dwordx4 v128, s[60:61]
	s_mov_b32 m0, s14
	s_nop 0
	global_load_lds_dwordx4 v132, s[60:61]
	s_waitcnt vmcnt(8)
	s_waitcnt lgkmcnt(0)
	s_setprio 1
	s_barrier
	v_mfma_f32_16x16x32_bf16 v[60:63], v[152:155], v[184:187], v[60:63]
	v_mfma_f32_16x16x32_bf16 v[56:59], v[160:163], v[184:187], v[56:59]
	v_mfma_f32_16x16x32_bf16 v[44:47], v[152:155], v[192:195], v[44:47]
	v_mfma_f32_16x16x32_bf16 v[40:43], v[160:163], v[192:195], v[40:43]
	v_mfma_f32_16x16x32_bf16 v[28:31], v[152:155], v[200:203], v[28:31]
	v_mfma_f32_16x16x32_bf16 v[24:27], v[160:163], v[200:203], v[24:27]
	v_mfma_f32_16x16x32_bf16 v[12:15], v[152:155], v[208:211], v[12:15]
	v_mfma_f32_16x16x32_bf16 v[8:11], v[160:163], v[208:211], v[8:11]
	v_mfma_f32_16x16x32_bf16 v[60:63], v[156:159], v[188:191], v[60:63]
	v_mfma_f32_16x16x32_bf16 v[56:59], v[164:167], v[188:191], v[56:59]
	v_mfma_f32_16x16x32_bf16 v[44:47], v[156:159], v[196:199], v[44:47]
	v_mfma_f32_16x16x32_bf16 v[40:43], v[164:167], v[196:199], v[40:43]
	v_mfma_f32_16x16x32_bf16 v[28:31], v[156:159], v[204:207], v[28:31]
	v_mfma_f32_16x16x32_bf16 v[24:27], v[164:167], v[204:207], v[24:27]
	v_mfma_f32_16x16x32_bf16 v[12:15], v[156:159], v[212:215], v[12:15]
	v_mfma_f32_16x16x32_bf16 v[8:11], v[164:167], v[212:215], v[8:11]
	v_mfma_f32_16x16x32_bf16 v[52:55], v[168:171], v[184:187], v[52:55]
	v_mfma_f32_16x16x32_bf16 v[48:51], v[176:179], v[184:187], v[48:51]
	v_mfma_f32_16x16x32_bf16 v[36:39], v[168:171], v[192:195], v[36:39]
	v_mfma_f32_16x16x32_bf16 v[32:35], v[176:179], v[192:195], v[32:35]
	v_mfma_f32_16x16x32_bf16 v[20:23], v[168:171], v[200:203], v[20:23]
	v_mfma_f32_16x16x32_bf16 v[16:19], v[176:179], v[200:203], v[16:19]
	v_mfma_f32_16x16x32_bf16 v[4:7], v[168:171], v[208:211], v[4:7]
	v_mfma_f32_16x16x32_bf16 v[0:3], v[176:179], v[208:211], v[0:3]
	v_mfma_f32_16x16x32_bf16 v[52:55], v[172:175], v[188:191], v[52:55]
	v_mfma_f32_16x16x32_bf16 v[48:51], v[180:183], v[188:191], v[48:51]
	v_mfma_f32_16x16x32_bf16 v[36:39], v[172:175], v[196:199], v[36:39]
	v_mfma_f32_16x16x32_bf16 v[32:35], v[180:183], v[196:199], v[32:35]
	v_mfma_f32_16x16x32_bf16 v[20:23], v[172:175], v[204:207], v[20:23]
	v_mfma_f32_16x16x32_bf16 v[16:19], v[180:183], v[204:207], v[16:19]
	v_mfma_f32_16x16x32_bf16 v[4:7], v[172:175], v[212:215], v[4:7]
	v_mfma_f32_16x16x32_bf16 v[0:3], v[180:183], v[212:215], v[0:3]
	s_barrier
; #define PG8_STAGE(bufoff, gbase, voff) do { _Pragma("unroll") for (int _i = 0; _i < 2; ++_i) \
;         __builtin_amdgcn_global_load_lds((const unsigned*)((const char*)(gbase) + (voff)[_i]), (PG8_LAS unsigned*)(lds + (bufoff) + ldsw + _i * 8192), 16, 0, 0); } while (0)
; #define PG8_LDA(dst, b, h) do { _Pragma("unroll") for (int m = 0; m < 4; ++m) _Pragma("unroll") for (int k = 0; k < 2; ++k) dst[m][k] = *(const PG8_LAS bf16x8*)(lds + PG8_SA(b, h) + aoff + m * 2048 + k * 1024); } while (0)
; #define PG8_LDB(dst, b, h) do { _Pragma("unroll") for (int n = 0; n < 2; ++n) _Pragma("unroll") for (int k = 0; k < 2; ++k) dst[n][k] = *(const PG8_LAS bf16x8*)(lds + PG8_SB(b, h) + boff + n * 2048 + k * 1024); } while (0)
; #define PG8_MMA(ai, bj, At, Bt) do { __builtin_amdgcn_s_setprio(1); _Pragma("unroll") for (int m = 0; m < 4; ++m) _Pragma("unroll") for (int n = 0; n < 2; ++n) _Pragma("unroll") for (int k = 0; k < 2; ++k) \
;         acc[ai][bj][m][n] = __builtin_amdgcn_mfma_f32_16x16x32_bf16(Bt[n][k], At[m][k], acc[ai][bj][m][n], 0, 0, 0); __builtin_amdgcn_s_setprio(0); } while (0)
; #define PG8_WAIT_V(n) asm volatile("s_waitcnt vmcnt(" #n ")" ::: "memory")
; #define PG8_WAIT_L(n) asm volatile("s_waitcnt lgkmcnt(" #n ")" ::: "memory")
; #define PG8_BAR __builtin_amdgcn_s_barrier()
; #define PG8_SCHED __builtin_amdgcn_sched_barrier(0)
; template <class Epi, class Sched, bool ALIGN_EPI = false, bool SP2 = false>
; __device__ __forceinline__ void gemm_phase(PG8_LAS unsigned char* lds, const Gemm g, const Sched& S, const Epi& E) {
;     ...
;             PG8_LDB(B0, 1, 0); PG8_LDB(B1, 1, 1); PG8_SCHED; PG8_LDA(At, 1, 0); PG8_STAGE(PG8_SA(0, 1), a2 + hstep, voffA);
;             PG8_WAIT_V(8); PG8_WAIT_L(0); PG8_BAR; PG8_MMA(0, 0, At, B0); PG8_MMA(0, 1, At, B1); PG8_BAR; PG8_SCHED;
;             PG8_LDA(At, 1, 1); PG8_STAGE(PG8_SB(1, 0), b3, voffB); PG8_STAGE(PG8_SB(1, 1), b3 + hstep, voffB); PG8_STAGE(PG8_SA(1, 0), a3, voffA);
;             PG8_WAIT_V(8); PG8_WAIT_L(0); PG8_BAR; PG8_MMA(1, 0, At, B0); PG8_MMA(1, 1, At, B1); PG8_BAR; PG8_SCHED;
;     ...
;         if constexpr (ALIGN_EPI) { if (wr == 0) PG8_BAR; }
	s_setprio 0
	ds_read_b128 v[152:155], v216
	ds_read_b128 v[156:159], v216 offset:1024
	ds_read_b128 v[160:163], v216 offset:2048
	ds_read_b128 v[164:167], v216 offset:3072
	ds_read_b128 v[168:171], v217
	ds_read_b128 v[172:175], v217 offset:1024
	ds_read_b128 v[176:179], v217 offset:2048
	ds_read_b128 v[180:183], v217 offset:3072
	ds_read_b128 v[184:187], v151 offset:32768
	ds_read_b128 v[188:191], v151 offset:33792
	ds_read_b128 v[192:195], v151 offset:34816
	ds_read_b128 v[196:199], v151 offset:35840
	ds_read_b128 v[200:203], v151 offset:36864
	ds_read_b128 v[204:207], v151 offset:37888
	ds_read_b128 v[208:211], v151 offset:38912
	ds_read_b128 v[212:215], v151 offset:39936
	s_add_u32 s98, s60, 0x80000
	s_addc_u32 s99, s61, 0
	s_mov_b32 m0, s15
	s_add_u32 s100, s60, 0x80
	s_addc_u32 s101, s61, 0
	global_load_lds_dwordx4 v128, s[98:99]
	s_mov_b32 m0, s33
	s_nop 0
	global_load_lds_dwordx4 v132, s[98:99]
	s_add_i32 s75, 0, 0x18000
	s_add_i32 s76, 0, 0x1c000
	s_add_u32 s98, s58, 0x80
	s_addc_u32 s99, s59, 0
	s_add_i32 s60, s75, s1
	s_mov_b32 m0, s60
	s_waitcnt vmcnt(8)
	s_waitcnt lgkmcnt(0)
	s_setprio 1
	s_barrier
	v_mfma_f32_16x16x32_bf16 v[124:127], v[152:155], v[184:187], v[124:127]
	v_mfma_f32_16x16x32_bf16 v[120:123], v[160:163], v[184:187], v[120:123]
	v_mfma_f32_16x16x32_bf16 v[108:111], v[152:155], v[192:195], v[108:111]
	v_mfma_f32_16x16x32_bf16 v[104:107], v[160:163], v[192:195], v[104:107]
	v_mfma_f32_16x16x32_bf16 v[92:95], v[152:155], v[200:203], v[92:95]
	v_mfma_f32_16x16x32_bf16 v[88:91], v[160:163], v[200:203], v[88:91]
	v_mfma_f32_16x16x32_bf16 v[76:79], v[152:155], v[208:211], v[76:79]
	v_mfma_f32_16x16x32_bf16 v[72:75], v[160:163], v[208:211], v[72:75]
	v_mfma_f32_16x16x32_bf16 v[124:127], v[156:159], v[188:191], v[124:127]
	v_mfma_f32_16x16x32_bf16 v[120:123], v[164:167], v[188:191], v[120:123]
	v_mfma_f32_16x16x32_bf16 v[108:111], v[156:159], v[196:199], v[108:111]
	v_mfma_f32_16x16x32_bf16 v[104:107], v[164:167], v[196:199], v[104:107]
	v_mfma_f32_16x16x32_bf16 v[92:95], v[156:159], v[204:207], v[92:95]
	v_mfma_f32_16x16x32_bf16 v[88:91], v[164:167], v[204:207], v[88:91]
	v_mfma_f32_16x16x32_bf16 v[76:79], v[156:159], v[212:215], v[76:79]
	v_mfma_f32_16x16x32_bf16 v[72:75], v[164:167], v[212:215], v[72:75]
	v_mfma_f32_16x16x32_bf16 v[116:119], v[168:171], v[184:187], v[116:119]
	v_mfma_f32_16x16x32_bf16 v[112:115], v[176:179], v[184:187], v[112:115]
	v_mfma_f32_16x16x32_bf16 v[100:103], v[168:171], v[192:195], v[100:103]
	v_mfma_f32_16x16x32_bf16 v[96:99], v[176:179], v[192:195], v[96:99]
	v_mfma_f32_16x16x32_bf16 v[84:87], v[168:171], v[200:203], v[84:87]
	v_mfma_f32_16x16x32_bf16 v[80:83], v[176:179], v[200:203], v[80:83]
	v_mfma_f32_16x16x32_bf16 v[68:71], v[168:171], v[208:211], v[68:71]
	v_mfma_f32_16x16x32_bf16 v[64:67], v[176:179], v[208:211], v[64:67]
	v_mfma_f32_16x16x32_bf16 v[116:119], v[172:175], v[188:191], v[116:119]
	v_mfma_f32_16x16x32_bf16 v[112:115], v[180:183], v[188:191], v[112:115]
	v_mfma_f32_16x16x32_bf16 v[100:103], v[172:175], v[196:199], v[100:103]
	v_mfma_f32_16x16x32_bf16 v[96:99], v[180:183], v[196:199], v[96:99]
	v_mfma_f32_16x16x32_bf16 v[84:87], v[172:175], v[204:207], v[84:87]
	v_mfma_f32_16x16x32_bf16 v[80:83], v[180:183], v[204:207], v[80:83]
	v_mfma_f32_16x16x32_bf16 v[68:71], v[172:175], v[212:215], v[68:71]
	v_mfma_f32_16x16x32_bf16 v[64:67], v[180:183], v[212:215], v[64:67]
	s_barrier
	s_setprio 0
	ds_read_b128 v[184:187], v151 offset:49152
	ds_read_b128 v[188:191], v151 offset:50176
	ds_read_b128 v[192:195], v151 offset:51200
	ds_read_b128 v[196:199], v151 offset:52224
	ds_read_b128 v[200:203], v151 offset:53248
	ds_read_b128 v[204:207], v151 offset:54272
	ds_read_b128 v[208:211], v151 offset:55296
	ds_read_b128 v[212:215], v151 offset:56320
	global_load_lds_dwordx4 v130, s[98:99]
	s_add_i32 m0, s60, 0x2000
	s_add_u32 s58, s58, 0x80080
	s_addc_u32 s59, s59, 0
	s_add_i32 s60, s76, s1
	global_load_lds_dwordx4 v134, s[98:99]
	s_mov_b32 m0, s60
	s_nop 0
	global_load_lds_dwordx4 v130, s[58:59]
	s_add_i32 m0, s60, 0x2000
	s_nop 0
	global_load_lds_dwordx4 v134, s[58:59]
	s_mov_b32 m0, s49
	s_nop 0
	global_load_lds_dwordx4 v128, s[100:101]
	s_mov_b32 m0, s62
	s_nop 0
	global_load_lds_dwordx4 v132, s[100:101]
	s_add_i32 s74, s74, 2
	s_add_u32 s50, s50, 0x100
	s_addc_u32 s51, s51, 0
	s_add_u32 s72, s72, 0x100
	s_addc_u32 s73, s73, 0
	s_cmp_gt_u32 s74, 29
	s_waitcnt vmcnt(8)
	s_waitcnt lgkmcnt(0)
	s_setprio 1
	s_barrier
	v_mfma_f32_16x16x32_bf16 v[60:63], v[152:155], v[184:187], v[60:63]
	v_mfma_f32_16x16x32_bf16 v[56:59], v[160:163], v[184:187], v[56:59]
	v_mfma_f32_16x16x32_bf16 v[44:47], v[152:155], v[192:195], v[44:47]
	v_mfma_f32_16x16x32_bf16 v[40:43], v[160:163], v[192:195], v[40:43]
	v_mfma_f32_16x16x32_bf16 v[28:31], v[152:155], v[200:203], v[28:31]
	v_mfma_f32_16x16x32_bf16 v[24:27], v[160:163], v[200:203], v[24:27]
	v_mfma_f32_16x16x32_bf16 v[12:15], v[152:155], v[208:211], v[12:15]
	v_mfma_f32_16x16x32_bf16 v[8:11], v[160:163], v[208:211], v[8:11]
	v_mfma_f32_16x16x32_bf16 v[60:63], v[156:159], v[188:191], v[60:63]
	v_mfma_f32_16x16x32_bf16 v[56:59], v[164:167], v[188:191], v[56:59]
	v_mfma_f32_16x16x32_bf16 v[44:47], v[156:159], v[196:199], v[44:47]
	v_mfma_f32_16x16x32_bf16 v[40:43], v[164:167], v[196:199], v[40:43]
	v_mfma_f32_16x16x32_bf16 v[28:31], v[156:159], v[204:207], v[28:31]
	v_mfma_f32_16x16x32_bf16 v[24:27], v[164:167], v[204:207], v[24:27]
	v_mfma_f32_16x16x32_bf16 v[12:15], v[156:159], v[212:215], v[12:15]
	v_mfma_f32_16x16x32_bf16 v[8:11], v[164:167], v[212:215], v[8:11]
	v_mfma_f32_16x16x32_bf16 v[52:55], v[168:171], v[184:187], v[52:55]
	v_mfma_f32_16x16x32_bf16 v[48:51], v[176:179], v[184:187], v[48:51]
	v_mfma_f32_16x16x32_bf16 v[36:39], v[168:171], v[192:195], v[36:39]
	v_mfma_f32_16x16x32_bf16 v[32:35], v[176:179], v[192:195], v[32:35]
	v_mfma_f32_16x16x32_bf16 v[20:23], v[168:171], v[200:203], v[20:23]
	v_mfma_f32_16x16x32_bf16 v[16:19], v[176:179], v[200:203], v[16:19]
	v_mfma_f32_16x16x32_bf16 v[4:7], v[168:171], v[208:211], v[4:7]
	v_mfma_f32_16x16x32_bf16 v[0:3], v[176:179], v[208:211], v[0:3]
	v_mfma_f32_16x16x32_bf16 v[52:55], v[172:175], v[188:191], v[52:55]
	v_mfma_f32_16x16x32_bf16 v[48:51], v[180:183], v[188:191], v[48:51]
	v_mfma_f32_16x16x32_bf16 v[36:39], v[172:175], v[196:199], v[36:39]
	v_mfma_f32_16x16x32_bf16 v[32:35], v[180:183], v[196:199], v[32:35]
	v_mfma_f32_16x16x32_bf16 v[20:23], v[172:175], v[204:207], v[20:23]
	v_mfma_f32_16x16x32_bf16 v[16:19], v[180:183], v[204:207], v[16:19]
	v_mfma_f32_16x16x32_bf16 v[4:7], v[172:175], v[212:215], v[4:7]
	v_mfma_f32_16x16x32_bf16 v[0:3], v[180:183], v[212:215], v[0:3]
	s_barrier
	s_setprio 0
	s_cbranch_scc0 .LBB0_1184
	s_and_b64 vcc, exec, s[12:13]
	s_cbranch_vccz .LBB0_1187
	s_barrier

; #define PG8_STAGE(bufoff, gbase, voff) do { _Pragma("unroll") for (int _i = 0; _i < 2; ++_i) \
;         __builtin_amdgcn_global_load_lds((const unsigned*)((const char*)(gbase) + (voff)[_i]), (PG8_LAS unsigned*)(lds + (bufoff) + ldsw + _i * 8192), 16, 0, 0); } while (0)
; #define PG8_LDA(dst, b, h) do { _Pragma("unroll") for (int m = 0; m < 4; ++m) _Pragma("unroll") for (int k = 0; k < 2; ++k) dst[m][k] = *(const PG8_LAS bf16x8*)(lds + PG8_SA(b, h) + aoff + m * 2048 + k * 1024); } while (0)
; #define PG8_LDB(dst, b, h) do { _Pragma("unroll") for (int n = 0; n < 2; ++n) _Pragma("unroll") for (int k = 0; k < 2; ++k) dst[n][k] = *(const PG8_LAS bf16x8*)(lds + PG8_SB(b, h) + boff + n * 2048 + k * 1024); } while (0)
; #define PG8_MMA(ai, bj, At, Bt) do { __builtin_amdgcn_s_setprio(1); _Pragma("unroll") for (int m = 0; m < 4; ++m) _Pragma("unroll") for (int n = 0; n < 2; ++n) _Pragma("unroll") for (int k = 0; k < 2; ++k) \
;         acc[ai][bj][m][n] = __builtin_amdgcn_mfma_f32_16x16x32_bf16(Bt[n][k], At[m][k], acc[ai][bj][m][n], 0, 0, 0); __builtin_amdgcn_s_setprio(0); } while (0)
; #define PG8_WAIT_V(n) asm volatile("s_waitcnt vmcnt(" #n ")" ::: "memory")
; #define PG8_WAIT_L(n) asm volatile("s_waitcnt lgkmcnt(" #n ")" ::: "memory")
; #define PG8_BAR __builtin_amdgcn_s_barrier()
; template <class Epi, class Sched, bool ALIGN_EPI = false, bool SP2 = false>
; __device__ __forceinline__ void gemm_phase(PG8_LAS unsigned char* lds, const Gemm g, const Sched& S, const Epi& E) {
;     ...
;             const char* a1 = cA + (size_t)(t + 1) * kstep;
;             const char* a2 = last ? nA : cA + (size_t)(t + 2) * kstep; const char* b2 = last ? nB : cB + (size_t)(t + 2) * kstep;
;             const char* a3 = a2 + kstep; const char* b3 = b2 + kstep;
;             if (last && has_next) S.a_ready(nxt);
;             if constexpr (SP2) {
;             PG8_LDB(B0, 0, 0); PG8_LDB(B1, 0, 1); PG8_SCHED; PG8_LDA(At, 0, 0); PG8_STAGE(PG8_SA(1, 1), a1 + hstep, voffA);
;             PG8_WAIT_V(8); PG8_WAIT_L(0); PG8_BAR; PG8_MMA(0, 0, At, B0); PG8_MMA(0, 1, At, B1); PG8_BAR; PG8_SCHED;
;             PG8_LDA(At, 0, 1); PG8_STAGE(PG8_SB(0, 0), b2, voffB); PG8_STAGE(PG8_SB(0, 1), b2 + hstep, voffB); PG8_STAGE(PG8_SA(0, 0), a2, voffA);
;             PG8_WAIT_V(8); PG8_WAIT_L(0); PG8_BAR; PG8_MMA(1, 0, At, B0); PG8_MMA(1, 1, At, B1); PG8_BAR; PG8_SCHED;
.LBB0_1260:
	ds_read_b128 v[128:131], v202
	ds_read_b128 v[132:135], v202 offset:1024
	ds_read_b128 v[136:139], v202 offset:2048
	ds_read_b128 v[140:143], v202 offset:3072
	ds_read_b128 v[144:147], v203
	ds_read_b128 v[148:151], v203 offset:1024
	ds_read_b128 v[152:155], v203 offset:2048
	ds_read_b128 v[156:159], v203 offset:3072
	s_add_i32 m0, s14, 0xc000
	ds_read_b128 v[160:163], v204
	ds_read_b128 v[164:167], v204 offset:1024
	ds_read_b128 v[184:187], v204 offset:2048
	ds_read_b128 v[188:191], v204 offset:3072
	ds_read_b128 v[192:195], v204 offset:4096
	ds_read_b128 v[206:209], v204 offset:5120
	ds_read_b128 v[210:213], v204 offset:6144
	ds_read_b128 v[214:217], v204 offset:7168
	global_load_lds_dwordx4 v176, s[50:51]
	s_add_i32 m0, s14, 0xe000
	s_nop 0
	global_load_lds_dwordx4 v178, s[50:51]
	s_add_u32 s58, s50, 0xffe00080
	s_addc_u32 s59, s51, -1
	s_cmpk_eq_i32 s72, 0x7c
	s_cselect_b32 s61, s25, s59
	s_cselect_b32 s60, s41, s58
	s_cselect_b32 s59, s39, s71
	s_cselect_b32 s58, s69, s70
	s_add_i32 s73, s67, s1
	s_mov_b32 m0, s73
	s_waitcnt vmcnt(8)
	s_waitcnt lgkmcnt(0)
	s_setprio 1
	s_barrier
	v_mfma_f32_16x16x32_bf16 v[124:127], v[128:131], v[160:163], v[124:127]
	v_mfma_f32_16x16x32_bf16 v[120:123], v[136:139], v[160:163], v[120:123]
	v_mfma_f32_16x16x32_bf16 v[116:119], v[128:131], v[184:187], v[116:119]
	v_mfma_f32_16x16x32_bf16 v[108:111], v[136:139], v[184:187], v[108:111]
	v_mfma_f32_16x16x32_bf16 v[92:95], v[128:131], v[192:195], v[92:95]
	v_mfma_f32_16x16x32_bf16 v[88:91], v[136:139], v[192:195], v[88:91]
	v_mfma_f32_16x16x32_bf16 v[76:79], v[128:131], v[210:213], v[76:79]
	v_mfma_f32_16x16x32_bf16 v[72:75], v[136:139], v[210:213], v[72:75]
	v_mfma_f32_16x16x32_bf16 v[124:127], v[132:135], v[164:167], v[124:127]
	v_mfma_f32_16x16x32_bf16 v[120:123], v[140:143], v[164:167], v[120:123]
	v_mfma_f32_16x16x32_bf16 v[116:119], v[132:135], v[188:191], v[116:119]
	v_mfma_f32_16x16x32_bf16 v[108:111], v[140:143], v[188:191], v[108:111]
	v_mfma_f32_16x16x32_bf16 v[92:95], v[132:135], v[206:209], v[92:95]
	v_mfma_f32_16x16x32_bf16 v[88:91], v[140:143], v[206:209], v[88:91]
	v_mfma_f32_16x16x32_bf16 v[76:79], v[132:135], v[214:217], v[76:79]
	v_mfma_f32_16x16x32_bf16 v[72:75], v[140:143], v[214:217], v[72:75]
	v_mfma_f32_16x16x32_bf16 v[112:115], v[144:147], v[160:163], v[112:115]
	v_mfma_f32_16x16x32_bf16 v[104:107], v[152:155], v[160:163], v[104:107]
	v_mfma_f32_16x16x32_bf16 v[100:103], v[144:147], v[184:187], v[100:103]
	v_mfma_f32_16x16x32_bf16 v[96:99], v[152:155], v[184:187], v[96:99]
	v_mfma_f32_16x16x32_bf16 v[84:87], v[144:147], v[192:195], v[84:87]
	v_mfma_f32_16x16x32_bf16 v[80:83], v[152:155], v[192:195], v[80:83]
	v_mfma_f32_16x16x32_bf16 v[68:71], v[144:147], v[210:213], v[68:71]
	v_mfma_f32_16x16x32_bf16 v[64:67], v[152:155], v[210:213], v[64:67]
	v_mfma_f32_16x16x32_bf16 v[112:115], v[148:151], v[164:167], v[112:115]
	v_mfma_f32_16x16x32_bf16 v[104:107], v[156:159], v[164:167], v[104:107]
	v_mfma_f32_16x16x32_bf16 v[100:103], v[148:151], v[188:191], v[100:103]
	v_mfma_f32_16x16x32_bf16 v[96:99], v[156:159], v[188:191], v[96:99]
	v_mfma_f32_16x16x32_bf16 v[84:87], v[148:151], v[206:209], v[84:87]
	v_mfma_f32_16x16x32_bf16 v[80:83], v[156:159], v[206:209], v[80:83]
	v_mfma_f32_16x16x32_bf16 v[68:71], v[148:151], v[214:217], v[68:71]
	v_mfma_f32_16x16x32_bf16 v[64:67], v[156:159], v[214:217], v[64:67]
	s_barrier
	s_setprio 0
	ds_read_b128 v[160:163], v204 offset:16384
	ds_read_b128 v[164:167], v204 offset:17408
	ds_read_b128 v[184:187], v204 offset:18432
	ds_read_b128 v[188:191], v204 offset:19456
	ds_read_b128 v[192:195], v204 offset:20480
	ds_read_b128 v[206:209], v204 offset:21504
	ds_read_b128 v[210:213], v204 offset:22528
	ds_read_b128 v[214:217], v204 offset:23552
	global_load_lds_dwordx4 v170, s[58:59]
	s_add_i32 m0, s73, 0x2000
	s_add_u32 s74, s58, 0x200000
	s_addc_u32 s75, s59, 0
	s_add_i32 s73, s68, s1
	global_load_lds_dwordx4 v174, s[58:59]
	s_mov_b32 m0, s73
	s_nop 0
	global_load_lds_dwordx4 v170, s[74:75]
	s_add_i32 m0, s73, 0x2000
	s_nop 0
	global_load_lds_dwordx4 v174, s[74:75]
	s_mov_b32 m0, s14
	s_nop 0
	global_load_lds_dwordx4 v168, s[60:61]
	s_mov_b32 m0, s15
	s_nop 0
	global_load_lds_dwordx4 v172, s[60:61]
	s_waitcnt vmcnt(8)
	s_waitcnt lgkmcnt(0)
	s_setprio 1
	s_barrier
	v_mfma_f32_16x16x32_bf16 v[60:63], v[128:131], v[160:163], v[60:63]
	v_mfma_f32_16x16x32_bf16 v[56:59], v[136:139], v[160:163], v[56:59]
	v_mfma_f32_16x16x32_bf16 v[44:47], v[128:131], v[184:187], v[44:47]
	v_mfma_f32_16x16x32_bf16 v[40:43], v[136:139], v[184:187], v[40:43]
	v_mfma_f32_16x16x32_bf16 v[28:31], v[128:131], v[192:195], v[28:31]
	v_mfma_f32_16x16x32_bf16 v[24:27], v[136:139], v[192:195], v[24:27]
	v_mfma_f32_16x16x32_bf16 v[12:15], v[128:131], v[210:213], v[12:15]
	v_mfma_f32_16x16x32_bf16 v[8:11], v[136:139], v[210:213], v[8:11]
	v_mfma_f32_16x16x32_bf16 v[60:63], v[132:135], v[164:167], v[60:63]
	v_mfma_f32_16x16x32_bf16 v[56:59], v[140:143], v[164:167], v[56:59]
	v_mfma_f32_16x16x32_bf16 v[44:47], v[132:135], v[188:191], v[44:47]
	v_mfma_f32_16x16x32_bf16 v[40:43], v[140:143], v[188:191], v[40:43]
	v_mfma_f32_16x16x32_bf16 v[28:31], v[132:135], v[206:209], v[28:31]
	v_mfma_f32_16x16x32_bf16 v[24:27], v[140:143], v[206:209], v[24:27]
	v_mfma_f32_16x16x32_bf16 v[12:15], v[132:135], v[214:217], v[12:15]
	v_mfma_f32_16x16x32_bf16 v[8:11], v[140:143], v[214:217], v[8:11]
	v_mfma_f32_16x16x32_bf16 v[52:55], v[144:147], v[160:163], v[52:55]
	v_mfma_f32_16x16x32_bf16 v[48:51], v[152:155], v[160:163], v[48:51]
	v_mfma_f32_16x16x32_bf16 v[36:39], v[144:147], v[184:187], v[36:39]
	v_mfma_f32_16x16x32_bf16 v[32:35], v[152:155], v[184:187], v[32:35]
	v_mfma_f32_16x16x32_bf16 v[20:23], v[144:147], v[192:195], v[20:23]
	v_mfma_f32_16x16x32_bf16 v[16:19], v[152:155], v[192:195], v[16:19]
	v_mfma_f32_16x16x32_bf16 v[4:7], v[144:147], v[210:213], v[4:7]
	v_mfma_f32_16x16x32_bf16 v[0:3], v[152:155], v[210:213], v[0:3]
	v_mfma_f32_16x16x32_bf16 v[52:55], v[148:151], v[164:167], v[52:55]
	v_mfma_f32_16x16x32_bf16 v[48:51], v[156:159], v[164:167], v[48:51]
	v_mfma_f32_16x16x32_bf16 v[36:39], v[148:151], v[188:191], v[36:39]
	v_mfma_f32_16x16x32_bf16 v[32:35], v[156:159], v[188:191], v[32:35]
	v_mfma_f32_16x16x32_bf16 v[20:23], v[148:151], v[206:209], v[20:23]
	v_mfma_f32_16x16x32_bf16 v[16:19], v[156:159], v[206:209], v[16:19]
	v_mfma_f32_16x16x32_bf16 v[4:7], v[148:151], v[214:217], v[4:7]
	v_mfma_f32_16x16x32_bf16 v[0:3], v[156:159], v[214:217], v[0:3]
	s_barrier
; #define PG8_STAGE(bufoff, gbase, voff) do { _Pragma("unroll") for (int _i = 0; _i < 2; ++_i) \
;         __builtin_amdgcn_global_load_lds((const unsigned*)((const char*)(gbase) + (voff)[_i]), (PG8_LAS unsigned*)(lds + (bufoff) + ldsw + _i * 8192), 16, 0, 0); } while (0)
; #define PG8_LDA(dst, b, h) do { _Pragma("unroll") for (int m = 0; m < 4; ++m) _Pragma("unroll") for (int k = 0; k < 2; ++k) dst[m][k] = *(const PG8_LAS bf16x8*)(lds + PG8_SA(b, h) + aoff + m * 2048 + k * 1024); } while (0)
; #define PG8_LDB(dst, b, h) do { _Pragma("unroll") for (int n = 0; n < 2; ++n) _Pragma("unroll") for (int k = 0; k < 2; ++k) dst[n][k] = *(const PG8_LAS bf16x8*)(lds + PG8_SB(b, h) + boff + n * 2048 + k * 1024); } while (0)
; #define PG8_MMA(ai, bj, At, Bt) do { __builtin_amdgcn_s_setprio(1); _Pragma("unroll") for (int m = 0; m < 4; ++m) _Pragma("unroll") for (int n = 0; n < 2; ++n) _Pragma("unroll") for (int k = 0; k < 2; ++k) \
;         acc[ai][bj][m][n] = __builtin_amdgcn_mfma_f32_16x16x32_bf16(Bt[n][k], At[m][k], acc[ai][bj][m][n], 0, 0, 0); __builtin_amdgcn_s_setprio(0); } while (0)
; #define PG8_WAIT_V(n) asm volatile("s_waitcnt vmcnt(" #n ")" ::: "memory")
; #define PG8_WAIT_L(n) asm volatile("s_waitcnt lgkmcnt(" #n ")" ::: "memory")
; #define PG8_BAR __builtin_amdgcn_s_barrier()
; #define PG8_SCHED __builtin_amdgcn_sched_barrier(0)
; template <class Epi, class Sched, bool ALIGN_EPI = false, bool SP2 = false>
; __device__ __forceinline__ void gemm_phase(PG8_LAS unsigned char* lds, const Gemm g, const Sched& S, const Epi& E) {
;     ...
;             PG8_WAIT_V(8); PG8_WAIT_L(0); PG8_BAR; PG8_MMA(1, 0, At, B0); PG8_MMA(1, 1, At, B1); PG8_BAR; PG8_SCHED;
;             PG8_LDB(B0, 1, 0); PG8_LDB(B1, 1, 1); PG8_SCHED; PG8_LDA(At, 1, 0); PG8_STAGE(PG8_SA(0, 1), a2 + hstep, voffA);
;             PG8_WAIT_V(8); PG8_WAIT_L(0); PG8_BAR; PG8_MMA(0, 0, At, B0); PG8_MMA(0, 1, At, B1); PG8_BAR; PG8_SCHED;
;             PG8_LDA(At, 1, 1); PG8_STAGE(PG8_SB(1, 0), b3, voffB); PG8_STAGE(PG8_SB(1, 1), b3 + hstep, voffB); PG8_STAGE(PG8_SA(1, 0), a3, voffA);
;             PG8_WAIT_V(8); PG8_WAIT_L(0); PG8_BAR; PG8_MMA(1, 0, At, B0); PG8_MMA(1, 1, At, B1); PG8_BAR; PG8_SCHED;
	s_setprio 0
	ds_read_b128 v[128:131], v218
	ds_read_b128 v[132:135], v218 offset:1024
	ds_read_b128 v[136:139], v218 offset:2048
	ds_read_b128 v[140:143], v218 offset:3072
	ds_read_b128 v[144:147], v219
	ds_read_b128 v[148:151], v219 offset:1024
	ds_read_b128 v[152:155], v219 offset:2048
	ds_read_b128 v[156:159], v219 offset:3072
	ds_read_b128 v[160:163], v204 offset:32768
	ds_read_b128 v[164:167], v204 offset:33792
	ds_read_b128 v[184:187], v204 offset:34816
	ds_read_b128 v[188:191], v204 offset:35840
	ds_read_b128 v[192:195], v204 offset:36864
	ds_read_b128 v[206:209], v204 offset:37888
	ds_read_b128 v[210:213], v204 offset:38912
	ds_read_b128 v[214:217], v204 offset:39936
	s_add_u32 s98, s60, 0x200000
	s_addc_u32 s99, s61, 0
	s_mov_b32 m0, s33
	s_add_u32 s100, s60, 0x80
	s_addc_u32 s101, s61, 0
	global_load_lds_dwordx4 v168, s[98:99]
	s_mov_b32 m0, s49
	s_nop 0
	global_load_lds_dwordx4 v172, s[98:99]
	s_add_i32 s73, 0, 0x18000
	s_add_i32 s74, 0, 0x1c000
	s_add_u32 s98, s58, 0x80
	s_addc_u32 s99, s59, 0
	s_add_i32 s60, s73, s1
	s_mov_b32 m0, s60
	s_waitcnt vmcnt(8)
	s_waitcnt lgkmcnt(0)
	s_setprio 1
	s_barrier
	v_mfma_f32_16x16x32_bf16 v[124:127], v[128:131], v[160:163], v[124:127]
	v_mfma_f32_16x16x32_bf16 v[120:123], v[136:139], v[160:163], v[120:123]
	v_mfma_f32_16x16x32_bf16 v[116:119], v[128:131], v[184:187], v[116:119]
	v_mfma_f32_16x16x32_bf16 v[108:111], v[136:139], v[184:187], v[108:111]
	v_mfma_f32_16x16x32_bf16 v[92:95], v[128:131], v[192:195], v[92:95]
	v_mfma_f32_16x16x32_bf16 v[88:91], v[136:139], v[192:195], v[88:91]
	v_mfma_f32_16x16x32_bf16 v[76:79], v[128:131], v[210:213], v[76:79]
	v_mfma_f32_16x16x32_bf16 v[72:75], v[136:139], v[210:213], v[72:75]
	v_mfma_f32_16x16x32_bf16 v[124:127], v[132:135], v[164:167], v[124:127]
	v_mfma_f32_16x16x32_bf16 v[120:123], v[140:143], v[164:167], v[120:123]
	v_mfma_f32_16x16x32_bf16 v[116:119], v[132:135], v[188:191], v[116:119]
	v_mfma_f32_16x16x32_bf16 v[108:111], v[140:143], v[188:191], v[108:111]
	v_mfma_f32_16x16x32_bf16 v[92:95], v[132:135], v[206:209], v[92:95]
	v_mfma_f32_16x16x32_bf16 v[88:91], v[140:143], v[206:209], v[88:91]
	v_mfma_f32_16x16x32_bf16 v[76:79], v[132:135], v[214:217], v[76:79]
	v_mfma_f32_16x16x32_bf16 v[72:75], v[140:143], v[214:217], v[72:75]
	v_mfma_f32_16x16x32_bf16 v[112:115], v[144:147], v[160:163], v[112:115]
	v_mfma_f32_16x16x32_bf16 v[104:107], v[152:155], v[160:163], v[104:107]
	v_mfma_f32_16x16x32_bf16 v[100:103], v[144:147], v[184:187], v[100:103]
	v_mfma_f32_16x16x32_bf16 v[96:99], v[152:155], v[184:187], v[96:99]
	v_mfma_f32_16x16x32_bf16 v[84:87], v[144:147], v[192:195], v[84:87]
	v_mfma_f32_16x16x32_bf16 v[80:83], v[152:155], v[192:195], v[80:83]
	v_mfma_f32_16x16x32_bf16 v[68:71], v[144:147], v[210:213], v[68:71]
	v_mfma_f32_16x16x32_bf16 v[64:67], v[152:155], v[210:213], v[64:67]
	v_mfma_f32_16x16x32_bf16 v[112:115], v[148:151], v[164:167], v[112:115]
	v_mfma_f32_16x16x32_bf16 v[104:107], v[156:159], v[164:167], v[104:107]
	v_mfma_f32_16x16x32_bf16 v[100:103], v[148:151], v[188:191], v[100:103]
	v_mfma_f32_16x16x32_bf16 v[96:99], v[156:159], v[188:191], v[96:99]
	v_mfma_f32_16x16x32_bf16 v[84:87], v[148:151], v[206:209], v[84:87]
	v_mfma_f32_16x16x32_bf16 v[80:83], v[156:159], v[206:209], v[80:83]
	v_mfma_f32_16x16x32_bf16 v[68:71], v[148:151], v[214:217], v[68:71]
	v_mfma_f32_16x16x32_bf16 v[64:67], v[156:159], v[214:217], v[64:67]
	s_barrier
	s_setprio 0
	ds_read_b128 v[160:163], v204 offset:49152
	ds_read_b128 v[164:167], v204 offset:50176
	ds_read_b128 v[184:187], v204 offset:51200
	ds_read_b128 v[188:191], v204 offset:52224
	ds_read_b128 v[192:195], v204 offset:53248
	ds_read_b128 v[206:209], v204 offset:54272
	ds_read_b128 v[210:213], v204 offset:55296
	ds_read_b128 v[214:217], v204 offset:56320
	global_load_lds_dwordx4 v170, s[98:99]
	s_add_i32 m0, s60, 0x2000
	s_add_u32 s58, s58, 0x200080
	s_addc_u32 s59, s59, 0
	s_add_i32 s60, s74, s1
	global_load_lds_dwordx4 v174, s[98:99]
	s_mov_b32 m0, s60
	s_nop 0
	global_load_lds_dwordx4 v170, s[58:59]
	s_add_i32 m0, s60, 0x2000
	s_nop 0
	global_load_lds_dwordx4 v174, s[58:59]
	s_mov_b32 m0, s63
	s_nop 0
	global_load_lds_dwordx4 v168, s[100:101]
	s_mov_b32 m0, s64
	s_nop 0
	global_load_lds_dwordx4 v172, s[100:101]
	s_add_i32 s72, s72, 2
	s_add_u32 s50, s50, 0x100
	s_addc_u32 s51, s51, 0
	s_add_u32 s70, s70, 0x100
	s_addc_u32 s71, s71, 0
	s_cmpk_gt_u32 s72, 0x7d
	s_waitcnt vmcnt(8)
	s_waitcnt lgkmcnt(0)
	s_setprio 1
	s_barrier
	v_mfma_f32_16x16x32_bf16 v[60:63], v[128:131], v[160:163], v[60:63]
	v_mfma_f32_16x16x32_bf16 v[56:59], v[136:139], v[160:163], v[56:59]
	v_mfma_f32_16x16x32_bf16 v[44:47], v[128:131], v[184:187], v[44:47]
	v_mfma_f32_16x16x32_bf16 v[40:43], v[136:139], v[184:187], v[40:43]
	v_mfma_f32_16x16x32_bf16 v[28:31], v[128:131], v[192:195], v[28:31]
	v_mfma_f32_16x16x32_bf16 v[24:27], v[136:139], v[192:195], v[24:27]
	v_mfma_f32_16x16x32_bf16 v[12:15], v[128:131], v[210:213], v[12:15]
	v_mfma_f32_16x16x32_bf16 v[8:11], v[136:139], v[210:213], v[8:11]
	v_mfma_f32_16x16x32_bf16 v[60:63], v[132:135], v[164:167], v[60:63]
	v_mfma_f32_16x16x32_bf16 v[56:59], v[140:143], v[164:167], v[56:59]
	v_mfma_f32_16x16x32_bf16 v[44:47], v[132:135], v[188:191], v[44:47]
	v_mfma_f32_16x16x32_bf16 v[40:43], v[140:143], v[188:191], v[40:43]
	v_mfma_f32_16x16x32_bf16 v[28:31], v[132:135], v[206:209], v[28:31]
	v_mfma_f32_16x16x32_bf16 v[24:27], v[140:143], v[206:209], v[24:27]
	v_mfma_f32_16x16x32_bf16 v[12:15], v[132:135], v[214:217], v[12:15]
	v_mfma_f32_16x16x32_bf16 v[8:11], v[140:143], v[214:217], v[8:11]
	v_mfma_f32_16x16x32_bf16 v[52:55], v[144:147], v[160:163], v[52:55]
	v_mfma_f32_16x16x32_bf16 v[48:51], v[152:155], v[160:163], v[48:51]
	v_mfma_f32_16x16x32_bf16 v[36:39], v[144:147], v[184:187], v[36:39]
	v_mfma_f32_16x16x32_bf16 v[32:35], v[152:155], v[184:187], v[32:35]
	v_mfma_f32_16x16x32_bf16 v[20:23], v[144:147], v[192:195], v[20:23]
	v_mfma_f32_16x16x32_bf16 v[16:19], v[152:155], v[192:195], v[16:19]
	v_mfma_f32_16x16x32_bf16 v[4:7], v[144:147], v[210:213], v[4:7]
	v_mfma_f32_16x16x32_bf16 v[0:3], v[152:155], v[210:213], v[0:3]
	v_mfma_f32_16x16x32_bf16 v[52:55], v[148:151], v[164:167], v[52:55]
	v_mfma_f32_16x16x32_bf16 v[48:51], v[156:159], v[164:167], v[48:51]
	v_mfma_f32_16x16x32_bf16 v[36:39], v[148:151], v[188:191], v[36:39]
	v_mfma_f32_16x16x32_bf16 v[32:35], v[156:159], v[188:191], v[32:35]
	v_mfma_f32_16x16x32_bf16 v[20:23], v[148:151], v[206:209], v[20:23]
	v_mfma_f32_16x16x32_bf16 v[16:19], v[156:159], v[206:209], v[16:19]
	v_mfma_f32_16x16x32_bf16 v[4:7], v[148:151], v[214:217], v[4:7]
	v_mfma_f32_16x16x32_bf16 v[0:3], v[156:159], v[214:217], v[0:3]
	s_barrier
	s_setprio 0
	s_cbranch_scc0 .LBB0_1260
	s_and_b64 vcc, exec, s[12:13]
	s_cbranch_vccz .LBB0_1263
	s_barrier

; #define PG8_STAGE(bufoff, gbase, voff) do { _Pragma("unroll") for (int _i = 0; _i < 2; ++_i) \
;         __builtin_amdgcn_global_load_lds((const unsigned*)((const char*)(gbase) + (voff)[_i]), (PG8_LAS unsigned*)(lds + (bufoff) + ldsw + _i * 8192), 16, 0, 0); } while (0)
; #define PG8_LDA(dst, b, h) do { _Pragma("unroll") for (int m = 0; m < 4; ++m) _Pragma("unroll") for (int k = 0; k < 2; ++k) dst[m][k] = *(const PG8_LAS bf16x8*)(lds + PG8_SA(b, h) + aoff + m * 2048 + k * 1024); } while (0)
; #define PG8_LDB(dst, b, h) do { _Pragma("unroll") for (int n = 0; n < 2; ++n) _Pragma("unroll") for (int k = 0; k < 2; ++k) dst[n][k] = *(const PG8_LAS bf16x8*)(lds + PG8_SB(b, h) + boff + n * 2048 + k * 1024); } while (0)
; #define PG8_MMA(ai, bj, At, Bt) do { __builtin_amdgcn_s_setprio(1); _Pragma("unroll") for (int m = 0; m < 4; ++m) _Pragma("unroll") for (int n = 0; n < 2; ++n) _Pragma("unroll") for (int k = 0; k < 2; ++k) \
;         acc[ai][bj][m][n] = __builtin_amdgcn_mfma_f32_16x16x32_bf16(Bt[n][k], At[m][k], acc[ai][bj][m][n], 0, 0, 0); __builtin_amdgcn_s_setprio(0); } while (0)
; #define PG8_WAIT_V(n) asm volatile("s_waitcnt vmcnt(" #n ")" ::: "memory")
; #define PG8_WAIT_L(n) asm volatile("s_waitcnt lgkmcnt(" #n ")" ::: "memory")
; template <class Epi, class Sched, bool ALIGN_EPI = false, bool SP2 = false>
; __device__ __forceinline__ void gemm_phase(PG8_LAS unsigned char* lds, const Gemm g, const Sched& S, const Epi& E) {
;     ...
;             const bool last = (t == nt - 2);
;             const char* a1 = cA + (size_t)(t + 1) * kstep;
;             const char* a2 = last ? nA : cA + (size_t)(t + 2) * kstep; const char* b2 = last ? nB : cB + (size_t)(t + 2) * kstep;
;             const char* a3 = a2 + kstep; const char* b3 = b2 + kstep;
;             if (last && has_next) S.a_ready(nxt);
;             if constexpr (SP2) {
;             PG8_LDB(B0, 0, 0); PG8_LDB(B1, 0, 1); PG8_SCHED; PG8_LDA(At, 0, 0); PG8_STAGE(PG8_SA(1, 1), a1 + hstep, voffA);
;             PG8_WAIT_V(8); PG8_WAIT_L(0); PG8_BAR; PG8_MMA(0, 0, At, B0); PG8_MMA(0, 1, At, B1); PG8_BAR; PG8_SCHED;
;             PG8_LDA(At, 0, 1); PG8_STAGE(PG8_SB(0, 0), b2, voffB); PG8_STAGE(PG8_SB(0, 1), b2 + hstep, voffB); PG8_STAGE(PG8_SA(0, 0), a2, voffA);
;             PG8_WAIT_V(8); PG8_WAIT_L(0); PG8_BAR; PG8_MMA(1, 0, At, B0); PG8_MMA(1, 1, At, B1); PG8_BAR; PG8_SCHED;
.LBB0_1336:
	ds_read_b128 v[152:155], v149
	ds_read_b128 v[156:159], v149 offset:1024
	ds_read_b128 v[160:163], v149 offset:2048
	ds_read_b128 v[164:167], v149 offset:3072
	ds_read_b128 v[168:171], v150
	ds_read_b128 v[172:175], v150 offset:1024
	ds_read_b128 v[176:179], v150 offset:2048
	ds_read_b128 v[180:183], v150 offset:3072
	s_add_i32 m0, s33, 0xc000
	ds_read_b128 v[184:187], v151
	ds_read_b128 v[188:191], v151 offset:1024
	ds_read_b128 v[192:195], v151 offset:2048
	ds_read_b128 v[196:199], v151 offset:3072
	ds_read_b128 v[200:203], v151 offset:4096
	ds_read_b128 v[204:207], v151 offset:5120
	ds_read_b128 v[208:211], v151 offset:6144
	ds_read_b128 v[212:215], v151 offset:7168
	global_load_lds_dwordx4 v136, s[46:47]
	s_add_i32 m0, s33, 0xe000
	s_nop 0
	global_load_lds_dwordx4 v138, s[46:47]
	s_add_u32 s48, s46, 0xfff80080
	s_addc_u32 s49, s47, -1
	s_cmp_eq_u32 s74, 28
	s_cselect_b32 s51, s25, s49
	s_cselect_b32 s50, s29, s48
	s_cselect_b32 s49, s23, s73
	s_cselect_b32 s48, s71, s72
	s_add_i32 s75, s65, s1
	s_mov_b32 m0, s75
	s_waitcnt vmcnt(8)
	s_waitcnt lgkmcnt(0)
	s_setprio 1
	s_barrier
	v_mfma_f32_16x16x32_bf16 v[124:127], v[152:155], v[184:187], v[124:127]
	v_mfma_f32_16x16x32_bf16 v[120:123], v[160:163], v[184:187], v[120:123]
	v_mfma_f32_16x16x32_bf16 v[108:111], v[152:155], v[192:195], v[108:111]
	v_mfma_f32_16x16x32_bf16 v[104:107], v[160:163], v[192:195], v[104:107]
	v_mfma_f32_16x16x32_bf16 v[92:95], v[152:155], v[200:203], v[92:95]
	v_mfma_f32_16x16x32_bf16 v[88:91], v[160:163], v[200:203], v[88:91]
	v_mfma_f32_16x16x32_bf16 v[76:79], v[152:155], v[208:211], v[76:79]
	v_mfma_f32_16x16x32_bf16 v[72:75], v[160:163], v[208:211], v[72:75]
	v_mfma_f32_16x16x32_bf16 v[124:127], v[156:159], v[188:191], v[124:127]
	v_mfma_f32_16x16x32_bf16 v[120:123], v[164:167], v[188:191], v[120:123]
	v_mfma_f32_16x16x32_bf16 v[108:111], v[156:159], v[196:199], v[108:111]
	v_mfma_f32_16x16x32_bf16 v[104:107], v[164:167], v[196:199], v[104:107]
	v_mfma_f32_16x16x32_bf16 v[92:95], v[156:159], v[204:207], v[92:95]
	v_mfma_f32_16x16x32_bf16 v[88:91], v[164:167], v[204:207], v[88:91]
	v_mfma_f32_16x16x32_bf16 v[76:79], v[156:159], v[212:215], v[76:79]
	v_mfma_f32_16x16x32_bf16 v[72:75], v[164:167], v[212:215], v[72:75]
	v_mfma_f32_16x16x32_bf16 v[116:119], v[168:171], v[184:187], v[116:119]
	v_mfma_f32_16x16x32_bf16 v[112:115], v[176:179], v[184:187], v[112:115]
	v_mfma_f32_16x16x32_bf16 v[100:103], v[168:171], v[192:195], v[100:103]
	v_mfma_f32_16x16x32_bf16 v[96:99], v[176:179], v[192:195], v[96:99]
	v_mfma_f32_16x16x32_bf16 v[84:87], v[168:171], v[200:203], v[84:87]
	v_mfma_f32_16x16x32_bf16 v[80:83], v[176:179], v[200:203], v[80:83]
	v_mfma_f32_16x16x32_bf16 v[68:71], v[168:171], v[208:211], v[68:71]
	v_mfma_f32_16x16x32_bf16 v[64:67], v[176:179], v[208:211], v[64:67]
	v_mfma_f32_16x16x32_bf16 v[116:119], v[172:175], v[188:191], v[116:119]
	v_mfma_f32_16x16x32_bf16 v[112:115], v[180:183], v[188:191], v[112:115]
	v_mfma_f32_16x16x32_bf16 v[100:103], v[172:175], v[196:199], v[100:103]
	v_mfma_f32_16x16x32_bf16 v[96:99], v[180:183], v[196:199], v[96:99]
	v_mfma_f32_16x16x32_bf16 v[84:87], v[172:175], v[204:207], v[84:87]
	v_mfma_f32_16x16x32_bf16 v[80:83], v[180:183], v[204:207], v[80:83]
	v_mfma_f32_16x16x32_bf16 v[68:71], v[172:175], v[212:215], v[68:71]
	v_mfma_f32_16x16x32_bf16 v[64:67], v[180:183], v[212:215], v[64:67]
	s_barrier
	s_setprio 0
	ds_read_b128 v[184:187], v151 offset:16384
	ds_read_b128 v[188:191], v151 offset:17408
	ds_read_b128 v[192:195], v151 offset:18432
	ds_read_b128 v[196:199], v151 offset:19456
	ds_read_b128 v[200:203], v151 offset:20480
	ds_read_b128 v[204:207], v151 offset:21504
	ds_read_b128 v[208:211], v151 offset:22528
	ds_read_b128 v[212:215], v151 offset:23552
	global_load_lds_dwordx4 v130, s[48:49]
	s_add_i32 m0, s75, 0x2000
	s_add_u32 s76, s48, 0x80000
	s_addc_u32 s77, s49, 0
	s_add_i32 s75, s66, s1
	global_load_lds_dwordx4 v134, s[48:49]
	s_mov_b32 m0, s75
	s_nop 0
	global_load_lds_dwordx4 v130, s[76:77]
	s_add_i32 m0, s75, 0x2000
	s_nop 0
	global_load_lds_dwordx4 v134, s[76:77]
	s_mov_b32 m0, s33
	s_nop 0
	global_load_lds_dwordx4 v128, s[50:51]
	s_mov_b32 m0, s43
	s_nop 0
	global_load_lds_dwordx4 v132, s[50:51]
	s_waitcnt vmcnt(8)
	s_waitcnt lgkmcnt(0)
	s_setprio 1
	s_barrier
	v_mfma_f32_16x16x32_bf16 v[60:63], v[152:155], v[184:187], v[60:63]
	v_mfma_f32_16x16x32_bf16 v[56:59], v[160:163], v[184:187], v[56:59]
	v_mfma_f32_16x16x32_bf16 v[44:47], v[152:155], v[192:195], v[44:47]
	v_mfma_f32_16x16x32_bf16 v[40:43], v[160:163], v[192:195], v[40:43]
	v_mfma_f32_16x16x32_bf16 v[28:31], v[152:155], v[200:203], v[28:31]
	v_mfma_f32_16x16x32_bf16 v[24:27], v[160:163], v[200:203], v[24:27]
	v_mfma_f32_16x16x32_bf16 v[12:15], v[152:155], v[208:211], v[12:15]
	v_mfma_f32_16x16x32_bf16 v[8:11], v[160:163], v[208:211], v[8:11]
	v_mfma_f32_16x16x32_bf16 v[60:63], v[156:159], v[188:191], v[60:63]
	v_mfma_f32_16x16x32_bf16 v[56:59], v[164:167], v[188:191], v[56:59]
	v_mfma_f32_16x16x32_bf16 v[44:47], v[156:159], v[196:199], v[44:47]
	v_mfma_f32_16x16x32_bf16 v[40:43], v[164:167], v[196:199], v[40:43]
	v_mfma_f32_16x16x32_bf16 v[28:31], v[156:159], v[204:207], v[28:31]
	v_mfma_f32_16x16x32_bf16 v[24:27], v[164:167], v[204:207], v[24:27]
	v_mfma_f32_16x16x32_bf16 v[12:15], v[156:159], v[212:215], v[12:15]
	v_mfma_f32_16x16x32_bf16 v[8:11], v[164:167], v[212:215], v[8:11]
	v_mfma_f32_16x16x32_bf16 v[52:55], v[168:171], v[184:187], v[52:55]
	v_mfma_f32_16x16x32_bf16 v[48:51], v[176:179], v[184:187], v[48:51]
	v_mfma_f32_16x16x32_bf16 v[36:39], v[168:171], v[192:195], v[36:39]
	v_mfma_f32_16x16x32_bf16 v[32:35], v[176:179], v[192:195], v[32:35]
	v_mfma_f32_16x16x32_bf16 v[20:23], v[168:171], v[200:203], v[20:23]
	v_mfma_f32_16x16x32_bf16 v[16:19], v[176:179], v[200:203], v[16:19]
	v_mfma_f32_16x16x32_bf16 v[4:7], v[168:171], v[208:211], v[4:7]
	v_mfma_f32_16x16x32_bf16 v[0:3], v[176:179], v[208:211], v[0:3]
	v_mfma_f32_16x16x32_bf16 v[52:55], v[172:175], v[188:191], v[52:55]
	v_mfma_f32_16x16x32_bf16 v[48:51], v[180:183], v[188:191], v[48:51]
	v_mfma_f32_16x16x32_bf16 v[36:39], v[172:175], v[196:199], v[36:39]
	v_mfma_f32_16x16x32_bf16 v[32:35], v[180:183], v[196:199], v[32:35]
	v_mfma_f32_16x16x32_bf16 v[20:23], v[172:175], v[204:207], v[20:23]
	v_mfma_f32_16x16x32_bf16 v[16:19], v[180:183], v[204:207], v[16:19]
	v_mfma_f32_16x16x32_bf16 v[4:7], v[172:175], v[212:215], v[4:7]
	v_mfma_f32_16x16x32_bf16 v[0:3], v[180:183], v[212:215], v[0:3]
	s_barrier
; #define PG8_STAGE(bufoff, gbase, voff) do { _Pragma("unroll") for (int _i = 0; _i < 2; ++_i) \
;         __builtin_amdgcn_global_load_lds((const unsigned*)((const char*)(gbase) + (voff)[_i]), (PG8_LAS unsigned*)(lds + (bufoff) + ldsw + _i * 8192), 16, 0, 0); } while (0)
; #define PG8_LDA(dst, b, h) do { _Pragma("unroll") for (int m = 0; m < 4; ++m) _Pragma("unroll") for (int k = 0; k < 2; ++k) dst[m][k] = *(const PG8_LAS bf16x8*)(lds + PG8_SA(b, h) + aoff + m * 2048 + k * 1024); } while (0)
; #define PG8_LDB(dst, b, h) do { _Pragma("unroll") for (int n = 0; n < 2; ++n) _Pragma("unroll") for (int k = 0; k < 2; ++k) dst[n][k] = *(const PG8_LAS bf16x8*)(lds + PG8_SB(b, h) + boff + n * 2048 + k * 1024); } while (0)
; #define PG8_MMA(ai, bj, At, Bt) do { __builtin_amdgcn_s_setprio(1); _Pragma("unroll") for (int m = 0; m < 4; ++m) _Pragma("unroll") for (int n = 0; n < 2; ++n) _Pragma("unroll") for (int k = 0; k < 2; ++k) \
;         acc[ai][bj][m][n] = __builtin_amdgcn_mfma_f32_16x16x32_bf16(Bt[n][k], At[m][k], acc[ai][bj][m][n], 0, 0, 0); __builtin_amdgcn_s_setprio(0); } while (0)
; #define PG8_WAIT_V(n) asm volatile("s_waitcnt vmcnt(" #n ")" ::: "memory")
; #define PG8_WAIT_L(n) asm volatile("s_waitcnt lgkmcnt(" #n ")" ::: "memory")
; #define PG8_BAR __builtin_amdgcn_s_barrier()
; #define PG8_SCHED __builtin_amdgcn_sched_barrier(0)
; template <class Epi, class Sched, bool ALIGN_EPI = false, bool SP2 = false>
; __device__ __forceinline__ void gemm_phase(PG8_LAS unsigned char* lds, const Gemm g, const Sched& S, const Epi& E) {
;     ...
;             PG8_LDB(B0, 1, 0); PG8_LDB(B1, 1, 1); PG8_SCHED; PG8_LDA(At, 1, 0); PG8_STAGE(PG8_SA(0, 1), a2 + hstep, voffA);
;             PG8_WAIT_V(8); PG8_WAIT_L(0); PG8_BAR; PG8_MMA(0, 0, At, B0); PG8_MMA(0, 1, At, B1); PG8_BAR; PG8_SCHED;
;             PG8_LDA(At, 1, 1); PG8_STAGE(PG8_SB(1, 0), b3, voffB); PG8_STAGE(PG8_SB(1, 1), b3 + hstep, voffB); PG8_STAGE(PG8_SA(1, 0), a3, voffA);
;             PG8_WAIT_V(8); PG8_WAIT_L(0); PG8_BAR; PG8_MMA(1, 0, At, B0); PG8_MMA(1, 1, At, B1); PG8_BAR; PG8_SCHED;
	s_setprio 0
	ds_read_b128 v[152:155], v216
	ds_read_b128 v[156:159], v216 offset:1024
	ds_read_b128 v[160:163], v216 offset:2048
	ds_read_b128 v[164:167], v216 offset:3072
	ds_read_b128 v[168:171], v217
	ds_read_b128 v[172:175], v217 offset:1024
	ds_read_b128 v[176:179], v217 offset:2048
	ds_read_b128 v[180:183], v217 offset:3072
	ds_read_b128 v[184:187], v151 offset:32768
	ds_read_b128 v[188:191], v151 offset:33792
	ds_read_b128 v[192:195], v151 offset:34816
	ds_read_b128 v[196:199], v151 offset:35840
	ds_read_b128 v[200:203], v151 offset:36864
	ds_read_b128 v[204:207], v151 offset:37888
	ds_read_b128 v[208:211], v151 offset:38912
	ds_read_b128 v[212:215], v151 offset:39936
	s_add_u32 s98, s50, 0x80000
	s_addc_u32 s99, s51, 0
	s_mov_b32 m0, s58
	s_add_u32 s100, s50, 0x80
	s_addc_u32 s101, s51, 0
	global_load_lds_dwordx4 v128, s[98:99]
	s_mov_b32 m0, s59
	s_nop 0
	global_load_lds_dwordx4 v132, s[98:99]
	s_add_i32 s75, 0, 0x18000
	s_add_i32 s76, 0, 0x1c000
	s_add_u32 s98, s48, 0x80
	s_addc_u32 s99, s49, 0
	s_add_i32 s50, s75, s1
	s_mov_b32 m0, s50
	s_waitcnt vmcnt(8)
	s_waitcnt lgkmcnt(0)
	s_setprio 1
	s_barrier
	v_mfma_f32_16x16x32_bf16 v[124:127], v[152:155], v[184:187], v[124:127]
	v_mfma_f32_16x16x32_bf16 v[120:123], v[160:163], v[184:187], v[120:123]
	v_mfma_f32_16x16x32_bf16 v[108:111], v[152:155], v[192:195], v[108:111]
	v_mfma_f32_16x16x32_bf16 v[104:107], v[160:163], v[192:195], v[104:107]
	v_mfma_f32_16x16x32_bf16 v[92:95], v[152:155], v[200:203], v[92:95]
	v_mfma_f32_16x16x32_bf16 v[88:91], v[160:163], v[200:203], v[88:91]
	v_mfma_f32_16x16x32_bf16 v[76:79], v[152:155], v[208:211], v[76:79]
	v_mfma_f32_16x16x32_bf16 v[72:75], v[160:163], v[208:211], v[72:75]
	v_mfma_f32_16x16x32_bf16 v[124:127], v[156:159], v[188:191], v[124:127]
	v_mfma_f32_16x16x32_bf16 v[120:123], v[164:167], v[188:191], v[120:123]
	v_mfma_f32_16x16x32_bf16 v[108:111], v[156:159], v[196:199], v[108:111]
	v_mfma_f32_16x16x32_bf16 v[104:107], v[164:167], v[196:199], v[104:107]
	v_mfma_f32_16x16x32_bf16 v[92:95], v[156:159], v[204:207], v[92:95]
	v_mfma_f32_16x16x32_bf16 v[88:91], v[164:167], v[204:207], v[88:91]
	v_mfma_f32_16x16x32_bf16 v[76:79], v[156:159], v[212:215], v[76:79]
	v_mfma_f32_16x16x32_bf16 v[72:75], v[164:167], v[212:215], v[72:75]
	v_mfma_f32_16x16x32_bf16 v[116:119], v[168:171], v[184:187], v[116:119]
	v_mfma_f32_16x16x32_bf16 v[112:115], v[176:179], v[184:187], v[112:115]
	v_mfma_f32_16x16x32_bf16 v[100:103], v[168:171], v[192:195], v[100:103]
	v_mfma_f32_16x16x32_bf16 v[96:99], v[176:179], v[192:195], v[96:99]
	v_mfma_f32_16x16x32_bf16 v[84:87], v[168:171], v[200:203], v[84:87]
	v_mfma_f32_16x16x32_bf16 v[80:83], v[176:179], v[200:203], v[80:83]
	v_mfma_f32_16x16x32_bf16 v[68:71], v[168:171], v[208:211], v[68:71]
	v_mfma_f32_16x16x32_bf16 v[64:67], v[176:179], v[208:211], v[64:67]
	v_mfma_f32_16x16x32_bf16 v[116:119], v[172:175], v[188:191], v[116:119]
	v_mfma_f32_16x16x32_bf16 v[112:115], v[180:183], v[188:191], v[112:115]
	v_mfma_f32_16x16x32_bf16 v[100:103], v[172:175], v[196:199], v[100:103]
	v_mfma_f32_16x16x32_bf16 v[96:99], v[180:183], v[196:199], v[96:99]
	v_mfma_f32_16x16x32_bf16 v[84:87], v[172:175], v[204:207], v[84:87]
	v_mfma_f32_16x16x32_bf16 v[80:83], v[180:183], v[204:207], v[80:83]
	v_mfma_f32_16x16x32_bf16 v[68:71], v[172:175], v[212:215], v[68:71]
	v_mfma_f32_16x16x32_bf16 v[64:67], v[180:183], v[212:215], v[64:67]
	s_barrier
	s_setprio 0
	ds_read_b128 v[184:187], v151 offset:49152
	ds_read_b128 v[188:191], v151 offset:50176
	ds_read_b128 v[192:195], v151 offset:51200
	ds_read_b128 v[196:199], v151 offset:52224
	ds_read_b128 v[200:203], v151 offset:53248
	ds_read_b128 v[204:207], v151 offset:54272
	ds_read_b128 v[208:211], v151 offset:55296
	ds_read_b128 v[212:215], v151 offset:56320
	global_load_lds_dwordx4 v130, s[98:99]
	s_add_i32 m0, s50, 0x2000
	s_add_u32 s48, s48, 0x80080
	s_addc_u32 s49, s49, 0
	s_add_i32 s50, s76, s1
	global_load_lds_dwordx4 v134, s[98:99]
	s_mov_b32 m0, s50
	s_nop 0
	global_load_lds_dwordx4 v130, s[48:49]
	s_add_i32 m0, s50, 0x2000
	s_nop 0
	global_load_lds_dwordx4 v134, s[48:49]
	s_mov_b32 m0, s61
	s_nop 0
	global_load_lds_dwordx4 v128, s[100:101]
	s_mov_b32 m0, s62
	s_nop 0
	global_load_lds_dwordx4 v132, s[100:101]
	s_add_i32 s74, s74, 2
	s_add_u32 s46, s46, 0x100
	s_addc_u32 s47, s47, 0
	s_add_u32 s72, s72, 0x100
	s_addc_u32 s73, s73, 0
	s_cmp_gt_u32 s74, 29
	s_waitcnt vmcnt(8)
	s_waitcnt lgkmcnt(0)
	s_setprio 1
	s_barrier
	v_mfma_f32_16x16x32_bf16 v[60:63], v[152:155], v[184:187], v[60:63]
	v_mfma_f32_16x16x32_bf16 v[56:59], v[160:163], v[184:187], v[56:59]
	v_mfma_f32_16x16x32_bf16 v[44:47], v[152:155], v[192:195], v[44:47]
	v_mfma_f32_16x16x32_bf16 v[40:43], v[160:163], v[192:195], v[40:43]
	v_mfma_f32_16x16x32_bf16 v[28:31], v[152:155], v[200:203], v[28:31]
	v_mfma_f32_16x16x32_bf16 v[24:27], v[160:163], v[200:203], v[24:27]
	v_mfma_f32_16x16x32_bf16 v[12:15], v[152:155], v[208:211], v[12:15]
	v_mfma_f32_16x16x32_bf16 v[8:11], v[160:163], v[208:211], v[8:11]
	v_mfma_f32_16x16x32_bf16 v[60:63], v[156:159], v[188:191], v[60:63]
	v_mfma_f32_16x16x32_bf16 v[56:59], v[164:167], v[188:191], v[56:59]
	v_mfma_f32_16x16x32_bf16 v[44:47], v[156:159], v[196:199], v[44:47]
	v_mfma_f32_16x16x32_bf16 v[40:43], v[164:167], v[196:199], v[40:43]
	v_mfma_f32_16x16x32_bf16 v[28:31], v[156:159], v[204:207], v[28:31]
	v_mfma_f32_16x16x32_bf16 v[24:27], v[164:167], v[204:207], v[24:27]
	v_mfma_f32_16x16x32_bf16 v[12:15], v[156:159], v[212:215], v[12:15]
	v_mfma_f32_16x16x32_bf16 v[8:11], v[164:167], v[212:215], v[8:11]
	v_mfma_f32_16x16x32_bf16 v[52:55], v[168:171], v[184:187], v[52:55]
	v_mfma_f32_16x16x32_bf16 v[48:51], v[176:179], v[184:187], v[48:51]
	v_mfma_f32_16x16x32_bf16 v[36:39], v[168:171], v[192:195], v[36:39]
	v_mfma_f32_16x16x32_bf16 v[32:35], v[176:179], v[192:195], v[32:35]
	v_mfma_f32_16x16x32_bf16 v[20:23], v[168:171], v[200:203], v[20:23]
	v_mfma_f32_16x16x32_bf16 v[16:19], v[176:179], v[200:203], v[16:19]
	v_mfma_f32_16x16x32_bf16 v[4:7], v[168:171], v[208:211], v[4:7]
	v_mfma_f32_16x16x32_bf16 v[0:3], v[176:179], v[208:211], v[0:3]
	v_mfma_f32_16x16x32_bf16 v[52:55], v[172:175], v[188:191], v[52:55]
	v_mfma_f32_16x16x32_bf16 v[48:51], v[180:183], v[188:191], v[48:51]
	v_mfma_f32_16x16x32_bf16 v[36:39], v[172:175], v[196:199], v[36:39]
	v_mfma_f32_16x16x32_bf16 v[32:35], v[180:183], v[196:199], v[32:35]
	v_mfma_f32_16x16x32_bf16 v[20:23], v[172:175], v[204:207], v[20:23]
	v_mfma_f32_16x16x32_bf16 v[16:19], v[180:183], v[204:207], v[16:19]
	v_mfma_f32_16x16x32_bf16 v[4:7], v[172:175], v[212:215], v[4:7]
	v_mfma_f32_16x16x32_bf16 v[0:3], v[180:183], v[212:215], v[0:3]
	s_barrier
	s_setprio 0
	s_cbranch_scc0 .LBB0_1336
	s_and_b64 vcc, exec, s[12:13]
	s_cbranch_vccz .LBB0_1339
	s_barrier

; #define PG8_STAGE(bufoff, gbase, voff) do { _Pragma("unroll") for (int _i = 0; _i < 2; ++_i) \
;         __builtin_amdgcn_global_load_lds((const unsigned*)((const char*)(gbase) + (voff)[_i]), (PG8_LAS unsigned*)(lds + (bufoff) + ldsw + _i * 8192), 16, 0, 0); } while (0)
; #define PG8_LDA(dst, b, h) do { _Pragma("unroll") for (int m = 0; m < 4; ++m) _Pragma("unroll") for (int k = 0; k < 2; ++k) dst[m][k] = *(const PG8_LAS bf16x8*)(lds + PG8_SA(b, h) + aoff + m * 2048 + k * 1024); } while (0)
; #define PG8_LDB(dst, b, h) do { _Pragma("unroll") for (int n = 0; n < 2; ++n) _Pragma("unroll") for (int k = 0; k < 2; ++k) dst[n][k] = *(const PG8_LAS bf16x8*)(lds + PG8_SB(b, h) + boff + n * 2048 + k * 1024); } while (0)
; #define PG8_MMA(ai, bj, At, Bt) do { __builtin_amdgcn_s_setprio(1); _Pragma("unroll") for (int m = 0; m < 4; ++m) _Pragma("unroll") for (int n = 0; n < 2; ++n) _Pragma("unroll") for (int k = 0; k < 2; ++k) \
;         acc[ai][bj][m][n] = __builtin_amdgcn_mfma_f32_16x16x32_bf16(Bt[n][k], At[m][k], acc[ai][bj][m][n], 0, 0, 0); __builtin_amdgcn_s_setprio(0); } while (0)
; #define PG8_WAIT_V(n) asm volatile("s_waitcnt vmcnt(" #n ")" ::: "memory")
; #define PG8_WAIT_L(n) asm volatile("s_waitcnt lgkmcnt(" #n ")" ::: "memory")
; template <class Epi, class Sched, bool ALIGN_EPI = false, bool SP2 = false>
; __device__ __forceinline__ void gemm_phase(PG8_LAS unsigned char* lds, const Gemm g, const Sched& S, const Epi& E) {
;     ...
;             const bool last = (t == nt - 2);
;             const char* a1 = cA + (size_t)(t + 1) * kstep;
;             const char* a2 = last ? nA : cA + (size_t)(t + 2) * kstep; const char* b2 = last ? nB : cB + (size_t)(t + 2) * kstep;
;             const char* a3 = a2 + kstep; const char* b3 = b2 + kstep;
;             if (last && has_next) S.a_ready(nxt);
;             if constexpr (SP2) {
;             PG8_LDB(B0, 0, 0); PG8_LDB(B1, 0, 1); PG8_SCHED; PG8_LDA(At, 0, 0); PG8_STAGE(PG8_SA(1, 1), a1 + hstep, voffA);
;             PG8_WAIT_V(8); PG8_WAIT_L(0); PG8_BAR; PG8_MMA(0, 0, At, B0); PG8_MMA(0, 1, At, B1); PG8_BAR; PG8_SCHED;
;             PG8_LDA(At, 0, 1); PG8_STAGE(PG8_SB(0, 0), b2, voffB); PG8_STAGE(PG8_SB(0, 1), b2 + hstep, voffB); PG8_STAGE(PG8_SA(0, 0), a2, voffA);
;             PG8_WAIT_V(8); PG8_WAIT_L(0); PG8_BAR; PG8_MMA(1, 0, At, B0); PG8_MMA(1, 1, At, B1); PG8_BAR; PG8_SCHED;
.LBB0_1412:
	ds_read_b128 v[128:131], v202
	ds_read_b128 v[132:135], v202 offset:1024
	ds_read_b128 v[136:139], v202 offset:2048
	ds_read_b128 v[140:143], v202 offset:3072
	ds_read_b128 v[144:147], v203
	ds_read_b128 v[148:151], v203 offset:1024
	ds_read_b128 v[152:155], v203 offset:2048
	ds_read_b128 v[156:159], v203 offset:3072
	s_add_i32 m0, s33, 0xc000
	ds_read_b128 v[160:163], v204
	ds_read_b128 v[164:167], v204 offset:1024
	ds_read_b128 v[184:187], v204 offset:2048
	ds_read_b128 v[188:191], v204 offset:3072
	ds_read_b128 v[192:195], v204 offset:4096
	ds_read_b128 v[206:209], v204 offset:5120
	ds_read_b128 v[210:213], v204 offset:6144
	ds_read_b128 v[214:217], v204 offset:7168
	global_load_lds_dwordx4 v176, s[42:43]
	s_add_i32 m0, s33, 0xe000
	s_nop 0
	global_load_lds_dwordx4 v178, s[42:43]
	s_add_u32 s46, s42, 0xffe00080
	s_addc_u32 s47, s43, -1
	s_cmpk_eq_i32 s68, 0x7c
	s_cselect_b32 s49, s23, s47
	s_cselect_b32 s48, s25, s46
	s_cselect_b32 s47, s21, s67
	s_cselect_b32 s46, s65, s66
	s_add_i32 s69, s63, s1
	s_mov_b32 m0, s69
	s_waitcnt vmcnt(8)
	s_waitcnt lgkmcnt(0)
	s_setprio 1
	s_barrier
	v_mfma_f32_16x16x32_bf16 v[124:127], v[128:131], v[160:163], v[124:127]
	v_mfma_f32_16x16x32_bf16 v[120:123], v[136:139], v[160:163], v[120:123]
	v_mfma_f32_16x16x32_bf16 v[116:119], v[128:131], v[184:187], v[116:119]
	v_mfma_f32_16x16x32_bf16 v[108:111], v[136:139], v[184:187], v[108:111]
	v_mfma_f32_16x16x32_bf16 v[92:95], v[128:131], v[192:195], v[92:95]
	v_mfma_f32_16x16x32_bf16 v[88:91], v[136:139], v[192:195], v[88:91]
	v_mfma_f32_16x16x32_bf16 v[76:79], v[128:131], v[210:213], v[76:79]
	v_mfma_f32_16x16x32_bf16 v[72:75], v[136:139], v[210:213], v[72:75]
	v_mfma_f32_16x16x32_bf16 v[124:127], v[132:135], v[164:167], v[124:127]
	v_mfma_f32_16x16x32_bf16 v[120:123], v[140:143], v[164:167], v[120:123]
	v_mfma_f32_16x16x32_bf16 v[116:119], v[132:135], v[188:191], v[116:119]
	v_mfma_f32_16x16x32_bf16 v[108:111], v[140:143], v[188:191], v[108:111]
	v_mfma_f32_16x16x32_bf16 v[92:95], v[132:135], v[206:209], v[92:95]
	v_mfma_f32_16x16x32_bf16 v[88:91], v[140:143], v[206:209], v[88:91]
	v_mfma_f32_16x16x32_bf16 v[76:79], v[132:135], v[214:217], v[76:79]
	v_mfma_f32_16x16x32_bf16 v[72:75], v[140:143], v[214:217], v[72:75]
	v_mfma_f32_16x16x32_bf16 v[112:115], v[144:147], v[160:163], v[112:115]
	v_mfma_f32_16x16x32_bf16 v[104:107], v[152:155], v[160:163], v[104:107]
	v_mfma_f32_16x16x32_bf16 v[100:103], v[144:147], v[184:187], v[100:103]
	v_mfma_f32_16x16x32_bf16 v[96:99], v[152:155], v[184:187], v[96:99]
	v_mfma_f32_16x16x32_bf16 v[84:87], v[144:147], v[192:195], v[84:87]
	v_mfma_f32_16x16x32_bf16 v[80:83], v[152:155], v[192:195], v[80:83]
	v_mfma_f32_16x16x32_bf16 v[68:71], v[144:147], v[210:213], v[68:71]
	v_mfma_f32_16x16x32_bf16 v[64:67], v[152:155], v[210:213], v[64:67]
	v_mfma_f32_16x16x32_bf16 v[112:115], v[148:151], v[164:167], v[112:115]
	v_mfma_f32_16x16x32_bf16 v[104:107], v[156:159], v[164:167], v[104:107]
	v_mfma_f32_16x16x32_bf16 v[100:103], v[148:151], v[188:191], v[100:103]
	v_mfma_f32_16x16x32_bf16 v[96:99], v[156:159], v[188:191], v[96:99]
	v_mfma_f32_16x16x32_bf16 v[84:87], v[148:151], v[206:209], v[84:87]
	v_mfma_f32_16x16x32_bf16 v[80:83], v[156:159], v[206:209], v[80:83]
	v_mfma_f32_16x16x32_bf16 v[68:71], v[148:151], v[214:217], v[68:71]
	v_mfma_f32_16x16x32_bf16 v[64:67], v[156:159], v[214:217], v[64:67]
	s_barrier
	s_setprio 0
	ds_read_b128 v[160:163], v204 offset:16384
	ds_read_b128 v[164:167], v204 offset:17408
	ds_read_b128 v[184:187], v204 offset:18432
	ds_read_b128 v[188:191], v204 offset:19456
	ds_read_b128 v[192:195], v204 offset:20480
	ds_read_b128 v[206:209], v204 offset:21504
	ds_read_b128 v[210:213], v204 offset:22528
	ds_read_b128 v[214:217], v204 offset:23552
	global_load_lds_dwordx4 v170, s[46:47]
	s_add_i32 m0, s69, 0x2000
	s_add_u32 s70, s46, 0x200000
	s_addc_u32 s71, s47, 0
	s_add_i32 s69, s64, s1
	global_load_lds_dwordx4 v174, s[46:47]
	s_mov_b32 m0, s69
	s_nop 0
	global_load_lds_dwordx4 v170, s[70:71]
	s_add_i32 m0, s69, 0x2000
	s_nop 0
	global_load_lds_dwordx4 v174, s[70:71]
	s_mov_b32 m0, s33
	s_nop 0
	global_load_lds_dwordx4 v168, s[48:49]
	s_mov_b32 m0, s41
	s_nop 0
	global_load_lds_dwordx4 v172, s[48:49]
	s_waitcnt vmcnt(8)
	s_waitcnt lgkmcnt(0)
	s_setprio 1
	s_barrier
	v_mfma_f32_16x16x32_bf16 v[60:63], v[128:131], v[160:163], v[60:63]
	v_mfma_f32_16x16x32_bf16 v[56:59], v[136:139], v[160:163], v[56:59]
	v_mfma_f32_16x16x32_bf16 v[44:47], v[128:131], v[184:187], v[44:47]
	v_mfma_f32_16x16x32_bf16 v[40:43], v[136:139], v[184:187], v[40:43]
	v_mfma_f32_16x16x32_bf16 v[28:31], v[128:131], v[192:195], v[28:31]
	v_mfma_f32_16x16x32_bf16 v[24:27], v[136:139], v[192:195], v[24:27]
	v_mfma_f32_16x16x32_bf16 v[12:15], v[128:131], v[210:213], v[12:15]
	v_mfma_f32_16x16x32_bf16 v[8:11], v[136:139], v[210:213], v[8:11]
	v_mfma_f32_16x16x32_bf16 v[60:63], v[132:135], v[164:167], v[60:63]
	v_mfma_f32_16x16x32_bf16 v[56:59], v[140:143], v[164:167], v[56:59]
	v_mfma_f32_16x16x32_bf16 v[44:47], v[132:135], v[188:191], v[44:47]
	v_mfma_f32_16x16x32_bf16 v[40:43], v[140:143], v[188:191], v[40:43]
	v_mfma_f32_16x16x32_bf16 v[28:31], v[132:135], v[206:209], v[28:31]
	v_mfma_f32_16x16x32_bf16 v[24:27], v[140:143], v[206:209], v[24:27]
	v_mfma_f32_16x16x32_bf16 v[12:15], v[132:135], v[214:217], v[12:15]
	v_mfma_f32_16x16x32_bf16 v[8:11], v[140:143], v[214:217], v[8:11]
	v_mfma_f32_16x16x32_bf16 v[52:55], v[144:147], v[160:163], v[52:55]
	v_mfma_f32_16x16x32_bf16 v[48:51], v[152:155], v[160:163], v[48:51]
	v_mfma_f32_16x16x32_bf16 v[36:39], v[144:147], v[184:187], v[36:39]
	v_mfma_f32_16x16x32_bf16 v[32:35], v[152:155], v[184:187], v[32:35]
	v_mfma_f32_16x16x32_bf16 v[20:23], v[144:147], v[192:195], v[20:23]
	v_mfma_f32_16x16x32_bf16 v[16:19], v[152:155], v[192:195], v[16:19]
	v_mfma_f32_16x16x32_bf16 v[4:7], v[144:147], v[210:213], v[4:7]
	v_mfma_f32_16x16x32_bf16 v[0:3], v[152:155], v[210:213], v[0:3]
	v_mfma_f32_16x16x32_bf16 v[52:55], v[148:151], v[164:167], v[52:55]
	v_mfma_f32_16x16x32_bf16 v[48:51], v[156:159], v[164:167], v[48:51]
	v_mfma_f32_16x16x32_bf16 v[36:39], v[148:151], v[188:191], v[36:39]
	v_mfma_f32_16x16x32_bf16 v[32:35], v[156:159], v[188:191], v[32:35]
	v_mfma_f32_16x16x32_bf16 v[20:23], v[148:151], v[206:209], v[20:23]
	v_mfma_f32_16x16x32_bf16 v[16:19], v[156:159], v[206:209], v[16:19]
	v_mfma_f32_16x16x32_bf16 v[4:7], v[148:151], v[214:217], v[4:7]
	v_mfma_f32_16x16x32_bf16 v[0:3], v[156:159], v[214:217], v[0:3]
	s_barrier
; #define PG8_STAGE(bufoff, gbase, voff) do { _Pragma("unroll") for (int _i = 0; _i < 2; ++_i) \
;         __builtin_amdgcn_global_load_lds((const unsigned*)((const char*)(gbase) + (voff)[_i]), (PG8_LAS unsigned*)(lds + (bufoff) + ldsw + _i * 8192), 16, 0, 0); } while (0)
; #define PG8_LDA(dst, b, h) do { _Pragma("unroll") for (int m = 0; m < 4; ++m) _Pragma("unroll") for (int k = 0; k < 2; ++k) dst[m][k] = *(const PG8_LAS bf16x8*)(lds + PG8_SA(b, h) + aoff + m * 2048 + k * 1024); } while (0)
; #define PG8_LDB(dst, b, h) do { _Pragma("unroll") for (int n = 0; n < 2; ++n) _Pragma("unroll") for (int k = 0; k < 2; ++k) dst[n][k] = *(const PG8_LAS bf16x8*)(lds + PG8_SB(b, h) + boff + n * 2048 + k * 1024); } while (0)
; #define PG8_MMA(ai, bj, At, Bt) do { __builtin_amdgcn_s_setprio(1); _Pragma("unroll") for (int m = 0; m < 4; ++m) _Pragma("unroll") for (int n = 0; n < 2; ++n) _Pragma("unroll") for (int k = 0; k < 2; ++k) \
;         acc[ai][bj][m][n] = __builtin_amdgcn_mfma_f32_16x16x32_bf16(Bt[n][k], At[m][k], acc[ai][bj][m][n], 0, 0, 0); __builtin_amdgcn_s_setprio(0); } while (0)
; #define PG8_WAIT_V(n) asm volatile("s_waitcnt vmcnt(" #n ")" ::: "memory")
; #define PG8_WAIT_L(n) asm volatile("s_waitcnt lgkmcnt(" #n ")" ::: "memory")
; #define PG8_BAR __builtin_amdgcn_s_barrier()
; #define PG8_SCHED __builtin_amdgcn_sched_barrier(0)
; template <class Epi, class Sched, bool ALIGN_EPI = false, bool SP2 = false>
; __device__ __forceinline__ void gemm_phase(PG8_LAS unsigned char* lds, const Gemm g, const Sched& S, const Epi& E) {
;     ...
;             PG8_LDB(B0, 1, 0); PG8_LDB(B1, 1, 1); PG8_SCHED; PG8_LDA(At, 1, 0); PG8_STAGE(PG8_SA(0, 1), a2 + hstep, voffA);
;             PG8_WAIT_V(8); PG8_WAIT_L(0); PG8_BAR; PG8_MMA(0, 0, At, B0); PG8_MMA(0, 1, At, B1); PG8_BAR; PG8_SCHED;
;             PG8_LDA(At, 1, 1); PG8_STAGE(PG8_SB(1, 0), b3, voffB); PG8_STAGE(PG8_SB(1, 1), b3 + hstep, voffB); PG8_STAGE(PG8_SA(1, 0), a3, voffA);
;             PG8_WAIT_V(8); PG8_WAIT_L(0); PG8_BAR; PG8_MMA(1, 0, At, B0); PG8_MMA(1, 1, At, B1); PG8_BAR; PG8_SCHED;
	s_setprio 0
	ds_read_b128 v[128:131], v218
	ds_read_b128 v[132:135], v218 offset:1024
	ds_read_b128 v[136:139], v218 offset:2048
	ds_read_b128 v[140:143], v218 offset:3072
	ds_read_b128 v[144:147], v219
	ds_read_b128 v[148:151], v219 offset:1024
	ds_read_b128 v[152:155], v219 offset:2048
	ds_read_b128 v[156:159], v219 offset:3072
	ds_read_b128 v[160:163], v204 offset:32768
	ds_read_b128 v[164:167], v204 offset:33792
	ds_read_b128 v[184:187], v204 offset:34816
	ds_read_b128 v[188:191], v204 offset:35840
	ds_read_b128 v[192:195], v204 offset:36864
	ds_read_b128 v[206:209], v204 offset:37888
	ds_read_b128 v[210:213], v204 offset:38912
	ds_read_b128 v[214:217], v204 offset:39936
	s_add_u32 s98, s48, 0x200000
	s_addc_u32 s99, s49, 0
	s_mov_b32 m0, s50
	s_add_u32 s100, s48, 0x80
	s_addc_u32 s101, s49, 0
	global_load_lds_dwordx4 v168, s[98:99]
	s_mov_b32 m0, s51
	s_nop 0
	global_load_lds_dwordx4 v172, s[98:99]
	s_add_i32 s69, 0, 0x18000
	s_add_i32 s70, 0, 0x1c000
	s_add_u32 s98, s46, 0x80
	s_addc_u32 s99, s47, 0
	s_add_i32 s48, s69, s1
	s_mov_b32 m0, s48
	s_waitcnt vmcnt(8)
	s_waitcnt lgkmcnt(0)
	s_setprio 1
	s_barrier
	v_mfma_f32_16x16x32_bf16 v[124:127], v[128:131], v[160:163], v[124:127]
	v_mfma_f32_16x16x32_bf16 v[120:123], v[136:139], v[160:163], v[120:123]
	v_mfma_f32_16x16x32_bf16 v[116:119], v[128:131], v[184:187], v[116:119]
	v_mfma_f32_16x16x32_bf16 v[108:111], v[136:139], v[184:187], v[108:111]
	v_mfma_f32_16x16x32_bf16 v[92:95], v[128:131], v[192:195], v[92:95]
	v_mfma_f32_16x16x32_bf16 v[88:91], v[136:139], v[192:195], v[88:91]
	v_mfma_f32_16x16x32_bf16 v[76:79], v[128:131], v[210:213], v[76:79]
	v_mfma_f32_16x16x32_bf16 v[72:75], v[136:139], v[210:213], v[72:75]
	v_mfma_f32_16x16x32_bf16 v[124:127], v[132:135], v[164:167], v[124:127]
	v_mfma_f32_16x16x32_bf16 v[120:123], v[140:143], v[164:167], v[120:123]
	v_mfma_f32_16x16x32_bf16 v[116:119], v[132:135], v[188:191], v[116:119]
	v_mfma_f32_16x16x32_bf16 v[108:111], v[140:143], v[188:191], v[108:111]
	v_mfma_f32_16x16x32_bf16 v[92:95], v[132:135], v[206:209], v[92:95]
	v_mfma_f32_16x16x32_bf16 v[88:91], v[140:143], v[206:209], v[88:91]
	v_mfma_f32_16x16x32_bf16 v[76:79], v[132:135], v[214:217], v[76:79]
	v_mfma_f32_16x16x32_bf16 v[72:75], v[140:143], v[214:217], v[72:75]
	v_mfma_f32_16x16x32_bf16 v[112:115], v[144:147], v[160:163], v[112:115]
	v_mfma_f32_16x16x32_bf16 v[104:107], v[152:155], v[160:163], v[104:107]
	v_mfma_f32_16x16x32_bf16 v[100:103], v[144:147], v[184:187], v[100:103]
	v_mfma_f32_16x16x32_bf16 v[96:99], v[152:155], v[184:187], v[96:99]
	v_mfma_f32_16x16x32_bf16 v[84:87], v[144:147], v[192:195], v[84:87]
	v_mfma_f32_16x16x32_bf16 v[80:83], v[152:155], v[192:195], v[80:83]
	v_mfma_f32_16x16x32_bf16 v[68:71], v[144:147], v[210:213], v[68:71]
	v_mfma_f32_16x16x32_bf16 v[64:67], v[152:155], v[210:213], v[64:67]
	v_mfma_f32_16x16x32_bf16 v[112:115], v[148:151], v[164:167], v[112:115]
	v_mfma_f32_16x16x32_bf16 v[104:107], v[156:159], v[164:167], v[104:107]
	v_mfma_f32_16x16x32_bf16 v[100:103], v[148:151], v[188:191], v[100:103]
	v_mfma_f32_16x16x32_bf16 v[96:99], v[156:159], v[188:191], v[96:99]
	v_mfma_f32_16x16x32_bf16 v[84:87], v[148:151], v[206:209], v[84:87]
	v_mfma_f32_16x16x32_bf16 v[80:83], v[156:159], v[206:209], v[80:83]
	v_mfma_f32_16x16x32_bf16 v[68:71], v[148:151], v[214:217], v[68:71]
	v_mfma_f32_16x16x32_bf16 v[64:67], v[156:159], v[214:217], v[64:67]
	s_barrier
	s_setprio 0
	ds_read_b128 v[160:163], v204 offset:49152
	ds_read_b128 v[164:167], v204 offset:50176
	ds_read_b128 v[184:187], v204 offset:51200
	ds_read_b128 v[188:191], v204 offset:52224
	ds_read_b128 v[192:195], v204 offset:53248
	ds_read_b128 v[206:209], v204 offset:54272
	ds_read_b128 v[210:213], v204 offset:55296
	ds_read_b128 v[214:217], v204 offset:56320
	global_load_lds_dwordx4 v170, s[98:99]
	s_add_i32 m0, s48, 0x2000
	s_add_u32 s46, s46, 0x200080
	s_addc_u32 s47, s47, 0
	s_add_i32 s48, s70, s1
	global_load_lds_dwordx4 v174, s[98:99]
	s_mov_b32 m0, s48
	s_nop 0
	global_load_lds_dwordx4 v170, s[46:47]
	s_add_i32 m0, s48, 0x2000
	s_nop 0
	global_load_lds_dwordx4 v174, s[46:47]
	s_mov_b32 m0, s59
	s_nop 0
	global_load_lds_dwordx4 v168, s[100:101]
	s_mov_b32 m0, s60
	s_nop 0
	global_load_lds_dwordx4 v172, s[100:101]
	s_add_i32 s68, s68, 2
	s_add_u32 s42, s42, 0x100
	s_addc_u32 s43, s43, 0
	s_add_u32 s66, s66, 0x100
	s_addc_u32 s67, s67, 0
	s_cmpk_gt_u32 s68, 0x7d
	s_waitcnt vmcnt(8)
	s_waitcnt lgkmcnt(0)
	s_setprio 1
	s_barrier
	v_mfma_f32_16x16x32_bf16 v[60:63], v[128:131], v[160:163], v[60:63]
	v_mfma_f32_16x16x32_bf16 v[56:59], v[136:139], v[160:163], v[56:59]
	v_mfma_f32_16x16x32_bf16 v[44:47], v[128:131], v[184:187], v[44:47]
	v_mfma_f32_16x16x32_bf16 v[40:43], v[136:139], v[184:187], v[40:43]
	v_mfma_f32_16x16x32_bf16 v[28:31], v[128:131], v[192:195], v[28:31]
	v_mfma_f32_16x16x32_bf16 v[24:27], v[136:139], v[192:195], v[24:27]
	v_mfma_f32_16x16x32_bf16 v[12:15], v[128:131], v[210:213], v[12:15]
	v_mfma_f32_16x16x32_bf16 v[8:11], v[136:139], v[210:213], v[8:11]
	v_mfma_f32_16x16x32_bf16 v[60:63], v[132:135], v[164:167], v[60:63]
	v_mfma_f32_16x16x32_bf16 v[56:59], v[140:143], v[164:167], v[56:59]
	v_mfma_f32_16x16x32_bf16 v[44:47], v[132:135], v[188:191], v[44:47]
	v_mfma_f32_16x16x32_bf16 v[40:43], v[140:143], v[188:191], v[40:43]
	v_mfma_f32_16x16x32_bf16 v[28:31], v[132:135], v[206:209], v[28:31]
	v_mfma_f32_16x16x32_bf16 v[24:27], v[140:143], v[206:209], v[24:27]
	v_mfma_f32_16x16x32_bf16 v[12:15], v[132:135], v[214:217], v[12:15]
	v_mfma_f32_16x16x32_bf16 v[8:11], v[140:143], v[214:217], v[8:11]
	v_mfma_f32_16x16x32_bf16 v[52:55], v[144:147], v[160:163], v[52:55]
	v_mfma_f32_16x16x32_bf16 v[48:51], v[152:155], v[160:163], v[48:51]
	v_mfma_f32_16x16x32_bf16 v[36:39], v[144:147], v[184:187], v[36:39]
	v_mfma_f32_16x16x32_bf16 v[32:35], v[152:155], v[184:187], v[32:35]
	v_mfma_f32_16x16x32_bf16 v[20:23], v[144:147], v[192:195], v[20:23]
	v_mfma_f32_16x16x32_bf16 v[16:19], v[152:155], v[192:195], v[16:19]
	v_mfma_f32_16x16x32_bf16 v[4:7], v[144:147], v[210:213], v[4:7]
	v_mfma_f32_16x16x32_bf16 v[0:3], v[152:155], v[210:213], v[0:3]
	v_mfma_f32_16x16x32_bf16 v[52:55], v[148:151], v[164:167], v[52:55]
	v_mfma_f32_16x16x32_bf16 v[48:51], v[156:159], v[164:167], v[48:51]
	v_mfma_f32_16x16x32_bf16 v[36:39], v[148:151], v[188:191], v[36:39]
	v_mfma_f32_16x16x32_bf16 v[32:35], v[156:159], v[188:191], v[32:35]
	v_mfma_f32_16x16x32_bf16 v[20:23], v[148:151], v[206:209], v[20:23]
	v_mfma_f32_16x16x32_bf16 v[16:19], v[156:159], v[206:209], v[16:19]
	v_mfma_f32_16x16x32_bf16 v[4:7], v[148:151], v[214:217], v[4:7]
	v_mfma_f32_16x16x32_bf16 v[0:3], v[156:159], v[214:217], v[0:3]
	s_barrier
	s_setprio 0
	s_cbranch_scc0 .LBB0_1412
	s_and_b64 vcc, exec, s[10:11]
	s_cbranch_vccz .LBB0_1415
	s_barrier
